# nt (non-temporal) hint on the dwordx4 epilogue stores of in-proj, gate, FFN-up, last-layer FFN-down and the ctx partial GEMMs, on top of v023
# speedup vs baseline: 1.0036x; 1.0036x over previous
;     __device__ __forceinline__ void operator()(const f32x4 (&acc)[2][2][4][2], const Unit& un, int wr, int wc, int fr, int fq) const {
;     ...
;             const f32x4 v0 = acc[ai][bj][m][0] * rr[ai][m] + s0[bj], v1 = acc[ai][bj][m][1] * rr[ai][m] + s1[bj];
;             if (pn < 4) {
;                 u32x4 w; w.x = pk2(gelu_tanh(v0.x), gelu_tanh(v0.y)); w.y = pk2(gelu_tanh(v0.z), gelu_tanh(v0.w)); w.z = pk2(gelu_tanh(v1.x), gelu_tanh(v1.y)); w.w = pk2(gelu_tanh(v1.z), gelu_tanh(v1.w));
;                 *(u32x4*)(ga + (size_t)row * 1024 + pn * 256 + ct) = w;
;             } else if (pn < 8) {
;                 u32x2 w; w.x = pk2(v0.x * sigmoidf_(v0.y), v0.z * sigmoidf_(v0.w)); w.y = pk2(v1.x * sigmoidf_(v1.y), v1.z * sigmoidf_(v1.w));
;                 *(u32x2*)(yb + (size_t)row * 512 + (((pn - 4) * 256 + ct) >> 1)) = w;
;             } else if (pn < 10 || (pn == 10 && bj == 0)) {
;                 const bool isq = pn < 10; const int cs = isq ? (pn - 8) * 256 + ct : ct;
;                 float x[8] = {v0.x, v0.y, v0.z, v0.w, v1.x, v1.y, v1.z, v1.w};
;                 if (lat) { const f32x4 ra = rp[m][0], rb = rp[m][1]; const float cc[4] = {ra.x, ra.z, rb.x, rb.z}, sn[4] = {ra.y, ra.w, rb.y, rb.w};
; #pragma unroll
;                     for (int jj = 0; jj < 4; ++jj) { const float x1 = x[2 * jj], x2 = x[2 * jj + 1]; x[2 * jj] = x1 * cc[jj] - x2 * sn[jj]; x[2 * jj + 1] = x1 * sn[jj] + x2 * cc[jj]; } }
;                 const float sc = isq ? QSCALE : 1.f;
;                 u32x4 w; w.x = pk2(x[0] * sc, x[1] * sc); w.y = pk2(x[2] * sc, x[3] * sc); w.z = pk2(x[4] * sc, x[5] * sc); w.w = pk2(x[6] * sc, x[7] * sc);
;                 if (isq) *(u32x4*)(q + (size_t)row * 512 + cs) = w; else *(u32x4*)(k + (size_t)row * 128 + cs) = w;
;             } else if (pn == 10) {
;                 const int dc = ct - 128; const float x[8] = {v0.x, v0.y, v0.z, v0.w, v1.x, v1.y, v1.z, v1.w};
;                 if (lat) { const int b = row >> 13, t = row & (SEQ - 1);
; #pragma unroll
;                     for (int e = 0; e < 8; ++e) vT[((size_t)(b * 128 + dc + e)) * SEQ + t] = (bf16)f2bf(x[e]); }
;                 else { const int rc = row - NLAT, b = rc >> 8, t = rc & 255;
; #pragma unroll
;                     for (int e = 0; e < 8; ++e) vcT[((size_t)(b * 128 + dc + e)) * CTXL + t] = (bf16)f2bf(x[e]); }
;             } else {
.LBB0_344:
	s_waitcnt vmcnt(0)
	v_pk_fma_f32 v[228:229], v[174:175], v[226:227], v[46:47] op_sel_hi:[1,0,1]
	v_pk_fma_f32 v[230:231], v[172:173], v[226:227], v[44:45] op_sel_hi:[1,0,1]
	v_pk_fma_f32 v[172:173], v[170:171], v[226:227], v[42:43] op_sel_hi:[1,0,1]
	v_pk_fma_f32 v[174:175], v[168:169], v[226:227], v[40:41] op_sel_hi:[1,0,1]
	s_and_b64 vcc, exec, s[52:53]
	s_cbranch_vccz .LBB0_368
	s_mov_b64 s[8:9], -1
	s_and_b64 vcc, exec, s[12:13]
	s_cbranch_vccz .LBB0_365
	s_andn2_b64 vcc, exec, s[48:49]
	s_cbranch_vccnz .LBB0_354
	s_and_b64 vcc, exec, s[46:47]
	s_cbranch_vccz .LBB0_353
	v_or_b32_e32 v195, s75, v184
	v_lshrrev_b32_e32 v195, 4, v195
	s_mov_b32 s8, 0x8400
	v_mad_u64_u32 v[210:211], s[8:9], v195, s8, v[198:199]
	v_lshlrev_b64 v[210:211], 5, v[210:211]
	v_cvt_pk_bf16_f32 v168, v230, v231
	v_cvt_pk_bf16_f32 v169, v228, v229
	v_cvt_pk_bf16_f32 v170, v174, v175
	v_cvt_pk_bf16_f32 v171, v172, v173
	v_lshl_add_u64 v[210:211], v[186:187], 0, v[210:211]
	global_store_dwordx4 v[210:211], v[168:171], off nt
	s_mov_b64 s[8:9], 0

; __device__ __forceinline__ unsigned pk2(float lo, float hi) { const f32x2 v = {lo, hi}; return __builtin_bit_cast(unsigned, __builtin_convertvector(v, bf16x2_t)); }
;     __device__ __forceinline__ void operator()(const f32x4 (&acc)[2][2][4][2], const Unit& un, int wr, int wc, int fr, int fq) const {
;     ...
;                 const bool isq = pn < 10; const int cs = isq ? (pn - 8) * 256 + ct : ct;
;                 float x[8] = {v0.x, v0.y, v0.z, v0.w, v1.x, v1.y, v1.z, v1.w};
;                 if (lat) { const f32x4 ra = rp[m][0], rb = rp[m][1]; const float cc[4] = {ra.x, ra.z, rb.x, rb.z}, sn[4] = {ra.y, ra.w, rb.y, rb.w};
; #pragma unroll
;                     for (int jj = 0; jj < 4; ++jj) { const float x1 = x[2 * jj], x2 = x[2 * jj + 1]; x[2 * jj] = x1 * cc[jj] - x2 * sn[jj]; x[2 * jj + 1] = x1 * sn[jj] + x2 * cc[jj]; } }
;                 const float sc = isq ? QSCALE : 1.f;
;                 u32x4 w; w.x = pk2(x[0] * sc, x[1] * sc); w.y = pk2(x[2] * sc, x[3] * sc); w.z = pk2(x[4] * sc, x[5] * sc); w.w = pk2(x[6] * sc, x[7] * sc);
;                 if (isq) *(u32x4*)(q + (size_t)row * 512 + cs) = w; else *(u32x4*)(k + (size_t)row * 128 + cs) = w;
.LBB0_360:
	v_pk_mul_f32 v[168:169], v[196:197], v[168:169] op_sel_hi:[0,1]
	v_pk_mul_f32 v[170:171], v[196:197], v[170:171] op_sel_hi:[0,1]
	v_cvt_pk_bf16_f32 v168, v168, v169
	v_cvt_pk_bf16_f32 v169, v170, v171
	v_pk_mul_f32 v[170:171], v[196:197], v[232:233] op_sel_hi:[0,1]
	v_pk_mul_f32 v[210:211], v[196:197], v[234:235] op_sel_hi:[0,1]
	v_cvt_pk_bf16_f32 v170, v170, v171
	v_cvt_pk_bf16_f32 v171, v210, v211
	s_mov_b64 s[8:9], -1
	s_and_b64 vcc, exec, s[48:49]
	s_cbranch_vccz .LBB0_362
	v_lshlrev_b64 v[210:211], 8, v[198:199]
	v_lshl_add_u64 v[210:211], s[22:23], 0, v[210:211]
	v_lshl_add_u64 v[210:211], v[208:209], 1, v[210:211]
	global_store_dwordx4 v[210:211], v[168:171], off nt
	s_mov_b64 s[8:9], 0
.LBB0_362:
	s_andn2_b64 vcc, exec, s[8:9]
	s_cbranch_vccnz .LBB0_364
	v_lshl_add_u64 v[210:211], s[20:21], 0, v[224:225]
	v_lshl_add_u64 v[210:211], v[208:209], 1, v[210:211]
	global_store_dwordx4 v[210:211], v[168:171], off nt

; __device__ __forceinline__ unsigned pk2(float lo, float hi) { const f32x2 v = {lo, hi}; return __builtin_bit_cast(unsigned, __builtin_convertvector(v, bf16x2_t)); }
; __device__ __forceinline__ float gelu_tanh(float x) { const float y = 0.7978845608028654f * (x + 0.044715f * x * x * x); return x * sigmoidf_(2.f * y); }
;     __device__ __forceinline__ void operator()(const f32x4 (&acc)[2][2][4][2], const Unit& un, int wr, int wc, int fr, int fq) const {
;     ...
;             if (pn < 4) {
;                 u32x4 w; w.x = pk2(gelu_tanh(v0.x), gelu_tanh(v0.y)); w.y = pk2(gelu_tanh(v0.z), gelu_tanh(v0.w)); w.z = pk2(gelu_tanh(v1.x), gelu_tanh(v1.y)); w.w = pk2(gelu_tanh(v1.z), gelu_tanh(v1.w));
;                 *(u32x4*)(ga + (size_t)row * 1024 + pn * 256 + ct) = w;
;     ...
;             } else {
;                 u32x4 w; w.x = pk2(v0.x, v0.y); w.y = pk2(v0.z, v0.w); w.z = pk2(v1.x, v1.y); w.w = pk2(v1.z, v1.w);
;                 const int col = (pn - 11) * 256 + ct;
;                 *(u32x4*)(u + ((size_t)(col >> 4) * NTOK + row) * 16 + (col & 15)) = w;
.LBB0_368:
	v_lshlrev_b64 v[168:169], 11, v[198:199]
	v_lshl_add_u64 v[170:171], s[16:17], 0, v[168:169]
	s_andn2_b64 vcc, exec, s[54:55]
	v_lshlrev_b32_e32 v168, 1, v184
	v_lshl_add_u64 v[170:171], s[50:51], 1, v[170:171]
	s_cbranch_vccnz .LBB0_370
	v_mul_f32_e32 v169, 0x3d372713, v230
	v_mul_f32_e32 v169, v230, v169
	v_fma_f32 v169, v230, v169, v230
	v_mul_f32_e32 v169, 0x3f4c422a, v169
	v_add_f32_e32 v169, v169, v169
	v_mul_f32_e32 v169, 0xbfb8aa3b, v169
	v_exp_f32_e32 v169, v169
	v_mov_b32_e32 v195, v231
	v_add_f32_e32 v169, 1.0, v169
	v_rcp_f32_e32 v210, v169
	v_mul_f32_e32 v169, 0x3d372713, v231
	v_mul_f32_e32 v169, v231, v169
	v_fmac_f32_e32 v195, v195, v169
	v_mul_f32_e32 v169, 0x3f4c422a, v195
	v_add_f32_e32 v169, v169, v169
	v_mul_f32_e32 v169, 0xbfb8aa3b, v169
	v_exp_f32_e32 v169, v169
	v_mov_b32_e32 v195, v175
	v_add_f32_e32 v169, 1.0, v169
	v_rcp_f32_e32 v211, v169
	v_mul_f32_e32 v169, 0x3d372713, v228
	v_mul_f32_e32 v169, v228, v169
	v_fma_f32 v169, v228, v169, v228
	v_mul_f32_e32 v169, 0x3f4c422a, v169
	v_add_f32_e32 v169, v169, v169
	v_mul_f32_e32 v169, 0xbfb8aa3b, v169
	v_exp_f32_e32 v169, v169
	v_pk_mul_f32 v[210:211], v[230:231], v[210:211]
	v_add_f32_e32 v169, 1.0, v169
	v_cvt_pk_bf16_f32 v230, v210, v211
	v_rcp_f32_e32 v210, v169
	v_mul_f32_e32 v169, 0x3d372713, v229
	v_mul_f32_e32 v169, v229, v169
	v_fma_f32 v169, v229, v169, v229
	v_mul_f32_e32 v169, 0x3f4c422a, v169
	v_add_f32_e32 v169, v169, v169
	v_mul_f32_e32 v169, 0xbfb8aa3b, v169
	v_exp_f32_e32 v169, v169
	s_nop 0
	v_add_f32_e32 v169, 1.0, v169
	v_rcp_f32_e32 v211, v169
	v_mul_f32_e32 v169, 0x3d372713, v174
	v_mul_f32_e32 v169, v174, v169
	v_fma_f32 v169, v174, v169, v174
	v_mul_f32_e32 v169, 0x3f4c422a, v169
	v_add_f32_e32 v169, v169, v169
	v_mul_f32_e32 v169, 0xbfb8aa3b, v169
	v_exp_f32_e32 v169, v169
	v_pk_mul_f32 v[210:211], v[228:229], v[210:211]
	v_add_f32_e32 v169, 1.0, v169
	v_cvt_pk_bf16_f32 v231, v210, v211
	v_rcp_f32_e32 v210, v169
	v_mul_f32_e32 v169, 0x3d372713, v175
	v_mul_f32_e32 v169, v175, v169
	v_fmac_f32_e32 v195, v195, v169
	v_mul_f32_e32 v169, 0x3f4c422a, v195
	v_add_f32_e32 v169, v169, v169
	v_mul_f32_e32 v169, 0xbfb8aa3b, v169
	v_exp_f32_e32 v169, v169
	s_nop 0
	v_add_f32_e32 v169, 1.0, v169
	v_rcp_f32_e32 v211, v169
	v_mul_f32_e32 v169, 0x3d372713, v172
	v_mul_f32_e32 v169, v172, v169
	v_fma_f32 v169, v172, v169, v172
	v_mul_f32_e32 v169, 0x3f4c422a, v169
	v_add_f32_e32 v169, v169, v169
	v_mul_f32_e32 v169, 0xbfb8aa3b, v169
	v_exp_f32_e32 v169, v169
	v_pk_mul_f32 v[174:175], v[174:175], v[210:211]
	v_add_f32_e32 v169, 1.0, v169
	v_cvt_pk_bf16_f32 v232, v174, v175
	v_rcp_f32_e32 v174, v169
	v_mul_f32_e32 v169, 0x3d372713, v173
	v_mul_f32_e32 v169, v173, v169
	v_fma_f32 v169, v173, v169, v173
	v_mul_f32_e32 v169, 0x3f4c422a, v169
	v_add_f32_e32 v169, v169, v169
	v_mul_f32_e32 v169, 0xbfb8aa3b, v169
	v_exp_f32_e32 v169, v169
	s_nop 0
	v_add_f32_e32 v169, 1.0, v169
	v_rcp_f32_e32 v175, v169
	v_mov_b32_e32 v169, v209
	v_pk_mul_f32 v[172:173], v[172:173], v[174:175]
	s_nop 0
	v_cvt_pk_bf16_f32 v233, v172, v173
	v_lshl_add_u64 v[172:173], v[170:171], 0, v[168:169]
	global_store_dwordx4 v[172:173], v[230:233], off nt
.LBB0_370:
	s_add_i32 s8, s76, 0xffff8000
	s_ashr_i32 s8, s8, 1
	v_cndmask_b32_e64 v169, 0, 1, s[52:53]
	v_mov_b32_e32 v227, v226
	s_and_b32 s78, s8, 0xffffff80
	s_ashr_i32 s8, s76, 6
	v_mov_b32_e32 v172, v226
	v_mov_b32_e32 v173, v226
	v_cmp_ne_u32_e64 s[10:11], 1, v169
	v_cndmask_b32_e64 v169, 0, 1, s[12:13]
	s_and_b32 s77, s8, 0xffffff80
	v_pk_fma_f32 v[166:167], v[166:167], v[172:173], v[30:31]
	v_pk_fma_f32 v[164:165], v[164:165], v[226:227], v[28:29]
	v_pk_fma_f32 v[162:163], v[162:163], v[172:173], v[26:27]
	v_pk_fma_f32 v[160:161], v[160:161], v[226:227], v[24:25]
	s_mov_b64 s[54:55], -1
	s_andn2_b64 vcc, exec, s[52:53]
	v_cmp_ne_u32_e64 s[8:9], 1, v169
	s_cbranch_vccnz .LBB0_390
	s_and_b64 vcc, exec, s[8:9]
	s_mov_b64 s[12:13], -1
	s_cbranch_vccnz .LBB0_387
	s_andn2_b64 vcc, exec, s[48:49]
	s_cbranch_vccnz .LBB0_381
	s_andn2_b64 vcc, exec, s[46:47]
	s_cbranch_vccnz .LBB0_375
	v_or_b32_e32 v169, s75, v239
	v_lshrrev_b32_e32 v169, 4, v169
	s_mov_b32 s12, 0x8400
	v_mad_u64_u32 v[210:211], s[12:13], v169, s12, v[198:199]
	v_lshlrev_b64 v[210:211], 5, v[210:211]
	v_cvt_pk_bf16_f32 v172, v164, v165
	v_cvt_pk_bf16_f32 v173, v166, v167
	v_cvt_pk_bf16_f32 v174, v160, v161
	v_cvt_pk_bf16_f32 v175, v162, v163
	v_lshl_add_u64 v[210:211], v[186:187], 0, v[210:211]
	s_mov_b64 s[12:13], 0
	global_store_dwordx4 v[210:211], v[172:175], off nt

; __device__ __forceinline__ unsigned pk2(float lo, float hi) { const f32x2 v = {lo, hi}; return __builtin_bit_cast(unsigned, __builtin_convertvector(v, bf16x2_t)); }
;     __device__ __forceinline__ void operator()(const f32x4 (&acc)[2][2][4][2], const Unit& un, int wr, int wc, int fr, int fq) const {
;     ...
;                 const float sc = isq ? QSCALE : 1.f;
;                 u32x4 w; w.x = pk2(x[0] * sc, x[1] * sc); w.y = pk2(x[2] * sc, x[3] * sc); w.z = pk2(x[4] * sc, x[5] * sc); w.w = pk2(x[6] * sc, x[7] * sc);
;                 if (isq) *(u32x4*)(q + (size_t)row * 512 + cs) = w; else *(u32x4*)(k + (size_t)row * 128 + cs) = w;
.LBB0_385:
	s_mov_b32 s12, 0x3e38aa3b
	v_pk_mul_f32 v[172:173], v[172:173], s[12:13] op_sel_hi:[1,0]
	v_pk_mul_f32 v[174:175], v[174:175], s[12:13] op_sel_hi:[1,0]
	v_cvt_pk_bf16_f32 v172, v172, v173
	v_cvt_pk_bf16_f32 v173, v174, v175
	v_pk_mul_f32 v[174:175], v[226:227], s[12:13] op_sel_hi:[1,0]
	v_pk_mul_f32 v[210:211], v[228:229], s[12:13] op_sel_hi:[1,0]
	v_cvt_pk_bf16_f32 v174, v174, v175
	v_cvt_pk_bf16_f32 v175, v210, v211
	v_lshl_add_u64 v[210:211], s[20:21], 0, v[224:225]
	v_add_u32_e32 v208, s37, v184
	v_lshl_add_u64 v[210:211], v[208:209], 1, v[210:211]
	global_store_dwordx4 v[210:211], v[172:175], off offset:256 nt

;     __device__ __forceinline__ void operator()(const f32x4 (&acc)[2][2][4][2], const Unit& un, int wr, int wc, int fr, int fq) const {
;     ...
;             const f32x4 v0 = acc[ai][bj][m][0] * rr[ai][m] + s0[bj], v1 = acc[ai][bj][m][1] * rr[ai][m] + s1[bj];
;             if (pn < 4) {
;                 u32x4 w; w.x = pk2(gelu_tanh(v0.x), gelu_tanh(v0.y)); w.y = pk2(gelu_tanh(v0.z), gelu_tanh(v0.w)); w.z = pk2(gelu_tanh(v1.x), gelu_tanh(v1.y)); w.w = pk2(gelu_tanh(v1.z), gelu_tanh(v1.w));
;                 *(u32x4*)(ga + (size_t)row * 1024 + pn * 256 + ct) = w;
;             } else if (pn < 8) {
;                 u32x2 w; w.x = pk2(v0.x * sigmoidf_(v0.y), v0.z * sigmoidf_(v0.w)); w.y = pk2(v1.x * sigmoidf_(v1.y), v1.z * sigmoidf_(v1.w));
;                 *(u32x2*)(yb + (size_t)row * 512 + (((pn - 4) * 256 + ct) >> 1)) = w;
;             } else if (pn < 10 || (pn == 10 && bj == 0)) {
;                 const bool isq = pn < 10; const int cs = isq ? (pn - 8) * 256 + ct : ct;
;                 float x[8] = {v0.x, v0.y, v0.z, v0.w, v1.x, v1.y, v1.z, v1.w};
;                 if (lat) { const f32x4 ra = rp[m][0], rb = rp[m][1]; const float cc[4] = {ra.x, ra.z, rb.x, rb.z}, sn[4] = {ra.y, ra.w, rb.y, rb.w};
; #pragma unroll
;                     for (int jj = 0; jj < 4; ++jj) { const float x1 = x[2 * jj], x2 = x[2 * jj + 1]; x[2 * jj] = x1 * cc[jj] - x2 * sn[jj]; x[2 * jj + 1] = x1 * sn[jj] + x2 * cc[jj]; } }
;                 const float sc = isq ? QSCALE : 1.f;
;                 u32x4 w; w.x = pk2(x[0] * sc, x[1] * sc); w.y = pk2(x[2] * sc, x[3] * sc); w.z = pk2(x[4] * sc, x[5] * sc); w.w = pk2(x[6] * sc, x[7] * sc);
;                 if (isq) *(u32x4*)(q + (size_t)row * 512 + cs) = w; else *(u32x4*)(k + (size_t)row * 128 + cs) = w;
;             } else if (pn == 10) {
;                 const int dc = ct - 128; const float x[8] = {v0.x, v0.y, v0.z, v0.w, v1.x, v1.y, v1.z, v1.w};
;                 if (lat) { const int b = row >> 13, t = row & (SEQ - 1);
; #pragma unroll
;                     for (int e = 0; e < 8; ++e) vT[((size_t)(b * 128 + dc + e)) * SEQ + t] = (bf16)f2bf(x[e]); }
;                 else { const int rc = row - NLAT, b = rc >> 8, t = rc & 255;
; #pragma unroll
;                     for (int e = 0; e < 8; ++e) vcT[((size_t)(b * 128 + dc + e)) * CTXL + t] = (bf16)f2bf(x[e]); }
;             } else {
.LBB0_390:
	s_andn2_b64 vcc, exec, s[54:55]
	s_cbranch_vccnz .LBB0_392
	v_mul_f32_e32 v169, 0x3d372713, v164
	v_mul_f32_e32 v169, v164, v169
	v_fma_f32 v169, v164, v169, v164
	v_mul_f32_e32 v169, 0x3f4c422a, v169
	v_add_f32_e32 v169, v169, v169
	v_mul_f32_e32 v169, 0xbfb8aa3b, v169
	v_exp_f32_e32 v169, v169
	v_mov_b32_e32 v173, v165
	v_add_f32_e32 v169, 1.0, v169
	v_rcp_f32_e32 v172, v169
	v_mul_f32_e32 v169, 0x3d372713, v165
	v_mul_f32_e32 v169, v165, v169
	v_fmac_f32_e32 v173, v173, v169
	v_mul_f32_e32 v169, 0x3f4c422a, v173
	v_add_f32_e32 v169, v169, v169
	v_mul_f32_e32 v169, 0xbfb8aa3b, v169
	v_exp_f32_e32 v169, v169
	s_nop 0
	v_add_f32_e32 v169, 1.0, v169
	v_rcp_f32_e32 v173, v169
	v_mov_b32_e32 v169, v161
	v_pk_mul_f32 v[164:165], v[164:165], v[172:173]
	s_nop 0
	v_cvt_pk_bf16_f32 v164, v164, v165
	v_mul_f32_e32 v165, 0x3d372713, v166
	v_mul_f32_e32 v165, v166, v165
	v_fma_f32 v165, v166, v165, v166
	v_mul_f32_e32 v165, 0x3f4c422a, v165
	v_add_f32_e32 v165, v165, v165
	v_mul_f32_e32 v165, 0xbfb8aa3b, v165
	v_exp_f32_e32 v165, v165
	s_nop 0
	v_add_f32_e32 v165, 1.0, v165
	v_rcp_f32_e32 v172, v165
	v_mul_f32_e32 v165, 0x3d372713, v167
	v_mul_f32_e32 v165, v167, v165
	v_fma_f32 v165, v167, v165, v167
	v_mul_f32_e32 v165, 0x3f4c422a, v165
	v_add_f32_e32 v165, v165, v165
	v_mul_f32_e32 v165, 0xbfb8aa3b, v165
	v_exp_f32_e32 v165, v165
	s_nop 0
	v_add_f32_e32 v165, 1.0, v165
	v_rcp_f32_e32 v173, v165
	s_nop 0
	v_pk_mul_f32 v[166:167], v[166:167], v[172:173]
	s_nop 0
	v_cvt_pk_bf16_f32 v165, v166, v167
	v_mul_f32_e32 v166, 0x3d372713, v160
	v_mul_f32_e32 v167, 0x3d372713, v161
	v_mul_f32_e32 v166, v160, v166
	v_mul_f32_e32 v167, v161, v167
	v_fma_f32 v166, v160, v166, v160
	v_fmac_f32_e32 v169, v169, v167
	v_mul_f32_e32 v166, 0x3f4c422a, v166
	v_mul_f32_e32 v167, 0x3f4c422a, v169
	v_add_f32_e32 v166, v166, v166
	v_add_f32_e32 v167, v167, v167
	v_mul_f32_e32 v166, 0xbfb8aa3b, v166
	v_mul_f32_e32 v167, 0xbfb8aa3b, v167
	v_exp_f32_e32 v166, v166
	v_exp_f32_e32 v167, v167
	v_mov_b32_e32 v169, v209
	v_add_f32_e32 v166, 1.0, v166
	v_add_f32_e32 v167, 1.0, v167
	v_rcp_f32_e32 v166, v166
	v_rcp_f32_e32 v167, v167
	s_nop 0
	v_pk_mul_f32 v[160:161], v[160:161], v[166:167]
	s_nop 0
	v_cvt_pk_bf16_f32 v166, v160, v161
	v_mul_f32_e32 v160, 0x3d372713, v162
	v_mul_f32_e32 v161, 0x3d372713, v163
	v_mul_f32_e32 v160, v162, v160
	v_mul_f32_e32 v161, v163, v161
	v_fma_f32 v160, v162, v160, v162
	v_fma_f32 v161, v163, v161, v163
	v_mul_f32_e32 v160, 0x3f4c422a, v160
	v_mul_f32_e32 v161, 0x3f4c422a, v161
	v_add_f32_e32 v160, v160, v160
	v_add_f32_e32 v161, v161, v161
	v_mul_f32_e32 v160, 0xbfb8aa3b, v160
	v_mul_f32_e32 v161, 0xbfb8aa3b, v161
	v_exp_f32_e32 v160, v160
	v_exp_f32_e32 v161, v161
	v_add_f32_e32 v160, 1.0, v160
	v_add_f32_e32 v161, 1.0, v161
	v_rcp_f32_e32 v160, v160
	v_rcp_f32_e32 v161, v161
	s_nop 0
	v_pk_mul_f32 v[160:161], v[162:163], v[160:161]
	s_nop 0
	v_cvt_pk_bf16_f32 v167, v160, v161
	v_lshl_add_u64 v[160:161], v[170:171], 0, v[168:169]
	global_store_dwordx4 v[160:161], v[164:167], off offset:256 nt
.LBB0_392:
	v_lshlrev_b64 v[160:161], 10, v[220:221]
	v_pk_fma_f32 v[162:163], v[158:159], v[222:223], v[46:47] op_sel_hi:[1,0,1]
	v_pk_fma_f32 v[164:165], v[156:157], v[222:223], v[44:45] op_sel_hi:[1,0,1]
	v_pk_fma_f32 v[156:157], v[154:155], v[222:223], v[42:43] op_sel_hi:[1,0,1]
	v_pk_fma_f32 v[158:159], v[152:153], v[222:223], v[40:41] op_sel_hi:[1,0,1]
	s_and_b64 vcc, exec, s[10:11]
	s_mov_b64 s[12:13], -1
	s_cbranch_vccnz .LBB0_412
	s_and_b64 vcc, exec, s[8:9]
	s_cbranch_vccnz .LBB0_409
	v_cndmask_b32_e64 v152, 0, 1, s[48:49]
	v_cmp_ne_u32_e64 s[12:13], 1, v152
	s_andn2_b64 vcc, exec, s[48:49]
	s_cbranch_vccnz .LBB0_398
	s_mov_b64 s[52:53], -1
	s_and_b64 vcc, exec, s[46:47]
	s_cbranch_vccz .LBB0_397
	v_or_b32_e32 v166, s75, v184
	v_lshrrev_b32_e32 v166, 4, v166
	s_mov_b32 s52, 0x8400
	v_mad_u64_u32 v[166:167], s[52:53], v166, s52, v[220:221]
	v_lshlrev_b64 v[166:167], 5, v[166:167]
	v_cvt_pk_bf16_f32 v152, v164, v165
	v_cvt_pk_bf16_f32 v153, v162, v163
	v_cvt_pk_bf16_f32 v154, v158, v159
	v_cvt_pk_bf16_f32 v155, v156, v157
	v_lshl_add_u64 v[166:167], v[186:187], 0, v[166:167]
	s_mov_b64 s[52:53], 0
	global_store_dwordx4 v[166:167], v[152:155], off nt

; __device__ __forceinline__ unsigned pk2(float lo, float hi) { const f32x2 v = {lo, hi}; return __builtin_bit_cast(unsigned, __builtin_convertvector(v, bf16x2_t)); }
;     __device__ __forceinline__ void operator()(const f32x4 (&acc)[2][2][4][2], const Unit& un, int wr, int wc, int fr, int fq) const {
;     ...
;                 const bool isq = pn < 10; const int cs = isq ? (pn - 8) * 256 + ct : ct;
;                 float x[8] = {v0.x, v0.y, v0.z, v0.w, v1.x, v1.y, v1.z, v1.w};
;                 if (lat) { const f32x4 ra = rp[m][0], rb = rp[m][1]; const float cc[4] = {ra.x, ra.z, rb.x, rb.z}, sn[4] = {ra.y, ra.w, rb.y, rb.w};
; #pragma unroll
;                     for (int jj = 0; jj < 4; ++jj) { const float x1 = x[2 * jj], x2 = x[2 * jj + 1]; x[2 * jj] = x1 * cc[jj] - x2 * sn[jj]; x[2 * jj + 1] = x1 * sn[jj] + x2 * cc[jj]; } }
;                 const float sc = isq ? QSCALE : 1.f;
;                 u32x4 w; w.x = pk2(x[0] * sc, x[1] * sc); w.y = pk2(x[2] * sc, x[3] * sc); w.z = pk2(x[4] * sc, x[5] * sc); w.w = pk2(x[6] * sc, x[7] * sc);
;                 if (isq) *(u32x4*)(q + (size_t)row * 512 + cs) = w; else *(u32x4*)(k + (size_t)row * 128 + cs) = w;
.LBB0_404:
	v_pk_mul_f32 v[152:153], v[196:197], v[152:153] op_sel_hi:[0,1]
	v_pk_mul_f32 v[154:155], v[196:197], v[154:155] op_sel_hi:[0,1]
	v_cvt_pk_bf16_f32 v152, v152, v153
	v_cvt_pk_bf16_f32 v153, v154, v155
	v_pk_mul_f32 v[154:155], v[196:197], v[166:167] op_sel_hi:[0,1]
	v_pk_mul_f32 v[166:167], v[196:197], v[170:171] op_sel_hi:[0,1]
	v_cvt_pk_bf16_f32 v154, v154, v155
	v_cvt_pk_bf16_f32 v155, v166, v167
	s_and_b64 vcc, exec, s[12:13]
	s_mov_b64 s[12:13], -1
	s_cbranch_vccnz .LBB0_406
	v_lshlrev_b64 v[166:167], 8, v[220:221]
	v_lshl_add_u64 v[166:167], s[22:23], 0, v[166:167]
	v_lshl_add_u64 v[166:167], v[208:209], 1, v[166:167]
	s_mov_b64 s[12:13], 0
	global_store_dwordx4 v[166:167], v[152:155], off nt
.LBB0_406:
	s_andn2_b64 vcc, exec, s[12:13]
	s_cbranch_vccnz .LBB0_408
	v_lshl_add_u64 v[166:167], s[20:21], 0, v[160:161]
	v_lshl_add_u64 v[166:167], v[208:209], 1, v[166:167]
	global_store_dwordx4 v[166:167], v[152:155], off nt

;     __device__ __forceinline__ void operator()(const f32x4 (&acc)[2][2][4][2], const Unit& un, int wr, int wc, int fr, int fq) const {
;     ...
;             const f32x4 v0 = acc[ai][bj][m][0] * rr[ai][m] + s0[bj], v1 = acc[ai][bj][m][1] * rr[ai][m] + s1[bj];
;             if (pn < 4) {
;                 u32x4 w; w.x = pk2(gelu_tanh(v0.x), gelu_tanh(v0.y)); w.y = pk2(gelu_tanh(v0.z), gelu_tanh(v0.w)); w.z = pk2(gelu_tanh(v1.x), gelu_tanh(v1.y)); w.w = pk2(gelu_tanh(v1.z), gelu_tanh(v1.w));
;                 *(u32x4*)(ga + (size_t)row * 1024 + pn * 256 + ct) = w;
;             } else if (pn < 8) {
;                 u32x2 w; w.x = pk2(v0.x * sigmoidf_(v0.y), v0.z * sigmoidf_(v0.w)); w.y = pk2(v1.x * sigmoidf_(v1.y), v1.z * sigmoidf_(v1.w));
;                 *(u32x2*)(yb + (size_t)row * 512 + (((pn - 4) * 256 + ct) >> 1)) = w;
;             } else if (pn < 10 || (pn == 10 && bj == 0)) {
;                 const bool isq = pn < 10; const int cs = isq ? (pn - 8) * 256 + ct : ct;
;                 float x[8] = {v0.x, v0.y, v0.z, v0.w, v1.x, v1.y, v1.z, v1.w};
;                 if (lat) { const f32x4 ra = rp[m][0], rb = rp[m][1]; const float cc[4] = {ra.x, ra.z, rb.x, rb.z}, sn[4] = {ra.y, ra.w, rb.y, rb.w};
; #pragma unroll
;                     for (int jj = 0; jj < 4; ++jj) { const float x1 = x[2 * jj], x2 = x[2 * jj + 1]; x[2 * jj] = x1 * cc[jj] - x2 * sn[jj]; x[2 * jj + 1] = x1 * sn[jj] + x2 * cc[jj]; } }
;                 const float sc = isq ? QSCALE : 1.f;
;                 u32x4 w; w.x = pk2(x[0] * sc, x[1] * sc); w.y = pk2(x[2] * sc, x[3] * sc); w.z = pk2(x[4] * sc, x[5] * sc); w.w = pk2(x[6] * sc, x[7] * sc);
;                 if (isq) *(u32x4*)(q + (size_t)row * 512 + cs) = w; else *(u32x4*)(k + (size_t)row * 128 + cs) = w;
;             } else if (pn == 10) {
;                 const int dc = ct - 128; const float x[8] = {v0.x, v0.y, v0.z, v0.w, v1.x, v1.y, v1.z, v1.w};
;                 if (lat) { const int b = row >> 13, t = row & (SEQ - 1);
; #pragma unroll
;                     for (int e = 0; e < 8; ++e) vT[((size_t)(b * 128 + dc + e)) * SEQ + t] = (bf16)f2bf(x[e]); }
;                 else { const int rc = row - NLAT, b = rc >> 8, t = rc & 255;
; #pragma unroll
;                     for (int e = 0; e < 8; ++e) vcT[((size_t)(b * 128 + dc + e)) * CTXL + t] = (bf16)f2bf(x[e]); }
;             } else {
.LBB0_412:
	v_lshlrev_b64 v[152:153], 11, v[220:221]
	v_lshl_add_u64 v[152:153], s[16:17], 0, v[152:153]
	s_andn2_b64 vcc, exec, s[12:13]
	v_lshl_add_u64 v[152:153], s[50:51], 1, v[152:153]
	s_cbranch_vccnz .LBB0_414
	v_mul_f32_e32 v154, 0x3d372713, v164
	v_mul_f32_e32 v155, 0x3d372713, v165
	v_mul_f32_e32 v154, v164, v154
	v_mul_f32_e32 v155, v165, v155
	v_mov_b32_e32 v166, v165
	v_fma_f32 v154, v164, v154, v164
	v_fmac_f32_e32 v166, v166, v155
	v_mul_f32_e32 v154, 0x3f4c422a, v154
	v_mul_f32_e32 v155, 0x3f4c422a, v166
	v_add_f32_e32 v154, v154, v154
	v_add_f32_e32 v155, v155, v155
	v_mul_f32_e32 v154, 0xbfb8aa3b, v154
	v_mul_f32_e32 v155, 0xbfb8aa3b, v155
	v_exp_f32_e32 v154, v154
	v_exp_f32_e32 v155, v155
	v_mov_b32_e32 v169, v209
	v_add_f32_e32 v154, 1.0, v154
	v_add_f32_e32 v155, 1.0, v155
	v_rcp_f32_e32 v154, v154
	v_rcp_f32_e32 v155, v155
	s_nop 0
	v_pk_mul_f32 v[154:155], v[164:165], v[154:155]
	s_nop 0
	v_cvt_pk_bf16_f32 v164, v154, v155
	v_mul_f32_e32 v154, 0x3d372713, v162
	v_mul_f32_e32 v155, 0x3d372713, v163
	v_mul_f32_e32 v154, v162, v154
	v_mul_f32_e32 v155, v163, v155
	v_fma_f32 v154, v162, v154, v162
	v_fma_f32 v155, v163, v155, v163
	v_mul_f32_e32 v154, 0x3f4c422a, v154
	v_mul_f32_e32 v155, 0x3f4c422a, v155
	v_add_f32_e32 v154, v154, v154
	v_add_f32_e32 v155, v155, v155
	v_mul_f32_e32 v154, 0xbfb8aa3b, v154
	v_mul_f32_e32 v155, 0xbfb8aa3b, v155
	v_exp_f32_e32 v154, v154
	v_exp_f32_e32 v155, v155
	v_add_f32_e32 v154, 1.0, v154
	v_add_f32_e32 v155, 1.0, v155
	v_rcp_f32_e32 v154, v154
	v_rcp_f32_e32 v155, v155
	s_nop 0
	v_pk_mul_f32 v[154:155], v[162:163], v[154:155]
	s_nop 0
	v_cvt_pk_bf16_f32 v165, v154, v155
	v_mul_f32_e32 v154, 0x3d372713, v158
	v_mul_f32_e32 v155, 0x3d372713, v159
	v_mul_f32_e32 v154, v158, v154
	v_mul_f32_e32 v155, v159, v155
	v_mov_b32_e32 v162, v159
	v_fma_f32 v154, v158, v154, v158
	v_fmac_f32_e32 v162, v162, v155
	v_mul_f32_e32 v154, 0x3f4c422a, v154
	v_mul_f32_e32 v155, 0x3f4c422a, v162
	v_add_f32_e32 v154, v154, v154
	v_add_f32_e32 v155, v155, v155
	v_mul_f32_e32 v154, 0xbfb8aa3b, v154
	v_mul_f32_e32 v155, 0xbfb8aa3b, v155
	v_exp_f32_e32 v154, v154
	v_exp_f32_e32 v155, v155
	v_add_f32_e32 v154, 1.0, v154
	v_add_f32_e32 v155, 1.0, v155
	v_rcp_f32_e32 v154, v154
	v_rcp_f32_e32 v155, v155
	s_nop 0
	v_pk_mul_f32 v[154:155], v[158:159], v[154:155]
	s_nop 0
	v_cvt_pk_bf16_f32 v166, v154, v155
	v_mul_f32_e32 v154, 0x3d372713, v156
	v_mul_f32_e32 v155, 0x3d372713, v157
	v_mul_f32_e32 v154, v156, v154
	v_mul_f32_e32 v155, v157, v155
	v_fma_f32 v154, v156, v154, v156
	v_fma_f32 v155, v157, v155, v157
	v_mul_f32_e32 v154, 0x3f4c422a, v154
	v_mul_f32_e32 v155, 0x3f4c422a, v155
	v_add_f32_e32 v154, v154, v154
	v_add_f32_e32 v155, v155, v155
	v_mul_f32_e32 v154, 0xbfb8aa3b, v154
	v_mul_f32_e32 v155, 0xbfb8aa3b, v155
	v_exp_f32_e32 v154, v154
	v_exp_f32_e32 v155, v155
	v_add_f32_e32 v154, 1.0, v154
	v_add_f32_e32 v155, 1.0, v155
	v_rcp_f32_e32 v154, v154
	v_rcp_f32_e32 v155, v155
	s_nop 0
	v_pk_mul_f32 v[154:155], v[156:157], v[154:155]
	s_nop 0
	v_cvt_pk_bf16_f32 v167, v154, v155
	v_lshl_add_u64 v[154:155], v[152:153], 0, v[168:169]
	global_store_dwordx4 v[154:155], v[164:167], off nt
.LBB0_414:
	v_mov_b32_e32 v223, v222
	v_mov_b32_e32 v154, v222
	v_mov_b32_e32 v155, v222
	v_pk_fma_f32 v[150:151], v[150:151], v[154:155], v[30:31]
	v_pk_fma_f32 v[148:149], v[148:149], v[222:223], v[28:29]
	v_pk_fma_f32 v[146:147], v[146:147], v[154:155], v[26:27]
	v_pk_fma_f32 v[144:145], v[144:145], v[222:223], v[24:25]
	s_and_b64 vcc, exec, s[10:11]
	s_mov_b64 s[12:13], -1
	s_cbranch_vccnz .LBB0_434
	s_and_b64 vcc, exec, s[8:9]
	s_cbranch_vccnz .LBB0_431
	s_andn2_b64 vcc, exec, s[48:49]
	s_cbranch_vccnz .LBB0_425
	s_andn2_b64 vcc, exec, s[46:47]
	s_cbranch_vccnz .LBB0_419
	v_or_b32_e32 v158, s75, v239
	v_lshrrev_b32_e32 v158, 4, v158
	s_mov_b32 s12, 0x8400
	v_mad_u64_u32 v[158:159], s[12:13], v158, s12, v[220:221]
	v_lshlrev_b64 v[158:159], 5, v[158:159]
	v_cvt_pk_bf16_f32 v154, v148, v149
	v_cvt_pk_bf16_f32 v155, v150, v151
	v_cvt_pk_bf16_f32 v156, v144, v145
	v_cvt_pk_bf16_f32 v157, v146, v147
	v_lshl_add_u64 v[158:159], v[186:187], 0, v[158:159]
	s_mov_b64 s[12:13], 0
	global_store_dwordx4 v[158:159], v[154:157], off nt

; __device__ __forceinline__ unsigned pk2(float lo, float hi) { const f32x2 v = {lo, hi}; return __builtin_bit_cast(unsigned, __builtin_convertvector(v, bf16x2_t)); }
;     __device__ __forceinline__ void operator()(const f32x4 (&acc)[2][2][4][2], const Unit& un, int wr, int wc, int fr, int fq) const {
;     ...
;                 const float sc = isq ? QSCALE : 1.f;
;                 u32x4 w; w.x = pk2(x[0] * sc, x[1] * sc); w.y = pk2(x[2] * sc, x[3] * sc); w.z = pk2(x[4] * sc, x[5] * sc); w.w = pk2(x[6] * sc, x[7] * sc);
;                 if (isq) *(u32x4*)(q + (size_t)row * 512 + cs) = w; else *(u32x4*)(k + (size_t)row * 128 + cs) = w;
.LBB0_429:
	s_mov_b32 s12, 0x3e38aa3b
	v_pk_mul_f32 v[154:155], v[154:155], s[12:13] op_sel_hi:[1,0]
	v_pk_mul_f32 v[156:157], v[156:157], s[12:13] op_sel_hi:[1,0]
	v_cvt_pk_bf16_f32 v154, v154, v155
	v_cvt_pk_bf16_f32 v155, v156, v157
	v_pk_mul_f32 v[156:157], v[158:159], s[12:13] op_sel_hi:[1,0]
	v_pk_mul_f32 v[158:159], v[162:163], s[12:13] op_sel_hi:[1,0]
	v_cvt_pk_bf16_f32 v156, v156, v157
	v_cvt_pk_bf16_f32 v157, v158, v159
	v_lshl_add_u64 v[158:159], s[20:21], 0, v[160:161]
	v_add_u32_e32 v208, s37, v184
	v_lshl_add_u64 v[158:159], v[208:209], 1, v[158:159]
	global_store_dwordx4 v[158:159], v[154:157], off offset:256 nt

;     __device__ __forceinline__ void operator()(const f32x4 (&acc)[2][2][4][2], const Unit& un, int wr, int wc, int fr, int fq) const {
;     ...
;             const f32x4 v0 = acc[ai][bj][m][0] * rr[ai][m] + s0[bj], v1 = acc[ai][bj][m][1] * rr[ai][m] + s1[bj];
;             if (pn < 4) {
;                 u32x4 w; w.x = pk2(gelu_tanh(v0.x), gelu_tanh(v0.y)); w.y = pk2(gelu_tanh(v0.z), gelu_tanh(v0.w)); w.z = pk2(gelu_tanh(v1.x), gelu_tanh(v1.y)); w.w = pk2(gelu_tanh(v1.z), gelu_tanh(v1.w));
;                 *(u32x4*)(ga + (size_t)row * 1024 + pn * 256 + ct) = w;
;             } else if (pn < 8) {
;                 u32x2 w; w.x = pk2(v0.x * sigmoidf_(v0.y), v0.z * sigmoidf_(v0.w)); w.y = pk2(v1.x * sigmoidf_(v1.y), v1.z * sigmoidf_(v1.w));
;                 *(u32x2*)(yb + (size_t)row * 512 + (((pn - 4) * 256 + ct) >> 1)) = w;
;             } else if (pn < 10 || (pn == 10 && bj == 0)) {
;                 const bool isq = pn < 10; const int cs = isq ? (pn - 8) * 256 + ct : ct;
;                 float x[8] = {v0.x, v0.y, v0.z, v0.w, v1.x, v1.y, v1.z, v1.w};
;                 if (lat) { const f32x4 ra = rp[m][0], rb = rp[m][1]; const float cc[4] = {ra.x, ra.z, rb.x, rb.z}, sn[4] = {ra.y, ra.w, rb.y, rb.w};
; #pragma unroll
;                     for (int jj = 0; jj < 4; ++jj) { const float x1 = x[2 * jj], x2 = x[2 * jj + 1]; x[2 * jj] = x1 * cc[jj] - x2 * sn[jj]; x[2 * jj + 1] = x1 * sn[jj] + x2 * cc[jj]; } }
;                 const float sc = isq ? QSCALE : 1.f;
;                 u32x4 w; w.x = pk2(x[0] * sc, x[1] * sc); w.y = pk2(x[2] * sc, x[3] * sc); w.z = pk2(x[4] * sc, x[5] * sc); w.w = pk2(x[6] * sc, x[7] * sc);
;                 if (isq) *(u32x4*)(q + (size_t)row * 512 + cs) = w; else *(u32x4*)(k + (size_t)row * 128 + cs) = w;
;             } else if (pn == 10) {
;                 const int dc = ct - 128; const float x[8] = {v0.x, v0.y, v0.z, v0.w, v1.x, v1.y, v1.z, v1.w};
;                 if (lat) { const int b = row >> 13, t = row & (SEQ - 1);
; #pragma unroll
;                     for (int e = 0; e < 8; ++e) vT[((size_t)(b * 128 + dc + e)) * SEQ + t] = (bf16)f2bf(x[e]); }
;                 else { const int rc = row - NLAT, b = rc >> 8, t = rc & 255;
; #pragma unroll
;                     for (int e = 0; e < 8; ++e) vcT[((size_t)(b * 128 + dc + e)) * CTXL + t] = (bf16)f2bf(x[e]); }
;             } else {
.LBB0_434:
	s_andn2_b64 vcc, exec, s[12:13]
	s_cbranch_vccnz .LBB0_436
	v_mul_f32_e32 v154, 0x3d372713, v148
	v_mul_f32_e32 v155, 0x3d372713, v149
	v_mul_f32_e32 v154, v148, v154
	v_mul_f32_e32 v155, v149, v155
	v_mov_b32_e32 v156, v149
	v_fma_f32 v154, v148, v154, v148
	v_fmac_f32_e32 v156, v156, v155
	v_mul_f32_e32 v154, 0x3f4c422a, v154
	v_mul_f32_e32 v155, 0x3f4c422a, v156
	v_add_f32_e32 v154, v154, v154
	v_add_f32_e32 v155, v155, v155
	v_mul_f32_e32 v154, 0xbfb8aa3b, v154
	v_mul_f32_e32 v155, 0xbfb8aa3b, v155
	v_exp_f32_e32 v154, v154
	v_exp_f32_e32 v155, v155
	v_mov_b32_e32 v169, v209
	v_add_f32_e32 v154, 1.0, v154
	v_add_f32_e32 v155, 1.0, v155
	v_rcp_f32_e32 v154, v154
	v_rcp_f32_e32 v155, v155
	s_nop 0
	v_pk_mul_f32 v[148:149], v[148:149], v[154:155]
	s_nop 0
	v_cvt_pk_bf16_f32 v148, v148, v149
	v_mul_f32_e32 v149, 0x3d372713, v150
	v_mul_f32_e32 v149, v150, v149
	v_fma_f32 v149, v150, v149, v150
	v_mul_f32_e32 v149, 0x3f4c422a, v149
	v_add_f32_e32 v149, v149, v149
	v_mul_f32_e32 v149, 0xbfb8aa3b, v149
	v_exp_f32_e32 v149, v149
	s_nop 0
	v_add_f32_e32 v149, 1.0, v149
	v_rcp_f32_e32 v154, v149
	v_mul_f32_e32 v149, 0x3d372713, v151
	v_mul_f32_e32 v149, v151, v149
	v_fma_f32 v149, v151, v149, v151
	v_mul_f32_e32 v149, 0x3f4c422a, v149
	v_add_f32_e32 v149, v149, v149
	v_mul_f32_e32 v149, 0xbfb8aa3b, v149
	v_exp_f32_e32 v149, v149
	s_nop 0
	v_add_f32_e32 v149, 1.0, v149
	v_rcp_f32_e32 v155, v149
	s_nop 0
	v_pk_mul_f32 v[150:151], v[150:151], v[154:155]
	s_nop 0
	v_cvt_pk_bf16_f32 v149, v150, v151
	v_mul_f32_e32 v150, 0x3d372713, v144
	v_mul_f32_e32 v151, 0x3d372713, v145
	v_mul_f32_e32 v150, v144, v150
	v_mul_f32_e32 v151, v145, v151
	v_mov_b32_e32 v154, v145
	v_fma_f32 v150, v144, v150, v144
	v_fmac_f32_e32 v154, v154, v151
	v_mul_f32_e32 v150, 0x3f4c422a, v150
	v_mul_f32_e32 v151, 0x3f4c422a, v154
	v_add_f32_e32 v150, v150, v150
	v_add_f32_e32 v151, v151, v151
	v_mul_f32_e32 v150, 0xbfb8aa3b, v150
	v_mul_f32_e32 v151, 0xbfb8aa3b, v151
	v_exp_f32_e32 v150, v150
	v_exp_f32_e32 v151, v151
	v_add_f32_e32 v150, 1.0, v150
	v_add_f32_e32 v151, 1.0, v151
	v_rcp_f32_e32 v150, v150
	v_rcp_f32_e32 v151, v151
	s_nop 0
	v_pk_mul_f32 v[144:145], v[144:145], v[150:151]
	s_nop 0
	v_cvt_pk_bf16_f32 v150, v144, v145
	v_mul_f32_e32 v144, 0x3d372713, v146
	v_mul_f32_e32 v145, 0x3d372713, v147
	v_mul_f32_e32 v144, v146, v144
	v_mul_f32_e32 v145, v147, v145
	v_fma_f32 v144, v146, v144, v146
	v_fma_f32 v145, v147, v145, v147
	v_mul_f32_e32 v144, 0x3f4c422a, v144
	v_mul_f32_e32 v145, 0x3f4c422a, v145
	v_add_f32_e32 v144, v144, v144
	v_add_f32_e32 v145, v145, v145
	v_mul_f32_e32 v144, 0xbfb8aa3b, v144
	v_mul_f32_e32 v145, 0xbfb8aa3b, v145
	v_exp_f32_e32 v144, v144
	v_exp_f32_e32 v145, v145
	v_add_f32_e32 v144, 1.0, v144
	v_add_f32_e32 v145, 1.0, v145
	v_rcp_f32_e32 v144, v144
	v_rcp_f32_e32 v145, v145
	s_nop 0
	v_pk_mul_f32 v[144:145], v[146:147], v[144:145]
	s_nop 0
	v_cvt_pk_bf16_f32 v151, v144, v145
	v_lshl_add_u64 v[144:145], v[152:153], 0, v[168:169]
	global_store_dwordx4 v[144:145], v[148:151], off offset:256 nt
.LBB0_436:
	v_lshlrev_b64 v[144:145], 10, v[216:217]
	v_pk_fma_f32 v[146:147], v[142:143], v[218:219], v[46:47] op_sel_hi:[1,0,1]
	v_pk_fma_f32 v[148:149], v[140:141], v[218:219], v[44:45] op_sel_hi:[1,0,1]
	v_pk_fma_f32 v[140:141], v[138:139], v[218:219], v[42:43] op_sel_hi:[1,0,1]
	v_pk_fma_f32 v[142:143], v[136:137], v[218:219], v[40:41] op_sel_hi:[1,0,1]
	s_and_b64 vcc, exec, s[10:11]
	s_mov_b64 s[12:13], -1
	s_cbranch_vccnz .LBB0_456
	s_and_b64 vcc, exec, s[8:9]
	s_cbranch_vccnz .LBB0_453
	v_cndmask_b32_e64 v136, 0, 1, s[48:49]
	v_cmp_ne_u32_e64 s[12:13], 1, v136
	s_andn2_b64 vcc, exec, s[48:49]
	s_cbranch_vccnz .LBB0_442
	s_mov_b64 s[52:53], -1
	s_and_b64 vcc, exec, s[46:47]
	s_cbranch_vccz .LBB0_441
	v_or_b32_e32 v150, s75, v184
	v_lshrrev_b32_e32 v150, 4, v150
	s_mov_b32 s52, 0x8400
	v_mad_u64_u32 v[150:151], s[52:53], v150, s52, v[216:217]
	v_lshlrev_b64 v[150:151], 5, v[150:151]
	v_cvt_pk_bf16_f32 v136, v148, v149
	v_cvt_pk_bf16_f32 v137, v146, v147
	v_cvt_pk_bf16_f32 v138, v142, v143
	v_cvt_pk_bf16_f32 v139, v140, v141
	v_lshl_add_u64 v[150:151], v[186:187], 0, v[150:151]
	s_mov_b64 s[52:53], 0
	global_store_dwordx4 v[150:151], v[136:139], off nt

; __device__ __forceinline__ unsigned pk2(float lo, float hi) { const f32x2 v = {lo, hi}; return __builtin_bit_cast(unsigned, __builtin_convertvector(v, bf16x2_t)); }
;     __device__ __forceinline__ void operator()(const f32x4 (&acc)[2][2][4][2], const Unit& un, int wr, int wc, int fr, int fq) const {
;     ...
;                 const bool isq = pn < 10; const int cs = isq ? (pn - 8) * 256 + ct : ct;
;                 float x[8] = {v0.x, v0.y, v0.z, v0.w, v1.x, v1.y, v1.z, v1.w};
;                 if (lat) { const f32x4 ra = rp[m][0], rb = rp[m][1]; const float cc[4] = {ra.x, ra.z, rb.x, rb.z}, sn[4] = {ra.y, ra.w, rb.y, rb.w};
; #pragma unroll
;                     for (int jj = 0; jj < 4; ++jj) { const float x1 = x[2 * jj], x2 = x[2 * jj + 1]; x[2 * jj] = x1 * cc[jj] - x2 * sn[jj]; x[2 * jj + 1] = x1 * sn[jj] + x2 * cc[jj]; } }
;                 const float sc = isq ? QSCALE : 1.f;
;                 u32x4 w; w.x = pk2(x[0] * sc, x[1] * sc); w.y = pk2(x[2] * sc, x[3] * sc); w.z = pk2(x[4] * sc, x[5] * sc); w.w = pk2(x[6] * sc, x[7] * sc);
;                 if (isq) *(u32x4*)(q + (size_t)row * 512 + cs) = w; else *(u32x4*)(k + (size_t)row * 128 + cs) = w;
.LBB0_448:
	v_pk_mul_f32 v[136:137], v[196:197], v[136:137] op_sel_hi:[0,1]
	v_pk_mul_f32 v[138:139], v[196:197], v[138:139] op_sel_hi:[0,1]
	v_cvt_pk_bf16_f32 v136, v136, v137
	v_cvt_pk_bf16_f32 v137, v138, v139
	v_pk_mul_f32 v[138:139], v[196:197], v[150:151] op_sel_hi:[0,1]
	v_pk_mul_f32 v[150:151], v[196:197], v[152:153] op_sel_hi:[0,1]
	v_cvt_pk_bf16_f32 v138, v138, v139
	v_cvt_pk_bf16_f32 v139, v150, v151
	s_and_b64 vcc, exec, s[12:13]
	s_mov_b64 s[12:13], -1
	s_cbranch_vccnz .LBB0_450
	v_lshlrev_b64 v[150:151], 8, v[216:217]
	v_lshl_add_u64 v[150:151], s[22:23], 0, v[150:151]
	v_lshl_add_u64 v[150:151], v[208:209], 1, v[150:151]
	s_mov_b64 s[12:13], 0
	global_store_dwordx4 v[150:151], v[136:139], off nt
.LBB0_450:
	s_andn2_b64 vcc, exec, s[12:13]
	s_cbranch_vccnz .LBB0_452
	v_lshl_add_u64 v[150:151], s[20:21], 0, v[144:145]
	v_lshl_add_u64 v[150:151], v[208:209], 1, v[150:151]
	global_store_dwordx4 v[150:151], v[136:139], off nt

;     __device__ __forceinline__ void operator()(const f32x4 (&acc)[2][2][4][2], const Unit& un, int wr, int wc, int fr, int fq) const {
;     ...
;             const f32x4 v0 = acc[ai][bj][m][0] * rr[ai][m] + s0[bj], v1 = acc[ai][bj][m][1] * rr[ai][m] + s1[bj];
;             if (pn < 4) {
;                 u32x4 w; w.x = pk2(gelu_tanh(v0.x), gelu_tanh(v0.y)); w.y = pk2(gelu_tanh(v0.z), gelu_tanh(v0.w)); w.z = pk2(gelu_tanh(v1.x), gelu_tanh(v1.y)); w.w = pk2(gelu_tanh(v1.z), gelu_tanh(v1.w));
;                 *(u32x4*)(ga + (size_t)row * 1024 + pn * 256 + ct) = w;
;             } else if (pn < 8) {
;                 u32x2 w; w.x = pk2(v0.x * sigmoidf_(v0.y), v0.z * sigmoidf_(v0.w)); w.y = pk2(v1.x * sigmoidf_(v1.y), v1.z * sigmoidf_(v1.w));
;                 *(u32x2*)(yb + (size_t)row * 512 + (((pn - 4) * 256 + ct) >> 1)) = w;
;             } else if (pn < 10 || (pn == 10 && bj == 0)) {
;                 const bool isq = pn < 10; const int cs = isq ? (pn - 8) * 256 + ct : ct;
;                 float x[8] = {v0.x, v0.y, v0.z, v0.w, v1.x, v1.y, v1.z, v1.w};
;                 if (lat) { const f32x4 ra = rp[m][0], rb = rp[m][1]; const float cc[4] = {ra.x, ra.z, rb.x, rb.z}, sn[4] = {ra.y, ra.w, rb.y, rb.w};
; #pragma unroll
;                     for (int jj = 0; jj < 4; ++jj) { const float x1 = x[2 * jj], x2 = x[2 * jj + 1]; x[2 * jj] = x1 * cc[jj] - x2 * sn[jj]; x[2 * jj + 1] = x1 * sn[jj] + x2 * cc[jj]; } }
;                 const float sc = isq ? QSCALE : 1.f;
;                 u32x4 w; w.x = pk2(x[0] * sc, x[1] * sc); w.y = pk2(x[2] * sc, x[3] * sc); w.z = pk2(x[4] * sc, x[5] * sc); w.w = pk2(x[6] * sc, x[7] * sc);
;                 if (isq) *(u32x4*)(q + (size_t)row * 512 + cs) = w; else *(u32x4*)(k + (size_t)row * 128 + cs) = w;
;             } else if (pn == 10) {
;                 const int dc = ct - 128; const float x[8] = {v0.x, v0.y, v0.z, v0.w, v1.x, v1.y, v1.z, v1.w};
;                 if (lat) { const int b = row >> 13, t = row & (SEQ - 1);
; #pragma unroll
;                     for (int e = 0; e < 8; ++e) vT[((size_t)(b * 128 + dc + e)) * SEQ + t] = (bf16)f2bf(x[e]); }
;                 else { const int rc = row - NLAT, b = rc >> 8, t = rc & 255;
; #pragma unroll
;                     for (int e = 0; e < 8; ++e) vcT[((size_t)(b * 128 + dc + e)) * CTXL + t] = (bf16)f2bf(x[e]); }
;             } else {
.LBB0_456:
	v_lshlrev_b64 v[136:137], 11, v[216:217]
	v_lshl_add_u64 v[136:137], s[16:17], 0, v[136:137]
	s_andn2_b64 vcc, exec, s[12:13]
	v_lshl_add_u64 v[136:137], s[50:51], 1, v[136:137]
	s_cbranch_vccnz .LBB0_458
	v_mul_f32_e32 v138, 0x3d372713, v148
	v_mul_f32_e32 v139, 0x3d372713, v149
	v_mul_f32_e32 v138, v148, v138
	v_mul_f32_e32 v139, v149, v139
	v_mov_b32_e32 v150, v149
	v_fma_f32 v138, v148, v138, v148
	v_fmac_f32_e32 v150, v150, v139
	v_mul_f32_e32 v138, 0x3f4c422a, v138
	v_mul_f32_e32 v139, 0x3f4c422a, v150
	v_add_f32_e32 v138, v138, v138
	v_add_f32_e32 v139, v139, v139
	v_mul_f32_e32 v138, 0xbfb8aa3b, v138
	v_mul_f32_e32 v139, 0xbfb8aa3b, v139
	v_exp_f32_e32 v138, v138
	v_exp_f32_e32 v139, v139
	v_mov_b32_e32 v169, v209
	v_add_f32_e32 v138, 1.0, v138
	v_add_f32_e32 v139, 1.0, v139
	v_rcp_f32_e32 v138, v138
	v_rcp_f32_e32 v139, v139
	s_nop 0
	v_pk_mul_f32 v[138:139], v[148:149], v[138:139]
	s_nop 0
	v_cvt_pk_bf16_f32 v148, v138, v139
	v_mul_f32_e32 v138, 0x3d372713, v146
	v_mul_f32_e32 v139, 0x3d372713, v147
	v_mul_f32_e32 v138, v146, v138
	v_mul_f32_e32 v139, v147, v139
	v_fma_f32 v138, v146, v138, v146
	v_fma_f32 v139, v147, v139, v147
	v_mul_f32_e32 v138, 0x3f4c422a, v138
	v_mul_f32_e32 v139, 0x3f4c422a, v139
	v_add_f32_e32 v138, v138, v138
	v_add_f32_e32 v139, v139, v139
	v_mul_f32_e32 v138, 0xbfb8aa3b, v138
	v_mul_f32_e32 v139, 0xbfb8aa3b, v139
	v_exp_f32_e32 v138, v138
	v_exp_f32_e32 v139, v139
	v_add_f32_e32 v138, 1.0, v138
	v_add_f32_e32 v139, 1.0, v139
	v_rcp_f32_e32 v138, v138
	v_rcp_f32_e32 v139, v139
	s_nop 0
	v_pk_mul_f32 v[138:139], v[146:147], v[138:139]
	s_nop 0
	v_cvt_pk_bf16_f32 v149, v138, v139
	v_mul_f32_e32 v138, 0x3d372713, v142
	v_mul_f32_e32 v139, 0x3d372713, v143
	v_mul_f32_e32 v138, v142, v138
	v_mul_f32_e32 v139, v143, v139
	v_mov_b32_e32 v146, v143
	v_fma_f32 v138, v142, v138, v142
	v_fmac_f32_e32 v146, v146, v139
	v_mul_f32_e32 v138, 0x3f4c422a, v138
	v_mul_f32_e32 v139, 0x3f4c422a, v146
	v_add_f32_e32 v138, v138, v138
	v_add_f32_e32 v139, v139, v139
	v_mul_f32_e32 v138, 0xbfb8aa3b, v138
	v_mul_f32_e32 v139, 0xbfb8aa3b, v139
	v_exp_f32_e32 v138, v138
	v_exp_f32_e32 v139, v139
	v_add_f32_e32 v138, 1.0, v138
	v_add_f32_e32 v139, 1.0, v139
	v_rcp_f32_e32 v138, v138
	v_rcp_f32_e32 v139, v139
	s_nop 0
	v_pk_mul_f32 v[138:139], v[142:143], v[138:139]
	s_nop 0
	v_cvt_pk_bf16_f32 v150, v138, v139
	v_mul_f32_e32 v138, 0x3d372713, v140
	v_mul_f32_e32 v139, 0x3d372713, v141
	v_mul_f32_e32 v138, v140, v138
	v_mul_f32_e32 v139, v141, v139
	v_fma_f32 v138, v140, v138, v140
	v_fma_f32 v139, v141, v139, v141
	v_mul_f32_e32 v138, 0x3f4c422a, v138
	v_mul_f32_e32 v139, 0x3f4c422a, v139
	v_add_f32_e32 v138, v138, v138
	v_add_f32_e32 v139, v139, v139
	v_mul_f32_e32 v138, 0xbfb8aa3b, v138
	v_mul_f32_e32 v139, 0xbfb8aa3b, v139
	v_exp_f32_e32 v138, v138
	v_exp_f32_e32 v139, v139
	v_add_f32_e32 v138, 1.0, v138
	v_add_f32_e32 v139, 1.0, v139
	v_rcp_f32_e32 v138, v138
	v_rcp_f32_e32 v139, v139
	s_nop 0
	v_pk_mul_f32 v[138:139], v[140:141], v[138:139]
	s_nop 0
	v_cvt_pk_bf16_f32 v151, v138, v139
	v_lshl_add_u64 v[138:139], v[136:137], 0, v[168:169]
	global_store_dwordx4 v[138:139], v[148:151], off nt
.LBB0_458:
	v_mov_b32_e32 v219, v218
	v_mov_b32_e32 v138, v218
	v_mov_b32_e32 v139, v218
	v_pk_fma_f32 v[134:135], v[134:135], v[138:139], v[30:31]
	v_pk_fma_f32 v[132:133], v[132:133], v[218:219], v[28:29]
	v_pk_fma_f32 v[130:131], v[130:131], v[138:139], v[26:27]
	v_pk_fma_f32 v[128:129], v[128:129], v[218:219], v[24:25]
	s_and_b64 vcc, exec, s[10:11]
	s_mov_b64 s[12:13], -1
	s_cbranch_vccnz .LBB0_478
	s_and_b64 vcc, exec, s[8:9]
	s_cbranch_vccnz .LBB0_475
	s_andn2_b64 vcc, exec, s[48:49]
	s_cbranch_vccnz .LBB0_469
	s_andn2_b64 vcc, exec, s[46:47]
	s_cbranch_vccnz .LBB0_463
	v_or_b32_e32 v142, s75, v239
	v_lshrrev_b32_e32 v142, 4, v142
	s_mov_b32 s12, 0x8400
	v_mad_u64_u32 v[142:143], s[12:13], v142, s12, v[216:217]
	v_lshlrev_b64 v[142:143], 5, v[142:143]
	v_cvt_pk_bf16_f32 v138, v132, v133
	v_cvt_pk_bf16_f32 v139, v134, v135
	v_cvt_pk_bf16_f32 v140, v128, v129
	v_cvt_pk_bf16_f32 v141, v130, v131
	v_lshl_add_u64 v[142:143], v[186:187], 0, v[142:143]
	s_mov_b64 s[12:13], 0
	global_store_dwordx4 v[142:143], v[138:141], off nt

; __device__ __forceinline__ unsigned pk2(float lo, float hi) { const f32x2 v = {lo, hi}; return __builtin_bit_cast(unsigned, __builtin_convertvector(v, bf16x2_t)); }
;     __device__ __forceinline__ void operator()(const f32x4 (&acc)[2][2][4][2], const Unit& un, int wr, int wc, int fr, int fq) const {
;     ...
;                 const float sc = isq ? QSCALE : 1.f;
;                 u32x4 w; w.x = pk2(x[0] * sc, x[1] * sc); w.y = pk2(x[2] * sc, x[3] * sc); w.z = pk2(x[4] * sc, x[5] * sc); w.w = pk2(x[6] * sc, x[7] * sc);
;                 if (isq) *(u32x4*)(q + (size_t)row * 512 + cs) = w; else *(u32x4*)(k + (size_t)row * 128 + cs) = w;
.LBB0_473:
	s_mov_b32 s12, 0x3e38aa3b
	v_pk_mul_f32 v[138:139], v[138:139], s[12:13] op_sel_hi:[1,0]
	v_pk_mul_f32 v[140:141], v[140:141], s[12:13] op_sel_hi:[1,0]
	v_cvt_pk_bf16_f32 v138, v138, v139
	v_cvt_pk_bf16_f32 v139, v140, v141
	v_pk_mul_f32 v[140:141], v[142:143], s[12:13] op_sel_hi:[1,0]
	v_pk_mul_f32 v[142:143], v[146:147], s[12:13] op_sel_hi:[1,0]
	v_cvt_pk_bf16_f32 v140, v140, v141
	v_cvt_pk_bf16_f32 v141, v142, v143
	v_lshl_add_u64 v[142:143], s[20:21], 0, v[144:145]
	v_add_u32_e32 v208, s37, v184
	v_lshl_add_u64 v[142:143], v[208:209], 1, v[142:143]
	global_store_dwordx4 v[142:143], v[138:141], off offset:256 nt

;     __device__ __forceinline__ void operator()(const f32x4 (&acc)[2][2][4][2], const Unit& un, int wr, int wc, int fr, int fq) const {
;     ...
;             const f32x4 v0 = acc[ai][bj][m][0] * rr[ai][m] + s0[bj], v1 = acc[ai][bj][m][1] * rr[ai][m] + s1[bj];
;             if (pn < 4) {
;                 u32x4 w; w.x = pk2(gelu_tanh(v0.x), gelu_tanh(v0.y)); w.y = pk2(gelu_tanh(v0.z), gelu_tanh(v0.w)); w.z = pk2(gelu_tanh(v1.x), gelu_tanh(v1.y)); w.w = pk2(gelu_tanh(v1.z), gelu_tanh(v1.w));
;                 *(u32x4*)(ga + (size_t)row * 1024 + pn * 256 + ct) = w;
;             } else if (pn < 8) {
;                 u32x2 w; w.x = pk2(v0.x * sigmoidf_(v0.y), v0.z * sigmoidf_(v0.w)); w.y = pk2(v1.x * sigmoidf_(v1.y), v1.z * sigmoidf_(v1.w));
;                 *(u32x2*)(yb + (size_t)row * 512 + (((pn - 4) * 256 + ct) >> 1)) = w;
;             } else if (pn < 10 || (pn == 10 && bj == 0)) {
;                 const bool isq = pn < 10; const int cs = isq ? (pn - 8) * 256 + ct : ct;
;                 float x[8] = {v0.x, v0.y, v0.z, v0.w, v1.x, v1.y, v1.z, v1.w};
;                 if (lat) { const f32x4 ra = rp[m][0], rb = rp[m][1]; const float cc[4] = {ra.x, ra.z, rb.x, rb.z}, sn[4] = {ra.y, ra.w, rb.y, rb.w};
; #pragma unroll
;                     for (int jj = 0; jj < 4; ++jj) { const float x1 = x[2 * jj], x2 = x[2 * jj + 1]; x[2 * jj] = x1 * cc[jj] - x2 * sn[jj]; x[2 * jj + 1] = x1 * sn[jj] + x2 * cc[jj]; } }
;                 const float sc = isq ? QSCALE : 1.f;
;                 u32x4 w; w.x = pk2(x[0] * sc, x[1] * sc); w.y = pk2(x[2] * sc, x[3] * sc); w.z = pk2(x[4] * sc, x[5] * sc); w.w = pk2(x[6] * sc, x[7] * sc);
;                 if (isq) *(u32x4*)(q + (size_t)row * 512 + cs) = w; else *(u32x4*)(k + (size_t)row * 128 + cs) = w;
;             } else if (pn == 10) {
;                 const int dc = ct - 128; const float x[8] = {v0.x, v0.y, v0.z, v0.w, v1.x, v1.y, v1.z, v1.w};
;                 if (lat) { const int b = row >> 13, t = row & (SEQ - 1);
; #pragma unroll
;                     for (int e = 0; e < 8; ++e) vT[((size_t)(b * 128 + dc + e)) * SEQ + t] = (bf16)f2bf(x[e]); }
;                 else { const int rc = row - NLAT, b = rc >> 8, t = rc & 255;
; #pragma unroll
;                     for (int e = 0; e < 8; ++e) vcT[((size_t)(b * 128 + dc + e)) * CTXL + t] = (bf16)f2bf(x[e]); }
;             } else {
.LBB0_478:
	s_andn2_b64 vcc, exec, s[12:13]
	s_cbranch_vccnz .LBB0_480
	v_mul_f32_e32 v138, 0x3d372713, v132
	v_mul_f32_e32 v139, 0x3d372713, v133
	v_mul_f32_e32 v138, v132, v138
	v_mul_f32_e32 v139, v133, v139
	v_mov_b32_e32 v140, v133
	v_fma_f32 v138, v132, v138, v132
	v_fmac_f32_e32 v140, v140, v139
	v_mul_f32_e32 v138, 0x3f4c422a, v138
	v_mul_f32_e32 v139, 0x3f4c422a, v140
	v_add_f32_e32 v138, v138, v138
	v_add_f32_e32 v139, v139, v139
	v_mul_f32_e32 v138, 0xbfb8aa3b, v138
	v_mul_f32_e32 v139, 0xbfb8aa3b, v139
	v_exp_f32_e32 v138, v138
	v_exp_f32_e32 v139, v139
	v_mov_b32_e32 v169, v209
	v_add_f32_e32 v138, 1.0, v138
	v_add_f32_e32 v139, 1.0, v139
	v_rcp_f32_e32 v138, v138
	v_rcp_f32_e32 v139, v139
	s_nop 0
	v_pk_mul_f32 v[132:133], v[132:133], v[138:139]
	s_nop 0
	v_cvt_pk_bf16_f32 v132, v132, v133
	v_mul_f32_e32 v133, 0x3d372713, v134
	v_mul_f32_e32 v133, v134, v133
	v_fma_f32 v133, v134, v133, v134
	v_mul_f32_e32 v133, 0x3f4c422a, v133
	v_add_f32_e32 v133, v133, v133
	v_mul_f32_e32 v133, 0xbfb8aa3b, v133
	v_exp_f32_e32 v133, v133
	s_nop 0
	v_add_f32_e32 v133, 1.0, v133
	v_rcp_f32_e32 v138, v133
	v_mul_f32_e32 v133, 0x3d372713, v135
	v_mul_f32_e32 v133, v135, v133
	v_fma_f32 v133, v135, v133, v135
	v_mul_f32_e32 v133, 0x3f4c422a, v133
	v_add_f32_e32 v133, v133, v133
	v_mul_f32_e32 v133, 0xbfb8aa3b, v133
	v_exp_f32_e32 v133, v133
	s_nop 0
	v_add_f32_e32 v133, 1.0, v133
	v_rcp_f32_e32 v139, v133
	s_nop 0
	v_pk_mul_f32 v[134:135], v[134:135], v[138:139]
	s_nop 0
	v_cvt_pk_bf16_f32 v133, v134, v135
	v_mul_f32_e32 v134, 0x3d372713, v128
	v_mul_f32_e32 v135, 0x3d372713, v129
	v_mul_f32_e32 v134, v128, v134
	v_mul_f32_e32 v135, v129, v135
	v_mov_b32_e32 v138, v129
	v_fma_f32 v134, v128, v134, v128
	v_fmac_f32_e32 v138, v138, v135
	v_mul_f32_e32 v134, 0x3f4c422a, v134
	v_mul_f32_e32 v135, 0x3f4c422a, v138
	v_add_f32_e32 v134, v134, v134
	v_add_f32_e32 v135, v135, v135
	v_mul_f32_e32 v134, 0xbfb8aa3b, v134
	v_mul_f32_e32 v135, 0xbfb8aa3b, v135
	v_exp_f32_e32 v134, v134
	v_exp_f32_e32 v135, v135
	v_add_f32_e32 v134, 1.0, v134
	v_add_f32_e32 v135, 1.0, v135
	v_rcp_f32_e32 v134, v134
	v_rcp_f32_e32 v135, v135
	s_nop 0
	v_pk_mul_f32 v[128:129], v[128:129], v[134:135]
	s_nop 0
	v_cvt_pk_bf16_f32 v134, v128, v129
	v_mul_f32_e32 v128, 0x3d372713, v130
	v_mul_f32_e32 v129, 0x3d372713, v131
	v_mul_f32_e32 v128, v130, v128
	v_mul_f32_e32 v129, v131, v129
	v_fma_f32 v128, v130, v128, v130
	v_fma_f32 v129, v131, v129, v131
	v_mul_f32_e32 v128, 0x3f4c422a, v128
	v_mul_f32_e32 v129, 0x3f4c422a, v129
	v_add_f32_e32 v128, v128, v128
	v_add_f32_e32 v129, v129, v129
	v_mul_f32_e32 v128, 0xbfb8aa3b, v128
	v_mul_f32_e32 v129, 0xbfb8aa3b, v129
	v_exp_f32_e32 v128, v128
	v_exp_f32_e32 v129, v129
	v_add_f32_e32 v128, 1.0, v128
	v_add_f32_e32 v129, 1.0, v129
	v_rcp_f32_e32 v128, v128
	v_rcp_f32_e32 v129, v129
	s_nop 0
	v_pk_mul_f32 v[128:129], v[130:131], v[128:129]
	s_nop 0
	v_cvt_pk_bf16_f32 v135, v128, v129
	v_lshl_add_u64 v[128:129], v[136:137], 0, v[168:169]
	global_store_dwordx4 v[128:129], v[132:135], off offset:256 nt
.LBB0_480:
	v_lshlrev_b64 v[128:129], 10, v[206:207]
	v_pk_fma_f32 v[130:131], v[126:127], v[214:215], v[46:47] op_sel_hi:[1,0,1]
	v_pk_fma_f32 v[132:133], v[124:125], v[214:215], v[44:45] op_sel_hi:[1,0,1]
	v_pk_fma_f32 v[124:125], v[122:123], v[214:215], v[42:43] op_sel_hi:[1,0,1]
	v_pk_fma_f32 v[126:127], v[120:121], v[214:215], v[40:41] op_sel_hi:[1,0,1]
	s_and_b64 vcc, exec, s[10:11]
	s_mov_b64 s[12:13], -1
	s_cbranch_vccnz .LBB0_500
	s_and_b64 vcc, exec, s[8:9]
	s_cbranch_vccnz .LBB0_497
	v_cndmask_b32_e64 v120, 0, 1, s[48:49]
	v_cmp_ne_u32_e64 s[12:13], 1, v120
	s_andn2_b64 vcc, exec, s[48:49]
	s_cbranch_vccnz .LBB0_486
	s_mov_b64 s[52:53], -1
	s_and_b64 vcc, exec, s[46:47]
	s_cbranch_vccz .LBB0_485
	v_or_b32_e32 v134, s75, v184
	v_lshrrev_b32_e32 v134, 4, v134
	s_mov_b32 s52, 0x8400
	v_mad_u64_u32 v[134:135], s[52:53], v134, s52, v[206:207]
	v_lshlrev_b64 v[134:135], 5, v[134:135]
	v_cvt_pk_bf16_f32 v120, v132, v133
	v_cvt_pk_bf16_f32 v121, v130, v131
	v_cvt_pk_bf16_f32 v122, v126, v127
	v_cvt_pk_bf16_f32 v123, v124, v125
	v_lshl_add_u64 v[134:135], v[186:187], 0, v[134:135]
	s_mov_b64 s[52:53], 0
	global_store_dwordx4 v[134:135], v[120:123], off nt

; __device__ __forceinline__ unsigned pk2(float lo, float hi) { const f32x2 v = {lo, hi}; return __builtin_bit_cast(unsigned, __builtin_convertvector(v, bf16x2_t)); }
;     __device__ __forceinline__ void operator()(const f32x4 (&acc)[2][2][4][2], const Unit& un, int wr, int wc, int fr, int fq) const {
;     ...
;                 const bool isq = pn < 10; const int cs = isq ? (pn - 8) * 256 + ct : ct;
;                 float x[8] = {v0.x, v0.y, v0.z, v0.w, v1.x, v1.y, v1.z, v1.w};
;                 if (lat) { const f32x4 ra = rp[m][0], rb = rp[m][1]; const float cc[4] = {ra.x, ra.z, rb.x, rb.z}, sn[4] = {ra.y, ra.w, rb.y, rb.w};
; #pragma unroll
;                     for (int jj = 0; jj < 4; ++jj) { const float x1 = x[2 * jj], x2 = x[2 * jj + 1]; x[2 * jj] = x1 * cc[jj] - x2 * sn[jj]; x[2 * jj + 1] = x1 * sn[jj] + x2 * cc[jj]; } }
;                 const float sc = isq ? QSCALE : 1.f;
;                 u32x4 w; w.x = pk2(x[0] * sc, x[1] * sc); w.y = pk2(x[2] * sc, x[3] * sc); w.z = pk2(x[4] * sc, x[5] * sc); w.w = pk2(x[6] * sc, x[7] * sc);
;                 if (isq) *(u32x4*)(q + (size_t)row * 512 + cs) = w; else *(u32x4*)(k + (size_t)row * 128 + cs) = w;
.LBB0_492:
	v_pk_mul_f32 v[120:121], v[196:197], v[120:121] op_sel_hi:[0,1]
	v_pk_mul_f32 v[122:123], v[196:197], v[122:123] op_sel_hi:[0,1]
	v_cvt_pk_bf16_f32 v120, v120, v121
	v_cvt_pk_bf16_f32 v121, v122, v123
	v_pk_mul_f32 v[122:123], v[196:197], v[134:135] op_sel_hi:[0,1]
	v_pk_mul_f32 v[134:135], v[196:197], v[136:137] op_sel_hi:[0,1]
	v_cvt_pk_bf16_f32 v122, v122, v123
	v_cvt_pk_bf16_f32 v123, v134, v135
	s_and_b64 vcc, exec, s[12:13]
	s_mov_b64 s[12:13], -1
	s_cbranch_vccnz .LBB0_494
	v_lshlrev_b64 v[134:135], 8, v[206:207]
	v_lshl_add_u64 v[134:135], s[22:23], 0, v[134:135]
	v_lshl_add_u64 v[134:135], v[208:209], 1, v[134:135]
	s_mov_b64 s[12:13], 0
	global_store_dwordx4 v[134:135], v[120:123], off nt
.LBB0_494:
	s_andn2_b64 vcc, exec, s[12:13]
	s_cbranch_vccnz .LBB0_496
	v_lshl_add_u64 v[134:135], s[20:21], 0, v[128:129]
	v_lshl_add_u64 v[134:135], v[208:209], 1, v[134:135]
	global_store_dwordx4 v[134:135], v[120:123], off nt

;     __device__ __forceinline__ void operator()(const f32x4 (&acc)[2][2][4][2], const Unit& un, int wr, int wc, int fr, int fq) const {
;     ...
;             const f32x4 v0 = acc[ai][bj][m][0] * rr[ai][m] + s0[bj], v1 = acc[ai][bj][m][1] * rr[ai][m] + s1[bj];
;             if (pn < 4) {
;                 u32x4 w; w.x = pk2(gelu_tanh(v0.x), gelu_tanh(v0.y)); w.y = pk2(gelu_tanh(v0.z), gelu_tanh(v0.w)); w.z = pk2(gelu_tanh(v1.x), gelu_tanh(v1.y)); w.w = pk2(gelu_tanh(v1.z), gelu_tanh(v1.w));
;                 *(u32x4*)(ga + (size_t)row * 1024 + pn * 256 + ct) = w;
;             } else if (pn < 8) {
;                 u32x2 w; w.x = pk2(v0.x * sigmoidf_(v0.y), v0.z * sigmoidf_(v0.w)); w.y = pk2(v1.x * sigmoidf_(v1.y), v1.z * sigmoidf_(v1.w));
;                 *(u32x2*)(yb + (size_t)row * 512 + (((pn - 4) * 256 + ct) >> 1)) = w;
;             } else if (pn < 10 || (pn == 10 && bj == 0)) {
;                 const bool isq = pn < 10; const int cs = isq ? (pn - 8) * 256 + ct : ct;
;                 float x[8] = {v0.x, v0.y, v0.z, v0.w, v1.x, v1.y, v1.z, v1.w};
;                 if (lat) { const f32x4 ra = rp[m][0], rb = rp[m][1]; const float cc[4] = {ra.x, ra.z, rb.x, rb.z}, sn[4] = {ra.y, ra.w, rb.y, rb.w};
; #pragma unroll
;                     for (int jj = 0; jj < 4; ++jj) { const float x1 = x[2 * jj], x2 = x[2 * jj + 1]; x[2 * jj] = x1 * cc[jj] - x2 * sn[jj]; x[2 * jj + 1] = x1 * sn[jj] + x2 * cc[jj]; } }
;                 const float sc = isq ? QSCALE : 1.f;
;                 u32x4 w; w.x = pk2(x[0] * sc, x[1] * sc); w.y = pk2(x[2] * sc, x[3] * sc); w.z = pk2(x[4] * sc, x[5] * sc); w.w = pk2(x[6] * sc, x[7] * sc);
;                 if (isq) *(u32x4*)(q + (size_t)row * 512 + cs) = w; else *(u32x4*)(k + (size_t)row * 128 + cs) = w;
;             } else if (pn == 10) {
;                 const int dc = ct - 128; const float x[8] = {v0.x, v0.y, v0.z, v0.w, v1.x, v1.y, v1.z, v1.w};
;                 if (lat) { const int b = row >> 13, t = row & (SEQ - 1);
; #pragma unroll
;                     for (int e = 0; e < 8; ++e) vT[((size_t)(b * 128 + dc + e)) * SEQ + t] = (bf16)f2bf(x[e]); }
;                 else { const int rc = row - NLAT, b = rc >> 8, t = rc & 255;
; #pragma unroll
;                     for (int e = 0; e < 8; ++e) vcT[((size_t)(b * 128 + dc + e)) * CTXL + t] = (bf16)f2bf(x[e]); }
;             } else {
.LBB0_500:
	v_lshlrev_b64 v[120:121], 11, v[206:207]
	v_lshl_add_u64 v[120:121], s[16:17], 0, v[120:121]
	s_andn2_b64 vcc, exec, s[12:13]
	v_lshl_add_u64 v[120:121], s[50:51], 1, v[120:121]
	s_cbranch_vccnz .LBB0_502
	v_mul_f32_e32 v122, 0x3d372713, v132
	v_mul_f32_e32 v123, 0x3d372713, v133
	v_mul_f32_e32 v122, v132, v122
	v_mul_f32_e32 v123, v133, v123
	v_mov_b32_e32 v134, v133
	v_fma_f32 v122, v132, v122, v132
	v_fmac_f32_e32 v134, v134, v123
	v_mul_f32_e32 v122, 0x3f4c422a, v122
	v_mul_f32_e32 v123, 0x3f4c422a, v134
	v_add_f32_e32 v122, v122, v122
	v_add_f32_e32 v123, v123, v123
	v_mul_f32_e32 v122, 0xbfb8aa3b, v122
	v_mul_f32_e32 v123, 0xbfb8aa3b, v123
	v_exp_f32_e32 v122, v122
	v_exp_f32_e32 v123, v123
	v_mov_b32_e32 v169, v209
	v_add_f32_e32 v122, 1.0, v122
	v_add_f32_e32 v123, 1.0, v123
	v_rcp_f32_e32 v122, v122
	v_rcp_f32_e32 v123, v123
	s_nop 0
	v_pk_mul_f32 v[122:123], v[132:133], v[122:123]
	s_nop 0
	v_cvt_pk_bf16_f32 v132, v122, v123
	v_mul_f32_e32 v122, 0x3d372713, v130
	v_mul_f32_e32 v123, 0x3d372713, v131
	v_mul_f32_e32 v122, v130, v122
	v_mul_f32_e32 v123, v131, v123
	v_fma_f32 v122, v130, v122, v130
	v_fma_f32 v123, v131, v123, v131
	v_mul_f32_e32 v122, 0x3f4c422a, v122
	v_mul_f32_e32 v123, 0x3f4c422a, v123
	v_add_f32_e32 v122, v122, v122
	v_add_f32_e32 v123, v123, v123
	v_mul_f32_e32 v122, 0xbfb8aa3b, v122
	v_mul_f32_e32 v123, 0xbfb8aa3b, v123
	v_exp_f32_e32 v122, v122
	v_exp_f32_e32 v123, v123
	v_add_f32_e32 v122, 1.0, v122
	v_add_f32_e32 v123, 1.0, v123
	v_rcp_f32_e32 v122, v122
	v_rcp_f32_e32 v123, v123
	s_nop 0
	v_pk_mul_f32 v[122:123], v[130:131], v[122:123]
	s_nop 0
	v_cvt_pk_bf16_f32 v133, v122, v123
	v_mul_f32_e32 v122, 0x3d372713, v126
	v_mul_f32_e32 v123, 0x3d372713, v127
	v_mul_f32_e32 v122, v126, v122
	v_mul_f32_e32 v123, v127, v123
	v_mov_b32_e32 v130, v127
	v_fma_f32 v122, v126, v122, v126
	v_fmac_f32_e32 v130, v130, v123
	v_mul_f32_e32 v122, 0x3f4c422a, v122
	v_mul_f32_e32 v123, 0x3f4c422a, v130
	v_add_f32_e32 v122, v122, v122
	v_add_f32_e32 v123, v123, v123
	v_mul_f32_e32 v122, 0xbfb8aa3b, v122
	v_mul_f32_e32 v123, 0xbfb8aa3b, v123
	v_exp_f32_e32 v122, v122
	v_exp_f32_e32 v123, v123
	v_add_f32_e32 v122, 1.0, v122
	v_add_f32_e32 v123, 1.0, v123
	v_rcp_f32_e32 v122, v122
	v_rcp_f32_e32 v123, v123
	s_nop 0
	v_pk_mul_f32 v[122:123], v[126:127], v[122:123]
	s_nop 0
	v_cvt_pk_bf16_f32 v134, v122, v123
	v_mul_f32_e32 v122, 0x3d372713, v124
	v_mul_f32_e32 v123, 0x3d372713, v125
	v_mul_f32_e32 v122, v124, v122
	v_mul_f32_e32 v123, v125, v123
	v_fma_f32 v122, v124, v122, v124
	v_fma_f32 v123, v125, v123, v125
	v_mul_f32_e32 v122, 0x3f4c422a, v122
	v_mul_f32_e32 v123, 0x3f4c422a, v123
	v_add_f32_e32 v122, v122, v122
	v_add_f32_e32 v123, v123, v123
	v_mul_f32_e32 v122, 0xbfb8aa3b, v122
	v_mul_f32_e32 v123, 0xbfb8aa3b, v123
	v_exp_f32_e32 v122, v122
	v_exp_f32_e32 v123, v123
	v_add_f32_e32 v122, 1.0, v122
	v_add_f32_e32 v123, 1.0, v123
	v_rcp_f32_e32 v122, v122
	v_rcp_f32_e32 v123, v123
	s_nop 0
	v_pk_mul_f32 v[122:123], v[124:125], v[122:123]
	s_nop 0
	v_cvt_pk_bf16_f32 v135, v122, v123
	v_lshl_add_u64 v[122:123], v[120:121], 0, v[168:169]
	global_store_dwordx4 v[122:123], v[132:135], off nt
.LBB0_502:
	v_mov_b32_e32 v215, v214
	v_mov_b32_e32 v122, v214
	v_mov_b32_e32 v123, v214
	v_pk_fma_f32 v[118:119], v[118:119], v[122:123], v[30:31]
	v_pk_fma_f32 v[116:117], v[116:117], v[214:215], v[28:29]
	v_pk_fma_f32 v[114:115], v[114:115], v[122:123], v[26:27]
	v_pk_fma_f32 v[112:113], v[112:113], v[214:215], v[24:25]
	s_and_b64 vcc, exec, s[10:11]
	s_mov_b64 s[12:13], -1
	s_cbranch_vccnz .LBB0_516
	s_and_b64 vcc, exec, s[8:9]
	s_cbranch_vccnz .LBB0_521
	s_andn2_b64 vcc, exec, s[48:49]
	s_cbranch_vccnz .LBB0_513
	s_andn2_b64 vcc, exec, s[46:47]
	s_cbranch_vccnz .LBB0_507
	v_or_b32_e32 v126, s75, v239
	v_lshrrev_b32_e32 v126, 4, v126
	s_mov_b32 s12, 0x8400
	v_mad_u64_u32 v[126:127], s[12:13], v126, s12, v[206:207]
	v_lshlrev_b64 v[126:127], 5, v[126:127]
	v_cvt_pk_bf16_f32 v122, v116, v117
	v_cvt_pk_bf16_f32 v123, v118, v119
	v_cvt_pk_bf16_f32 v124, v112, v113
	v_cvt_pk_bf16_f32 v125, v114, v115
	v_lshl_add_u64 v[126:127], v[186:187], 0, v[126:127]
	s_mov_b64 s[12:13], 0
	global_store_dwordx4 v[126:127], v[122:125], off nt

; __device__ __forceinline__ unsigned pk2(float lo, float hi) { const f32x2 v = {lo, hi}; return __builtin_bit_cast(unsigned, __builtin_convertvector(v, bf16x2_t)); }
; __device__ __forceinline__ float gelu_tanh(float x) { const float y = 0.7978845608028654f * (x + 0.044715f * x * x * x); return x * sigmoidf_(2.f * y); }
;     __device__ __forceinline__ void operator()(const f32x4 (&acc)[2][2][4][2], const Unit& un, int wr, int wc, int fr, int fq) const {
;     ...
;             if (pn < 4) {
;                 u32x4 w; w.x = pk2(gelu_tanh(v0.x), gelu_tanh(v0.y)); w.y = pk2(gelu_tanh(v0.z), gelu_tanh(v0.w)); w.z = pk2(gelu_tanh(v1.x), gelu_tanh(v1.y)); w.w = pk2(gelu_tanh(v1.z), gelu_tanh(v1.w));
;                 *(u32x4*)(ga + (size_t)row * 1024 + pn * 256 + ct) = w;
.LBB0_517:
	v_mul_f32_e32 v122, 0x3d372713, v116
	v_mul_f32_e32 v123, 0x3d372713, v117
	v_mul_f32_e32 v122, v116, v122
	v_mul_f32_e32 v123, v117, v123
	v_mov_b32_e32 v124, v117
	v_fma_f32 v122, v116, v122, v116
	v_fmac_f32_e32 v124, v124, v123
	v_mul_f32_e32 v122, 0x3f4c422a, v122
	v_mul_f32_e32 v123, 0x3f4c422a, v124
	v_add_f32_e32 v122, v122, v122
	v_add_f32_e32 v123, v123, v123
	v_mul_f32_e32 v122, 0xbfb8aa3b, v122
	v_mul_f32_e32 v123, 0xbfb8aa3b, v123
	v_exp_f32_e32 v122, v122
	v_exp_f32_e32 v123, v123
	v_mov_b32_e32 v169, v209
	v_add_f32_e32 v122, 1.0, v122
	v_add_f32_e32 v123, 1.0, v123
	v_rcp_f32_e32 v122, v122
	v_rcp_f32_e32 v123, v123
	s_nop 0
	v_pk_mul_f32 v[116:117], v[116:117], v[122:123]
	s_nop 0
	v_cvt_pk_bf16_f32 v116, v116, v117
	v_mul_f32_e32 v117, 0x3d372713, v118
	v_mul_f32_e32 v117, v118, v117
	v_fma_f32 v117, v118, v117, v118
	v_mul_f32_e32 v117, 0x3f4c422a, v117
	v_add_f32_e32 v117, v117, v117
	v_mul_f32_e32 v117, 0xbfb8aa3b, v117
	v_exp_f32_e32 v117, v117
	s_nop 0
	v_add_f32_e32 v117, 1.0, v117
	v_rcp_f32_e32 v122, v117
	v_mul_f32_e32 v117, 0x3d372713, v119
	v_mul_f32_e32 v117, v119, v117
	v_fma_f32 v117, v119, v117, v119
	v_mul_f32_e32 v117, 0x3f4c422a, v117
	v_add_f32_e32 v117, v117, v117
	v_mul_f32_e32 v117, 0xbfb8aa3b, v117
	v_exp_f32_e32 v117, v117
	s_nop 0
	v_add_f32_e32 v117, 1.0, v117
	v_rcp_f32_e32 v123, v117
	s_nop 0
	v_pk_mul_f32 v[118:119], v[118:119], v[122:123]
	s_nop 0
	v_cvt_pk_bf16_f32 v117, v118, v119
	v_mul_f32_e32 v118, 0x3d372713, v112
	v_mul_f32_e32 v119, 0x3d372713, v113
	v_mul_f32_e32 v118, v112, v118
	v_mul_f32_e32 v119, v113, v119
	v_mov_b32_e32 v122, v113
	v_fma_f32 v118, v112, v118, v112
	v_fmac_f32_e32 v122, v122, v119
	v_mul_f32_e32 v118, 0x3f4c422a, v118
	v_mul_f32_e32 v119, 0x3f4c422a, v122
	v_add_f32_e32 v118, v118, v118
	v_add_f32_e32 v119, v119, v119
	v_mul_f32_e32 v118, 0xbfb8aa3b, v118
	v_mul_f32_e32 v119, 0xbfb8aa3b, v119
	v_exp_f32_e32 v118, v118
	v_exp_f32_e32 v119, v119
	v_add_f32_e32 v118, 1.0, v118
	v_add_f32_e32 v119, 1.0, v119
	v_rcp_f32_e32 v118, v118
	v_rcp_f32_e32 v119, v119
	s_nop 0
	v_pk_mul_f32 v[112:113], v[112:113], v[118:119]
	s_nop 0
	v_cvt_pk_bf16_f32 v118, v112, v113
	v_mul_f32_e32 v112, 0x3d372713, v114
	v_mul_f32_e32 v113, 0x3d372713, v115
	v_mul_f32_e32 v112, v114, v112
	v_mul_f32_e32 v113, v115, v113
	v_fma_f32 v112, v114, v112, v114
	v_fma_f32 v113, v115, v113, v115
	v_mul_f32_e32 v112, 0x3f4c422a, v112
	v_mul_f32_e32 v113, 0x3f4c422a, v113
	v_add_f32_e32 v112, v112, v112
	v_add_f32_e32 v113, v113, v113
	v_mul_f32_e32 v112, 0xbfb8aa3b, v112
	v_mul_f32_e32 v113, 0xbfb8aa3b, v113
	v_exp_f32_e32 v112, v112
	v_exp_f32_e32 v113, v113
	v_add_f32_e32 v112, 1.0, v112
	v_add_f32_e32 v113, 1.0, v113
	v_rcp_f32_e32 v112, v112
	v_rcp_f32_e32 v113, v113
	s_nop 0
	v_pk_mul_f32 v[112:113], v[114:115], v[112:113]
	s_nop 0
	v_cvt_pk_bf16_f32 v119, v112, v113
	v_lshl_add_u64 v[112:113], v[120:121], 0, v[168:169]
	global_store_dwordx4 v[112:113], v[116:119], off offset:256 nt
	s_and_b64 vcc, exec, s[0:1]
	s_movk_i32 s77, 0x7dff
	s_mov_b32 s78, 0x200000
	s_cbranch_vccz .LBB0_525
	s_branch .LBB0_526

; __device__ __forceinline__ unsigned pk2(float lo, float hi) { const f32x2 v = {lo, hi}; return __builtin_bit_cast(unsigned, __builtin_convertvector(v, bf16x2_t)); }
;     __device__ __forceinline__ void operator()(const f32x4 (&acc)[2][2][4][2], const Unit& un, int wr, int wc, int fr, int fq) const {
;     ...
;                 const float sc = isq ? QSCALE : 1.f;
;                 u32x4 w; w.x = pk2(x[0] * sc, x[1] * sc); w.y = pk2(x[2] * sc, x[3] * sc); w.z = pk2(x[4] * sc, x[5] * sc); w.w = pk2(x[6] * sc, x[7] * sc);
;                 if (isq) *(u32x4*)(q + (size_t)row * 512 + cs) = w; else *(u32x4*)(k + (size_t)row * 128 + cs) = w;
.LBB0_519:
	s_mov_b32 s12, 0x3e38aa3b
	v_pk_mul_f32 v[122:123], v[122:123], s[12:13] op_sel_hi:[1,0]
	v_pk_mul_f32 v[124:125], v[124:125], s[12:13] op_sel_hi:[1,0]
	v_cvt_pk_bf16_f32 v122, v122, v123
	v_cvt_pk_bf16_f32 v123, v124, v125
	v_pk_mul_f32 v[124:125], v[126:127], s[12:13] op_sel_hi:[1,0]
	v_pk_mul_f32 v[126:127], v[130:131], s[12:13] op_sel_hi:[1,0]
	v_cvt_pk_bf16_f32 v124, v124, v125
	v_cvt_pk_bf16_f32 v125, v126, v127
	v_lshl_add_u64 v[126:127], s[20:21], 0, v[128:129]
	v_add_u32_e32 v208, s37, v184
	v_lshl_add_u64 v[126:127], v[208:209], 1, v[126:127]
	global_store_dwordx4 v[126:127], v[122:125], off offset:256 nt

; __device__ __forceinline__ unsigned f2bf(float f) { return pk2(f, f) & 0xffffu; }
;     __device__ __forceinline__ void operator()(const f32x4 (&acc)[2][2][4][2], const Unit& un, int wr, int wc, int fr, int fq) const {
;     ...
;             const int row = rbase + ai * 128 + m * 16; const int ct = bj * 128 + cw;
;             const f32x4 v0 = acc[ai][bj][m][0] * rr[ai][m] + s0[bj], v1 = acc[ai][bj][m][1] * rr[ai][m] + s1[bj];
;             if (pn < 4) {
;                 u32x4 w; w.x = pk2(gelu_tanh(v0.x), gelu_tanh(v0.y)); w.y = pk2(gelu_tanh(v0.z), gelu_tanh(v0.w)); w.z = pk2(gelu_tanh(v1.x), gelu_tanh(v1.y)); w.w = pk2(gelu_tanh(v1.z), gelu_tanh(v1.w));
;                 *(u32x4*)(ga + (size_t)row * 1024 + pn * 256 + ct) = w;
;             } else if (pn < 8) {
;                 u32x2 w; w.x = pk2(v0.x * sigmoidf_(v0.y), v0.z * sigmoidf_(v0.w)); w.y = pk2(v1.x * sigmoidf_(v1.y), v1.z * sigmoidf_(v1.w));
;                 *(u32x2*)(yb + (size_t)row * 512 + (((pn - 4) * 256 + ct) >> 1)) = w;
;             } else if (pn < 10 || (pn == 10 && bj == 0)) {
;                 const bool isq = pn < 10; const int cs = isq ? (pn - 8) * 256 + ct : ct;
;                 float x[8] = {v0.x, v0.y, v0.z, v0.w, v1.x, v1.y, v1.z, v1.w};
;                 if (lat) { const f32x4 ra = rp[m][0], rb = rp[m][1]; const float cc[4] = {ra.x, ra.z, rb.x, rb.z}, sn[4] = {ra.y, ra.w, rb.y, rb.w};
; #pragma unroll
;                     for (int jj = 0; jj < 4; ++jj) { const float x1 = x[2 * jj], x2 = x[2 * jj + 1]; x[2 * jj] = x1 * cc[jj] - x2 * sn[jj]; x[2 * jj + 1] = x1 * sn[jj] + x2 * cc[jj]; } }
;                 const float sc = isq ? QSCALE : 1.f;
;                 u32x4 w; w.x = pk2(x[0] * sc, x[1] * sc); w.y = pk2(x[2] * sc, x[3] * sc); w.z = pk2(x[4] * sc, x[5] * sc); w.w = pk2(x[6] * sc, x[7] * sc);
;                 if (isq) *(u32x4*)(q + (size_t)row * 512 + cs) = w; else *(u32x4*)(k + (size_t)row * 128 + cs) = w;
;             } else if (pn == 10) {
;                 const int dc = ct - 128; const float x[8] = {v0.x, v0.y, v0.z, v0.w, v1.x, v1.y, v1.z, v1.w};
;                 if (lat) { const int b = row >> 13, t = row & (SEQ - 1);
; #pragma unroll
;                     for (int e = 0; e < 8; ++e) vT[((size_t)(b * 128 + dc + e)) * SEQ + t] = (bf16)f2bf(x[e]); }
;                 else { const int rc = row - NLAT, b = rc >> 8, t = rc & 255;
; #pragma unroll
.LBB0_526:
	v_add_u32_e32 v114, 0x80, v198
	v_ashrrev_i32_e32 v115, 31, v114
	v_lshlrev_b64 v[112:113], 10, v[114:115]
	v_pk_fma_f32 v[116:117], v[102:103], v[204:205], v[46:47] op_sel_hi:[1,0,1]
	v_pk_fma_f32 v[118:119], v[100:101], v[204:205], v[44:45] op_sel_hi:[1,0,1]
	v_pk_fma_f32 v[100:101], v[98:99], v[204:205], v[42:43] op_sel_hi:[1,0,1]
	v_pk_fma_f32 v[102:103], v[96:97], v[204:205], v[40:41] op_sel_hi:[1,0,1]
	s_and_b64 vcc, exec, s[10:11]
	s_mov_b64 s[0:1], -1
	s_cbranch_vccnz .LBB0_546
	s_and_b64 vcc, exec, s[8:9]
	s_cbranch_vccnz .LBB0_543
	v_cndmask_b32_e64 v96, 0, 1, s[48:49]
	v_cmp_ne_u32_e64 s[0:1], 1, v96
	s_andn2_b64 vcc, exec, s[48:49]
	s_cbranch_vccnz .LBB0_532
	s_mov_b64 s[12:13], -1
	s_and_b64 vcc, exec, s[46:47]
	s_cbranch_vccz .LBB0_531
	v_or_b32_e32 v120, s75, v184
	v_lshrrev_b32_e32 v120, 4, v120
	s_mov_b32 s12, 0x8400
	v_mad_u64_u32 v[120:121], s[12:13], v120, s12, v[114:115]
	v_lshlrev_b64 v[120:121], 5, v[120:121]
	v_cvt_pk_bf16_f32 v96, v118, v119
	v_cvt_pk_bf16_f32 v97, v116, v117
	v_cvt_pk_bf16_f32 v98, v102, v103
	v_cvt_pk_bf16_f32 v99, v100, v101
	v_lshl_add_u64 v[120:121], v[186:187], 0, v[120:121]
	s_mov_b64 s[12:13], 0
	global_store_dwordx4 v[120:121], v[96:99], off nt

; __device__ __forceinline__ unsigned pk2(float lo, float hi) { const f32x2 v = {lo, hi}; return __builtin_bit_cast(unsigned, __builtin_convertvector(v, bf16x2_t)); }
;     __device__ __forceinline__ void operator()(const f32x4 (&acc)[2][2][4][2], const Unit& un, int wr, int wc, int fr, int fq) const {
;     ...
;                 const bool isq = pn < 10; const int cs = isq ? (pn - 8) * 256 + ct : ct;
;                 float x[8] = {v0.x, v0.y, v0.z, v0.w, v1.x, v1.y, v1.z, v1.w};
;                 if (lat) { const f32x4 ra = rp[m][0], rb = rp[m][1]; const float cc[4] = {ra.x, ra.z, rb.x, rb.z}, sn[4] = {ra.y, ra.w, rb.y, rb.w};
; #pragma unroll
;                     for (int jj = 0; jj < 4; ++jj) { const float x1 = x[2 * jj], x2 = x[2 * jj + 1]; x[2 * jj] = x1 * cc[jj] - x2 * sn[jj]; x[2 * jj + 1] = x1 * sn[jj] + x2 * cc[jj]; } }
;                 const float sc = isq ? QSCALE : 1.f;
;                 u32x4 w; w.x = pk2(x[0] * sc, x[1] * sc); w.y = pk2(x[2] * sc, x[3] * sc); w.z = pk2(x[4] * sc, x[5] * sc); w.w = pk2(x[6] * sc, x[7] * sc);
;                 if (isq) *(u32x4*)(q + (size_t)row * 512 + cs) = w; else *(u32x4*)(k + (size_t)row * 128 + cs) = w;
.LBB0_538:
	v_pk_mul_f32 v[96:97], v[196:197], v[96:97] op_sel_hi:[0,1]
	v_pk_mul_f32 v[98:99], v[196:197], v[98:99] op_sel_hi:[0,1]
	v_cvt_pk_bf16_f32 v96, v96, v97
	v_cvt_pk_bf16_f32 v97, v98, v99
	v_pk_mul_f32 v[98:99], v[196:197], v[120:121] op_sel_hi:[0,1]
	v_pk_mul_f32 v[120:121], v[196:197], v[122:123] op_sel_hi:[0,1]
	v_cvt_pk_bf16_f32 v98, v98, v99
	v_cvt_pk_bf16_f32 v99, v120, v121
	s_and_b64 vcc, exec, s[0:1]
	s_mov_b64 s[0:1], -1
	s_cbranch_vccnz .LBB0_540
	v_lshlrev_b64 v[120:121], 8, v[114:115]
	v_lshl_add_u64 v[120:121], s[22:23], 0, v[120:121]
	v_lshl_add_u64 v[120:121], v[208:209], 1, v[120:121]
	s_mov_b64 s[0:1], 0
	global_store_dwordx4 v[120:121], v[96:99], off nt
.LBB0_540:
	s_andn2_b64 vcc, exec, s[0:1]
	s_cbranch_vccnz .LBB0_542
	v_lshl_add_u64 v[120:121], s[20:21], 0, v[112:113]
	v_lshl_add_u64 v[120:121], v[208:209], 1, v[120:121]
	global_store_dwordx4 v[120:121], v[96:99], off nt

;     __device__ __forceinline__ void operator()(const f32x4 (&acc)[2][2][4][2], const Unit& un, int wr, int wc, int fr, int fq) const {
;     ...
;             const f32x4 v0 = acc[ai][bj][m][0] * rr[ai][m] + s0[bj], v1 = acc[ai][bj][m][1] * rr[ai][m] + s1[bj];
;             if (pn < 4) {
;                 u32x4 w; w.x = pk2(gelu_tanh(v0.x), gelu_tanh(v0.y)); w.y = pk2(gelu_tanh(v0.z), gelu_tanh(v0.w)); w.z = pk2(gelu_tanh(v1.x), gelu_tanh(v1.y)); w.w = pk2(gelu_tanh(v1.z), gelu_tanh(v1.w));
;                 *(u32x4*)(ga + (size_t)row * 1024 + pn * 256 + ct) = w;
;             } else if (pn < 8) {
;                 u32x2 w; w.x = pk2(v0.x * sigmoidf_(v0.y), v0.z * sigmoidf_(v0.w)); w.y = pk2(v1.x * sigmoidf_(v1.y), v1.z * sigmoidf_(v1.w));
;                 *(u32x2*)(yb + (size_t)row * 512 + (((pn - 4) * 256 + ct) >> 1)) = w;
;             } else if (pn < 10 || (pn == 10 && bj == 0)) {
;                 const bool isq = pn < 10; const int cs = isq ? (pn - 8) * 256 + ct : ct;
;                 float x[8] = {v0.x, v0.y, v0.z, v0.w, v1.x, v1.y, v1.z, v1.w};
;                 if (lat) { const f32x4 ra = rp[m][0], rb = rp[m][1]; const float cc[4] = {ra.x, ra.z, rb.x, rb.z}, sn[4] = {ra.y, ra.w, rb.y, rb.w};
; #pragma unroll
;                     for (int jj = 0; jj < 4; ++jj) { const float x1 = x[2 * jj], x2 = x[2 * jj + 1]; x[2 * jj] = x1 * cc[jj] - x2 * sn[jj]; x[2 * jj + 1] = x1 * sn[jj] + x2 * cc[jj]; } }
;                 const float sc = isq ? QSCALE : 1.f;
;                 u32x4 w; w.x = pk2(x[0] * sc, x[1] * sc); w.y = pk2(x[2] * sc, x[3] * sc); w.z = pk2(x[4] * sc, x[5] * sc); w.w = pk2(x[6] * sc, x[7] * sc);
;                 if (isq) *(u32x4*)(q + (size_t)row * 512 + cs) = w; else *(u32x4*)(k + (size_t)row * 128 + cs) = w;
;             } else if (pn == 10) {
;                 const int dc = ct - 128; const float x[8] = {v0.x, v0.y, v0.z, v0.w, v1.x, v1.y, v1.z, v1.w};
;                 if (lat) { const int b = row >> 13, t = row & (SEQ - 1);
; #pragma unroll
;                     for (int e = 0; e < 8; ++e) vT[((size_t)(b * 128 + dc + e)) * SEQ + t] = (bf16)f2bf(x[e]); }
;                 else { const int rc = row - NLAT, b = rc >> 8, t = rc & 255;
; #pragma unroll
;                     for (int e = 0; e < 8; ++e) vcT[((size_t)(b * 128 + dc + e)) * CTXL + t] = (bf16)f2bf(x[e]); }
;             } else {
.LBB0_546:
	v_lshlrev_b64 v[96:97], 11, v[114:115]
	v_lshl_add_u64 v[96:97], s[16:17], 0, v[96:97]
	s_andn2_b64 vcc, exec, s[0:1]
	v_lshl_add_u64 v[96:97], s[50:51], 1, v[96:97]
	s_cbranch_vccnz .LBB0_548
	v_mul_f32_e32 v98, 0x3d372713, v118
	v_mul_f32_e32 v99, 0x3d372713, v119
	v_mul_f32_e32 v98, v118, v98
	v_mul_f32_e32 v99, v119, v99
	v_mov_b32_e32 v120, v119
	v_fma_f32 v98, v118, v98, v118
	v_fmac_f32_e32 v120, v120, v99
	v_mul_f32_e32 v98, 0x3f4c422a, v98
	v_mul_f32_e32 v99, 0x3f4c422a, v120
	v_add_f32_e32 v98, v98, v98
	v_add_f32_e32 v99, v99, v99
	v_mul_f32_e32 v98, 0xbfb8aa3b, v98
	v_mul_f32_e32 v99, 0xbfb8aa3b, v99
	v_exp_f32_e32 v98, v98
	v_exp_f32_e32 v99, v99
	v_mov_b32_e32 v169, v209
	v_add_f32_e32 v98, 1.0, v98
	v_add_f32_e32 v99, 1.0, v99
	v_rcp_f32_e32 v98, v98
	v_rcp_f32_e32 v99, v99
	s_nop 0
	v_pk_mul_f32 v[98:99], v[118:119], v[98:99]
	s_nop 0
	v_cvt_pk_bf16_f32 v118, v98, v99
	v_mul_f32_e32 v98, 0x3d372713, v116
	v_mul_f32_e32 v99, 0x3d372713, v117
	v_mul_f32_e32 v98, v116, v98
	v_mul_f32_e32 v99, v117, v99
	v_fma_f32 v98, v116, v98, v116
	v_fma_f32 v99, v117, v99, v117
	v_mul_f32_e32 v98, 0x3f4c422a, v98
	v_mul_f32_e32 v99, 0x3f4c422a, v99
	v_add_f32_e32 v98, v98, v98
	v_add_f32_e32 v99, v99, v99
	v_mul_f32_e32 v98, 0xbfb8aa3b, v98
	v_mul_f32_e32 v99, 0xbfb8aa3b, v99
	v_exp_f32_e32 v98, v98
	v_exp_f32_e32 v99, v99
	v_add_f32_e32 v98, 1.0, v98
	v_add_f32_e32 v99, 1.0, v99
	v_rcp_f32_e32 v98, v98
	v_rcp_f32_e32 v99, v99
	s_nop 0
	v_pk_mul_f32 v[98:99], v[116:117], v[98:99]
	s_nop 0
	v_cvt_pk_bf16_f32 v119, v98, v99
	v_mul_f32_e32 v98, 0x3d372713, v102
	v_mul_f32_e32 v99, 0x3d372713, v103
	v_mul_f32_e32 v98, v102, v98
	v_mul_f32_e32 v99, v103, v99
	v_mov_b32_e32 v116, v103
	v_fma_f32 v98, v102, v98, v102
	v_fmac_f32_e32 v116, v116, v99
	v_mul_f32_e32 v98, 0x3f4c422a, v98
	v_mul_f32_e32 v99, 0x3f4c422a, v116
	v_add_f32_e32 v98, v98, v98
	v_add_f32_e32 v99, v99, v99
	v_mul_f32_e32 v98, 0xbfb8aa3b, v98
	v_mul_f32_e32 v99, 0xbfb8aa3b, v99
	v_exp_f32_e32 v98, v98
	v_exp_f32_e32 v99, v99
	v_add_f32_e32 v98, 1.0, v98
	v_add_f32_e32 v99, 1.0, v99
	v_rcp_f32_e32 v98, v98
	v_rcp_f32_e32 v99, v99
	s_nop 0
	v_pk_mul_f32 v[98:99], v[102:103], v[98:99]
	s_nop 0
	v_cvt_pk_bf16_f32 v120, v98, v99
	v_mul_f32_e32 v98, 0x3d372713, v100
	v_mul_f32_e32 v99, 0x3d372713, v101
	v_mul_f32_e32 v98, v100, v98
	v_mul_f32_e32 v99, v101, v99
	v_fma_f32 v98, v100, v98, v100
	v_fma_f32 v99, v101, v99, v101
	v_mul_f32_e32 v98, 0x3f4c422a, v98
	v_mul_f32_e32 v99, 0x3f4c422a, v99
	v_add_f32_e32 v98, v98, v98
	v_add_f32_e32 v99, v99, v99
	v_mul_f32_e32 v98, 0xbfb8aa3b, v98
	v_mul_f32_e32 v99, 0xbfb8aa3b, v99
	v_exp_f32_e32 v98, v98
	v_exp_f32_e32 v99, v99
	v_add_f32_e32 v98, 1.0, v98
	v_add_f32_e32 v99, 1.0, v99
	v_rcp_f32_e32 v98, v98
	v_rcp_f32_e32 v99, v99
	s_nop 0
	v_pk_mul_f32 v[98:99], v[100:101], v[98:99]
	s_nop 0
	v_cvt_pk_bf16_f32 v121, v98, v99
	v_lshl_add_u64 v[98:99], v[96:97], 0, v[168:169]
	global_store_dwordx4 v[98:99], v[118:121], off nt
.LBB0_548:
	s_addk_i32 s76, 0x8080
	v_ashrrev_i32_e32 v98, 6, v114
	v_mov_b32_e32 v205, v204
	s_ashr_i32 s0, s76, 1
	v_and_b32_e32 v116, 0xffffff80, v98
	v_mov_b32_e32 v98, v204
	v_mov_b32_e32 v99, v204
	s_and_b32 s54, s0, 0xffffff80
	v_pk_fma_f32 v[94:95], v[94:95], v[98:99], v[30:31]
	v_pk_fma_f32 v[92:93], v[92:93], v[204:205], v[28:29]
	v_pk_fma_f32 v[90:91], v[90:91], v[98:99], v[26:27]
	v_pk_fma_f32 v[88:89], v[88:89], v[204:205], v[24:25]
	s_and_b64 vcc, exec, s[10:11]
	s_mov_b64 s[0:1], -1
	s_cbranch_vccnz .LBB0_568
	s_and_b64 vcc, exec, s[8:9]
	s_cbranch_vccnz .LBB0_565
	s_andn2_b64 vcc, exec, s[48:49]
	s_cbranch_vccnz .LBB0_559
	s_andn2_b64 vcc, exec, s[46:47]
	s_cbranch_vccnz .LBB0_553
	v_or_b32_e32 v102, s75, v239
	v_lshrrev_b32_e32 v102, 4, v102
	s_mov_b32 s0, 0x8400
	v_mad_u64_u32 v[102:103], s[0:1], v102, s0, v[114:115]
	v_lshlrev_b64 v[102:103], 5, v[102:103]
	v_cvt_pk_bf16_f32 v98, v92, v93
	v_cvt_pk_bf16_f32 v99, v94, v95
	v_cvt_pk_bf16_f32 v100, v88, v89
	v_cvt_pk_bf16_f32 v101, v90, v91
	v_lshl_add_u64 v[102:103], v[186:187], 0, v[102:103]
	s_mov_b64 s[0:1], 0
	global_store_dwordx4 v[102:103], v[98:101], off nt

; __device__ __forceinline__ unsigned pk2(float lo, float hi) { const f32x2 v = {lo, hi}; return __builtin_bit_cast(unsigned, __builtin_convertvector(v, bf16x2_t)); }
;     __device__ __forceinline__ void operator()(const f32x4 (&acc)[2][2][4][2], const Unit& un, int wr, int wc, int fr, int fq) const {
;     ...
;                 const float sc = isq ? QSCALE : 1.f;
;                 u32x4 w; w.x = pk2(x[0] * sc, x[1] * sc); w.y = pk2(x[2] * sc, x[3] * sc); w.z = pk2(x[4] * sc, x[5] * sc); w.w = pk2(x[6] * sc, x[7] * sc);
;                 if (isq) *(u32x4*)(q + (size_t)row * 512 + cs) = w; else *(u32x4*)(k + (size_t)row * 128 + cs) = w;
.LBB0_563:
	s_mov_b32 s0, 0x3e38aa3b
	v_pk_mul_f32 v[98:99], v[98:99], s[0:1] op_sel_hi:[1,0]
	v_pk_mul_f32 v[100:101], v[100:101], s[0:1] op_sel_hi:[1,0]
	v_cvt_pk_bf16_f32 v98, v98, v99
	v_cvt_pk_bf16_f32 v99, v100, v101
	v_pk_mul_f32 v[100:101], v[102:103], s[0:1] op_sel_hi:[1,0]
	v_pk_mul_f32 v[102:103], v[104:105], s[0:1] op_sel_hi:[1,0]
	v_cvt_pk_bf16_f32 v100, v100, v101
	v_cvt_pk_bf16_f32 v101, v102, v103
	v_lshl_add_u64 v[102:103], s[20:21], 0, v[112:113]
	v_add_u32_e32 v208, s37, v184
	v_lshl_add_u64 v[102:103], v[208:209], 1, v[102:103]
	global_store_dwordx4 v[102:103], v[98:101], off offset:256 nt

; __device__ __forceinline__ unsigned f2bf(float f) { return pk2(f, f) & 0xffffu; }
;     __device__ __forceinline__ void operator()(const f32x4 (&acc)[2][2][4][2], const Unit& un, int wr, int wc, int fr, int fq) const {
;     ...
;             const int row = rbase + ai * 128 + m * 16; const int ct = bj * 128 + cw;
;             const f32x4 v0 = acc[ai][bj][m][0] * rr[ai][m] + s0[bj], v1 = acc[ai][bj][m][1] * rr[ai][m] + s1[bj];
;             if (pn < 4) {
;                 u32x4 w; w.x = pk2(gelu_tanh(v0.x), gelu_tanh(v0.y)); w.y = pk2(gelu_tanh(v0.z), gelu_tanh(v0.w)); w.z = pk2(gelu_tanh(v1.x), gelu_tanh(v1.y)); w.w = pk2(gelu_tanh(v1.z), gelu_tanh(v1.w));
;                 *(u32x4*)(ga + (size_t)row * 1024 + pn * 256 + ct) = w;
;             } else if (pn < 8) {
;                 u32x2 w; w.x = pk2(v0.x * sigmoidf_(v0.y), v0.z * sigmoidf_(v0.w)); w.y = pk2(v1.x * sigmoidf_(v1.y), v1.z * sigmoidf_(v1.w));
;                 *(u32x2*)(yb + (size_t)row * 512 + (((pn - 4) * 256 + ct) >> 1)) = w;
;             } else if (pn < 10 || (pn == 10 && bj == 0)) {
;                 const bool isq = pn < 10; const int cs = isq ? (pn - 8) * 256 + ct : ct;
;                 float x[8] = {v0.x, v0.y, v0.z, v0.w, v1.x, v1.y, v1.z, v1.w};
;                 if (lat) { const f32x4 ra = rp[m][0], rb = rp[m][1]; const float cc[4] = {ra.x, ra.z, rb.x, rb.z}, sn[4] = {ra.y, ra.w, rb.y, rb.w};
; #pragma unroll
;                     for (int jj = 0; jj < 4; ++jj) { const float x1 = x[2 * jj], x2 = x[2 * jj + 1]; x[2 * jj] = x1 * cc[jj] - x2 * sn[jj]; x[2 * jj + 1] = x1 * sn[jj] + x2 * cc[jj]; } }
;                 const float sc = isq ? QSCALE : 1.f;
;                 u32x4 w; w.x = pk2(x[0] * sc, x[1] * sc); w.y = pk2(x[2] * sc, x[3] * sc); w.z = pk2(x[4] * sc, x[5] * sc); w.w = pk2(x[6] * sc, x[7] * sc);
;                 if (isq) *(u32x4*)(q + (size_t)row * 512 + cs) = w; else *(u32x4*)(k + (size_t)row * 128 + cs) = w;
;             } else if (pn == 10) {
;                 const int dc = ct - 128; const float x[8] = {v0.x, v0.y, v0.z, v0.w, v1.x, v1.y, v1.z, v1.w};
;                 if (lat) { const int b = row >> 13, t = row & (SEQ - 1);
; #pragma unroll
;                     for (int e = 0; e < 8; ++e) vT[((size_t)(b * 128 + dc + e)) * SEQ + t] = (bf16)f2bf(x[e]); }
;                 else { const int rc = row - NLAT, b = rc >> 8, t = rc & 255;
; #pragma unroll
.LBB0_568:
	s_andn2_b64 vcc, exec, s[0:1]
	s_cbranch_vccnz .LBB0_570
	v_mul_f32_e32 v98, 0x3d372713, v92
	v_mul_f32_e32 v99, 0x3d372713, v93
	v_mul_f32_e32 v98, v92, v98
	v_mul_f32_e32 v99, v93, v99
	v_mov_b32_e32 v100, v93
	v_fma_f32 v98, v92, v98, v92
	v_fmac_f32_e32 v100, v100, v99
	v_mul_f32_e32 v98, 0x3f4c422a, v98
	v_mul_f32_e32 v99, 0x3f4c422a, v100
	v_add_f32_e32 v98, v98, v98
	v_add_f32_e32 v99, v99, v99
	v_mul_f32_e32 v98, 0xbfb8aa3b, v98
	v_mul_f32_e32 v99, 0xbfb8aa3b, v99
	v_exp_f32_e32 v98, v98
	v_exp_f32_e32 v99, v99
	v_mov_b32_e32 v169, v209
	v_add_f32_e32 v98, 1.0, v98
	v_add_f32_e32 v99, 1.0, v99
	v_rcp_f32_e32 v98, v98
	v_rcp_f32_e32 v99, v99
	s_nop 0
	v_pk_mul_f32 v[92:93], v[92:93], v[98:99]
	s_nop 0
	v_cvt_pk_bf16_f32 v92, v92, v93
	v_mul_f32_e32 v93, 0x3d372713, v94
	v_mul_f32_e32 v93, v94, v93
	v_fma_f32 v93, v94, v93, v94
	v_mul_f32_e32 v93, 0x3f4c422a, v93
	v_add_f32_e32 v93, v93, v93
	v_mul_f32_e32 v93, 0xbfb8aa3b, v93
	v_exp_f32_e32 v93, v93
	s_nop 0
	v_add_f32_e32 v93, 1.0, v93
	v_rcp_f32_e32 v98, v93
	v_mul_f32_e32 v93, 0x3d372713, v95
	v_mul_f32_e32 v93, v95, v93
	v_fma_f32 v93, v95, v93, v95
	v_mul_f32_e32 v93, 0x3f4c422a, v93
	v_add_f32_e32 v93, v93, v93
	v_mul_f32_e32 v93, 0xbfb8aa3b, v93
	v_exp_f32_e32 v93, v93
	s_nop 0
	v_add_f32_e32 v93, 1.0, v93
	v_rcp_f32_e32 v99, v93
	s_nop 0
	v_pk_mul_f32 v[94:95], v[94:95], v[98:99]
	s_nop 0
	v_cvt_pk_bf16_f32 v93, v94, v95
	v_mul_f32_e32 v94, 0x3d372713, v88
	v_mul_f32_e32 v95, 0x3d372713, v89
	v_mul_f32_e32 v94, v88, v94
	v_mul_f32_e32 v95, v89, v95
	v_mov_b32_e32 v98, v89
	v_fma_f32 v94, v88, v94, v88
	v_fmac_f32_e32 v98, v98, v95
	v_mul_f32_e32 v94, 0x3f4c422a, v94
	v_mul_f32_e32 v95, 0x3f4c422a, v98
	v_add_f32_e32 v94, v94, v94
	v_add_f32_e32 v95, v95, v95
	v_mul_f32_e32 v94, 0xbfb8aa3b, v94
	v_mul_f32_e32 v95, 0xbfb8aa3b, v95
	v_exp_f32_e32 v94, v94
	v_exp_f32_e32 v95, v95
	v_add_f32_e32 v94, 1.0, v94
	v_add_f32_e32 v95, 1.0, v95
	v_rcp_f32_e32 v94, v94
	v_rcp_f32_e32 v95, v95
	s_nop 0
	v_pk_mul_f32 v[88:89], v[88:89], v[94:95]
	s_nop 0
	v_cvt_pk_bf16_f32 v94, v88, v89
	v_mul_f32_e32 v88, 0x3d372713, v90
	v_mul_f32_e32 v89, 0x3d372713, v91
	v_mul_f32_e32 v88, v90, v88
	v_mul_f32_e32 v89, v91, v89
	v_fma_f32 v88, v90, v88, v90
	v_fma_f32 v89, v91, v89, v91
	v_mul_f32_e32 v88, 0x3f4c422a, v88
	v_mul_f32_e32 v89, 0x3f4c422a, v89
	v_add_f32_e32 v88, v88, v88
	v_add_f32_e32 v89, v89, v89
	v_mul_f32_e32 v88, 0xbfb8aa3b, v88
	v_mul_f32_e32 v89, 0xbfb8aa3b, v89
	v_exp_f32_e32 v88, v88
	v_exp_f32_e32 v89, v89
	v_add_f32_e32 v88, 1.0, v88
	v_add_f32_e32 v89, 1.0, v89
	v_rcp_f32_e32 v88, v88
	v_rcp_f32_e32 v89, v89
	s_nop 0
	v_pk_mul_f32 v[88:89], v[90:91], v[88:89]
	s_nop 0
	v_cvt_pk_bf16_f32 v95, v88, v89
	v_lshl_add_u64 v[88:89], v[96:97], 0, v[168:169]
	global_store_dwordx4 v[88:89], v[92:95], off offset:256 nt
.LBB0_570:
	v_add_u32_e32 v90, 0x90, v198
	v_ashrrev_i32_e32 v91, 31, v90
	v_lshlrev_b64 v[88:89], 10, v[90:91]
	v_pk_fma_f32 v[92:93], v[78:79], v[202:203], v[46:47] op_sel_hi:[1,0,1]
	v_pk_fma_f32 v[94:95], v[76:77], v[202:203], v[44:45] op_sel_hi:[1,0,1]
	v_pk_fma_f32 v[76:77], v[74:75], v[202:203], v[42:43] op_sel_hi:[1,0,1]
	v_pk_fma_f32 v[78:79], v[72:73], v[202:203], v[40:41] op_sel_hi:[1,0,1]
	s_and_b64 vcc, exec, s[10:11]
	s_mov_b64 s[0:1], -1
	s_cbranch_vccnz .LBB0_590
	s_and_b64 vcc, exec, s[8:9]
	s_cbranch_vccnz .LBB0_587
	v_cndmask_b32_e64 v72, 0, 1, s[48:49]
	v_cmp_ne_u32_e64 s[0:1], 1, v72
	s_andn2_b64 vcc, exec, s[48:49]
	s_cbranch_vccnz .LBB0_576
	s_mov_b64 s[12:13], -1
	s_and_b64 vcc, exec, s[46:47]
	s_cbranch_vccz .LBB0_575
	v_or_b32_e32 v96, s75, v184
	v_lshrrev_b32_e32 v96, 4, v96
	s_mov_b32 s12, 0x8400
	v_mad_u64_u32 v[96:97], s[12:13], v96, s12, v[90:91]
	v_lshlrev_b64 v[96:97], 5, v[96:97]
	v_cvt_pk_bf16_f32 v72, v94, v95
	v_cvt_pk_bf16_f32 v73, v92, v93
	v_cvt_pk_bf16_f32 v74, v78, v79
	v_cvt_pk_bf16_f32 v75, v76, v77
	v_lshl_add_u64 v[96:97], v[186:187], 0, v[96:97]
	s_mov_b64 s[12:13], 0
	global_store_dwordx4 v[96:97], v[72:75], off nt

; __device__ __forceinline__ unsigned pk2(float lo, float hi) { const f32x2 v = {lo, hi}; return __builtin_bit_cast(unsigned, __builtin_convertvector(v, bf16x2_t)); }
;     __device__ __forceinline__ void operator()(const f32x4 (&acc)[2][2][4][2], const Unit& un, int wr, int wc, int fr, int fq) const {
;     ...
;                 const bool isq = pn < 10; const int cs = isq ? (pn - 8) * 256 + ct : ct;
;                 float x[8] = {v0.x, v0.y, v0.z, v0.w, v1.x, v1.y, v1.z, v1.w};
;                 if (lat) { const f32x4 ra = rp[m][0], rb = rp[m][1]; const float cc[4] = {ra.x, ra.z, rb.x, rb.z}, sn[4] = {ra.y, ra.w, rb.y, rb.w};
; #pragma unroll
;                     for (int jj = 0; jj < 4; ++jj) { const float x1 = x[2 * jj], x2 = x[2 * jj + 1]; x[2 * jj] = x1 * cc[jj] - x2 * sn[jj]; x[2 * jj + 1] = x1 * sn[jj] + x2 * cc[jj]; } }
;                 const float sc = isq ? QSCALE : 1.f;
;                 u32x4 w; w.x = pk2(x[0] * sc, x[1] * sc); w.y = pk2(x[2] * sc, x[3] * sc); w.z = pk2(x[4] * sc, x[5] * sc); w.w = pk2(x[6] * sc, x[7] * sc);
;                 if (isq) *(u32x4*)(q + (size_t)row * 512 + cs) = w; else *(u32x4*)(k + (size_t)row * 128 + cs) = w;
.LBB0_582:
	v_pk_mul_f32 v[72:73], v[196:197], v[72:73] op_sel_hi:[0,1]
	v_pk_mul_f32 v[74:75], v[196:197], v[74:75] op_sel_hi:[0,1]
	v_cvt_pk_bf16_f32 v72, v72, v73
	v_cvt_pk_bf16_f32 v73, v74, v75
	v_pk_mul_f32 v[74:75], v[196:197], v[96:97] op_sel_hi:[0,1]
	v_pk_mul_f32 v[96:97], v[196:197], v[98:99] op_sel_hi:[0,1]
	v_cvt_pk_bf16_f32 v74, v74, v75
	v_cvt_pk_bf16_f32 v75, v96, v97
	s_and_b64 vcc, exec, s[0:1]
	s_mov_b64 s[0:1], -1
	s_cbranch_vccnz .LBB0_584
	v_lshlrev_b64 v[96:97], 8, v[90:91]
	v_lshl_add_u64 v[96:97], s[22:23], 0, v[96:97]
	v_lshl_add_u64 v[96:97], v[208:209], 1, v[96:97]
	s_mov_b64 s[0:1], 0
	global_store_dwordx4 v[96:97], v[72:75], off nt
.LBB0_584:
	s_andn2_b64 vcc, exec, s[0:1]
	s_cbranch_vccnz .LBB0_586
	v_lshl_add_u64 v[96:97], s[20:21], 0, v[88:89]
	v_lshl_add_u64 v[96:97], v[208:209], 1, v[96:97]
	global_store_dwordx4 v[96:97], v[72:75], off nt

; __device__ __forceinline__ unsigned f2bf(float f) { return pk2(f, f) & 0xffffu; }
;     __device__ __forceinline__ void operator()(const f32x4 (&acc)[2][2][4][2], const Unit& un, int wr, int wc, int fr, int fq) const {
;     ...
;             const int row = rbase + ai * 128 + m * 16; const int ct = bj * 128 + cw;
;             const f32x4 v0 = acc[ai][bj][m][0] * rr[ai][m] + s0[bj], v1 = acc[ai][bj][m][1] * rr[ai][m] + s1[bj];
;             if (pn < 4) {
;                 u32x4 w; w.x = pk2(gelu_tanh(v0.x), gelu_tanh(v0.y)); w.y = pk2(gelu_tanh(v0.z), gelu_tanh(v0.w)); w.z = pk2(gelu_tanh(v1.x), gelu_tanh(v1.y)); w.w = pk2(gelu_tanh(v1.z), gelu_tanh(v1.w));
;                 *(u32x4*)(ga + (size_t)row * 1024 + pn * 256 + ct) = w;
;             } else if (pn < 8) {
;                 u32x2 w; w.x = pk2(v0.x * sigmoidf_(v0.y), v0.z * sigmoidf_(v0.w)); w.y = pk2(v1.x * sigmoidf_(v1.y), v1.z * sigmoidf_(v1.w));
;                 *(u32x2*)(yb + (size_t)row * 512 + (((pn - 4) * 256 + ct) >> 1)) = w;
;             } else if (pn < 10 || (pn == 10 && bj == 0)) {
;                 const bool isq = pn < 10; const int cs = isq ? (pn - 8) * 256 + ct : ct;
;                 float x[8] = {v0.x, v0.y, v0.z, v0.w, v1.x, v1.y, v1.z, v1.w};
;                 if (lat) { const f32x4 ra = rp[m][0], rb = rp[m][1]; const float cc[4] = {ra.x, ra.z, rb.x, rb.z}, sn[4] = {ra.y, ra.w, rb.y, rb.w};
; #pragma unroll
;                     for (int jj = 0; jj < 4; ++jj) { const float x1 = x[2 * jj], x2 = x[2 * jj + 1]; x[2 * jj] = x1 * cc[jj] - x2 * sn[jj]; x[2 * jj + 1] = x1 * sn[jj] + x2 * cc[jj]; } }
;                 const float sc = isq ? QSCALE : 1.f;
;                 u32x4 w; w.x = pk2(x[0] * sc, x[1] * sc); w.y = pk2(x[2] * sc, x[3] * sc); w.z = pk2(x[4] * sc, x[5] * sc); w.w = pk2(x[6] * sc, x[7] * sc);
;                 if (isq) *(u32x4*)(q + (size_t)row * 512 + cs) = w; else *(u32x4*)(k + (size_t)row * 128 + cs) = w;
;             } else if (pn == 10) {
;                 const int dc = ct - 128; const float x[8] = {v0.x, v0.y, v0.z, v0.w, v1.x, v1.y, v1.z, v1.w};
;                 if (lat) { const int b = row >> 13, t = row & (SEQ - 1);
; #pragma unroll
;                     for (int e = 0; e < 8; ++e) vT[((size_t)(b * 128 + dc + e)) * SEQ + t] = (bf16)f2bf(x[e]); }
;                 else { const int rc = row - NLAT, b = rc >> 8, t = rc & 255;
; #pragma unroll
.LBB0_590:
	v_lshlrev_b64 v[72:73], 11, v[90:91]
	v_lshl_add_u64 v[72:73], s[16:17], 0, v[72:73]
	s_andn2_b64 vcc, exec, s[0:1]
	v_lshl_add_u64 v[72:73], s[50:51], 1, v[72:73]
	s_cbranch_vccnz .LBB0_592
	v_mul_f32_e32 v74, 0x3d372713, v94
	v_mul_f32_e32 v75, 0x3d372713, v95
	v_mul_f32_e32 v74, v94, v74
	v_mul_f32_e32 v75, v95, v75
	v_mov_b32_e32 v96, v95
	v_fma_f32 v74, v94, v74, v94
	v_fmac_f32_e32 v96, v96, v75
	v_mul_f32_e32 v74, 0x3f4c422a, v74
	v_mul_f32_e32 v75, 0x3f4c422a, v96
	v_add_f32_e32 v74, v74, v74
	v_add_f32_e32 v75, v75, v75
	v_mul_f32_e32 v74, 0xbfb8aa3b, v74
	v_mul_f32_e32 v75, 0xbfb8aa3b, v75
	v_exp_f32_e32 v74, v74
	v_exp_f32_e32 v75, v75
	v_mov_b32_e32 v169, v209
	v_add_f32_e32 v74, 1.0, v74
	v_add_f32_e32 v75, 1.0, v75
	v_rcp_f32_e32 v74, v74
	v_rcp_f32_e32 v75, v75
	s_nop 0
	v_pk_mul_f32 v[74:75], v[94:95], v[74:75]
	s_nop 0
	v_cvt_pk_bf16_f32 v94, v74, v75
	v_mul_f32_e32 v74, 0x3d372713, v92
	v_mul_f32_e32 v75, 0x3d372713, v93
	v_mul_f32_e32 v74, v92, v74
	v_mul_f32_e32 v75, v93, v75
	v_fma_f32 v74, v92, v74, v92
	v_fma_f32 v75, v93, v75, v93
	v_mul_f32_e32 v74, 0x3f4c422a, v74
	v_mul_f32_e32 v75, 0x3f4c422a, v75
	v_add_f32_e32 v74, v74, v74
	v_add_f32_e32 v75, v75, v75
	v_mul_f32_e32 v74, 0xbfb8aa3b, v74
	v_mul_f32_e32 v75, 0xbfb8aa3b, v75
	v_exp_f32_e32 v74, v74
	v_exp_f32_e32 v75, v75
	v_add_f32_e32 v74, 1.0, v74
	v_add_f32_e32 v75, 1.0, v75
	v_rcp_f32_e32 v74, v74
	v_rcp_f32_e32 v75, v75
	s_nop 0
	v_pk_mul_f32 v[74:75], v[92:93], v[74:75]
	s_nop 0
	v_cvt_pk_bf16_f32 v95, v74, v75
	v_mul_f32_e32 v74, 0x3d372713, v78
	v_mul_f32_e32 v75, 0x3d372713, v79
	v_mul_f32_e32 v74, v78, v74
	v_mul_f32_e32 v75, v79, v75
	v_mov_b32_e32 v92, v79
	v_fma_f32 v74, v78, v74, v78
	v_fmac_f32_e32 v92, v92, v75
	v_mul_f32_e32 v74, 0x3f4c422a, v74
	v_mul_f32_e32 v75, 0x3f4c422a, v92
	v_add_f32_e32 v74, v74, v74
	v_add_f32_e32 v75, v75, v75
	v_mul_f32_e32 v74, 0xbfb8aa3b, v74
	v_mul_f32_e32 v75, 0xbfb8aa3b, v75
	v_exp_f32_e32 v74, v74
	v_exp_f32_e32 v75, v75
	v_add_f32_e32 v74, 1.0, v74
	v_add_f32_e32 v75, 1.0, v75
	v_rcp_f32_e32 v74, v74
	v_rcp_f32_e32 v75, v75
	s_nop 0
	v_pk_mul_f32 v[74:75], v[78:79], v[74:75]
	s_nop 0
	v_cvt_pk_bf16_f32 v96, v74, v75
	v_mul_f32_e32 v74, 0x3d372713, v76
	v_mul_f32_e32 v75, 0x3d372713, v77
	v_mul_f32_e32 v74, v76, v74
	v_mul_f32_e32 v75, v77, v75
	v_fma_f32 v74, v76, v74, v76
	v_fma_f32 v75, v77, v75, v77
	v_mul_f32_e32 v74, 0x3f4c422a, v74
	v_mul_f32_e32 v75, 0x3f4c422a, v75
	v_add_f32_e32 v74, v74, v74
	v_add_f32_e32 v75, v75, v75
	v_mul_f32_e32 v74, 0xbfb8aa3b, v74
	v_mul_f32_e32 v75, 0xbfb8aa3b, v75
	v_exp_f32_e32 v74, v74
	v_exp_f32_e32 v75, v75
	v_add_f32_e32 v74, 1.0, v74
	v_add_f32_e32 v75, 1.0, v75
	v_rcp_f32_e32 v74, v74
	v_rcp_f32_e32 v75, v75
	s_nop 0
	v_pk_mul_f32 v[74:75], v[76:77], v[74:75]
	s_nop 0
	v_cvt_pk_bf16_f32 v97, v74, v75
	v_lshl_add_u64 v[74:75], v[72:73], 0, v[168:169]
	global_store_dwordx4 v[74:75], v[94:97], off nt
.LBB0_592:
	v_mov_b32_e32 v203, v202
	v_mov_b32_e32 v74, v202
	v_mov_b32_e32 v75, v202
	v_pk_fma_f32 v[70:71], v[70:71], v[74:75], v[30:31]
	v_pk_fma_f32 v[68:69], v[68:69], v[202:203], v[28:29]
	v_pk_fma_f32 v[66:67], v[66:67], v[74:75], v[26:27]
	v_pk_fma_f32 v[64:65], v[64:65], v[202:203], v[24:25]
	s_and_b64 vcc, exec, s[10:11]
	s_mov_b64 s[0:1], -1
	s_cbranch_vccnz .LBB0_612
	s_and_b64 vcc, exec, s[8:9]
	s_cbranch_vccnz .LBB0_609
	s_andn2_b64 vcc, exec, s[48:49]
	s_cbranch_vccnz .LBB0_603
	s_andn2_b64 vcc, exec, s[46:47]
	s_cbranch_vccnz .LBB0_597
	v_or_b32_e32 v78, s75, v239
	v_lshrrev_b32_e32 v78, 4, v78
	s_mov_b32 s0, 0x8400
	v_mad_u64_u32 v[78:79], s[0:1], v78, s0, v[90:91]
	v_lshlrev_b64 v[78:79], 5, v[78:79]
	v_cvt_pk_bf16_f32 v74, v68, v69
	v_cvt_pk_bf16_f32 v75, v70, v71
	v_cvt_pk_bf16_f32 v76, v64, v65
	v_cvt_pk_bf16_f32 v77, v66, v67
	v_lshl_add_u64 v[78:79], v[186:187], 0, v[78:79]
	s_mov_b64 s[0:1], 0
	global_store_dwordx4 v[78:79], v[74:77], off nt

; __device__ __forceinline__ unsigned pk2(float lo, float hi) { const f32x2 v = {lo, hi}; return __builtin_bit_cast(unsigned, __builtin_convertvector(v, bf16x2_t)); }
;     __device__ __forceinline__ void operator()(const f32x4 (&acc)[2][2][4][2], const Unit& un, int wr, int wc, int fr, int fq) const {
;     ...
;                 const bool isq = pn < 10; const int cs = isq ? (pn - 8) * 256 + ct : ct;
;                 float x[8] = {v0.x, v0.y, v0.z, v0.w, v1.x, v1.y, v1.z, v1.w};
;                 if (lat) { const f32x4 ra = rp[m][0], rb = rp[m][1]; const float cc[4] = {ra.x, ra.z, rb.x, rb.z}, sn[4] = {ra.y, ra.w, rb.y, rb.w};
; #pragma unroll
;                     for (int jj = 0; jj < 4; ++jj) { const float x1 = x[2 * jj], x2 = x[2 * jj + 1]; x[2 * jj] = x1 * cc[jj] - x2 * sn[jj]; x[2 * jj + 1] = x1 * sn[jj] + x2 * cc[jj]; } }
;                 const float sc = isq ? QSCALE : 1.f;
;                 u32x4 w; w.x = pk2(x[0] * sc, x[1] * sc); w.y = pk2(x[2] * sc, x[3] * sc); w.z = pk2(x[4] * sc, x[5] * sc); w.w = pk2(x[6] * sc, x[7] * sc);
;                 if (isq) *(u32x4*)(q + (size_t)row * 512 + cs) = w; else *(u32x4*)(k + (size_t)row * 128 + cs) = w;
.LBB0_607:
	s_mov_b32 s0, 0x3e38aa3b
	v_pk_mul_f32 v[74:75], v[74:75], s[0:1] op_sel_hi:[1,0]
	v_pk_mul_f32 v[76:77], v[76:77], s[0:1] op_sel_hi:[1,0]
	v_cvt_pk_bf16_f32 v74, v74, v75
	v_cvt_pk_bf16_f32 v75, v76, v77
	v_pk_mul_f32 v[76:77], v[78:79], s[0:1] op_sel_hi:[1,0]
	v_pk_mul_f32 v[78:79], v[80:81], s[0:1] op_sel_hi:[1,0]
	v_cvt_pk_bf16_f32 v76, v76, v77
	v_cvt_pk_bf16_f32 v77, v78, v79
	v_lshl_add_u64 v[78:79], s[20:21], 0, v[88:89]
	v_add_u32_e32 v208, s37, v184
	v_lshl_add_u64 v[78:79], v[208:209], 1, v[78:79]
	global_store_dwordx4 v[78:79], v[74:77], off offset:256 nt

; __device__ __forceinline__ unsigned f2bf(float f) { return pk2(f, f) & 0xffffu; }
;     __device__ __forceinline__ void operator()(const f32x4 (&acc)[2][2][4][2], const Unit& un, int wr, int wc, int fr, int fq) const {
;     ...
;             const int row = rbase + ai * 128 + m * 16; const int ct = bj * 128 + cw;
;             const f32x4 v0 = acc[ai][bj][m][0] * rr[ai][m] + s0[bj], v1 = acc[ai][bj][m][1] * rr[ai][m] + s1[bj];
;             if (pn < 4) {
;                 u32x4 w; w.x = pk2(gelu_tanh(v0.x), gelu_tanh(v0.y)); w.y = pk2(gelu_tanh(v0.z), gelu_tanh(v0.w)); w.z = pk2(gelu_tanh(v1.x), gelu_tanh(v1.y)); w.w = pk2(gelu_tanh(v1.z), gelu_tanh(v1.w));
;                 *(u32x4*)(ga + (size_t)row * 1024 + pn * 256 + ct) = w;
;             } else if (pn < 8) {
;                 u32x2 w; w.x = pk2(v0.x * sigmoidf_(v0.y), v0.z * sigmoidf_(v0.w)); w.y = pk2(v1.x * sigmoidf_(v1.y), v1.z * sigmoidf_(v1.w));
;                 *(u32x2*)(yb + (size_t)row * 512 + (((pn - 4) * 256 + ct) >> 1)) = w;
;             } else if (pn < 10 || (pn == 10 && bj == 0)) {
;                 const bool isq = pn < 10; const int cs = isq ? (pn - 8) * 256 + ct : ct;
;                 float x[8] = {v0.x, v0.y, v0.z, v0.w, v1.x, v1.y, v1.z, v1.w};
;                 if (lat) { const f32x4 ra = rp[m][0], rb = rp[m][1]; const float cc[4] = {ra.x, ra.z, rb.x, rb.z}, sn[4] = {ra.y, ra.w, rb.y, rb.w};
; #pragma unroll
;                     for (int jj = 0; jj < 4; ++jj) { const float x1 = x[2 * jj], x2 = x[2 * jj + 1]; x[2 * jj] = x1 * cc[jj] - x2 * sn[jj]; x[2 * jj + 1] = x1 * sn[jj] + x2 * cc[jj]; } }
;                 const float sc = isq ? QSCALE : 1.f;
;                 u32x4 w; w.x = pk2(x[0] * sc, x[1] * sc); w.y = pk2(x[2] * sc, x[3] * sc); w.z = pk2(x[4] * sc, x[5] * sc); w.w = pk2(x[6] * sc, x[7] * sc);
;                 if (isq) *(u32x4*)(q + (size_t)row * 512 + cs) = w; else *(u32x4*)(k + (size_t)row * 128 + cs) = w;
;             } else if (pn == 10) {
;                 const int dc = ct - 128; const float x[8] = {v0.x, v0.y, v0.z, v0.w, v1.x, v1.y, v1.z, v1.w};
;                 if (lat) { const int b = row >> 13, t = row & (SEQ - 1);
; #pragma unroll
;                     for (int e = 0; e < 8; ++e) vT[((size_t)(b * 128 + dc + e)) * SEQ + t] = (bf16)f2bf(x[e]); }
;                 else { const int rc = row - NLAT, b = rc >> 8, t = rc & 255;
; #pragma unroll
.LBB0_612:
	s_andn2_b64 vcc, exec, s[0:1]
	s_cbranch_vccnz .LBB0_614
	v_mul_f32_e32 v74, 0x3d372713, v68
	v_mul_f32_e32 v75, 0x3d372713, v69
	v_mul_f32_e32 v74, v68, v74
	v_mul_f32_e32 v75, v69, v75
	v_mov_b32_e32 v76, v69
	v_fma_f32 v74, v68, v74, v68
	v_fmac_f32_e32 v76, v76, v75
	v_mul_f32_e32 v74, 0x3f4c422a, v74
	v_mul_f32_e32 v75, 0x3f4c422a, v76
	v_add_f32_e32 v74, v74, v74
	v_add_f32_e32 v75, v75, v75
	v_mul_f32_e32 v74, 0xbfb8aa3b, v74
	v_mul_f32_e32 v75, 0xbfb8aa3b, v75
	v_exp_f32_e32 v74, v74
	v_exp_f32_e32 v75, v75
	v_mov_b32_e32 v169, v209
	v_add_f32_e32 v74, 1.0, v74
	v_add_f32_e32 v75, 1.0, v75
	v_rcp_f32_e32 v74, v74
	v_rcp_f32_e32 v75, v75
	s_nop 0
	v_pk_mul_f32 v[68:69], v[68:69], v[74:75]
	s_nop 0
	v_cvt_pk_bf16_f32 v68, v68, v69
	v_mul_f32_e32 v69, 0x3d372713, v70
	v_mul_f32_e32 v69, v70, v69
	v_fma_f32 v69, v70, v69, v70
	v_mul_f32_e32 v69, 0x3f4c422a, v69
	v_add_f32_e32 v69, v69, v69
	v_mul_f32_e32 v69, 0xbfb8aa3b, v69
	v_exp_f32_e32 v69, v69
	s_nop 0
	v_add_f32_e32 v69, 1.0, v69
	v_rcp_f32_e32 v74, v69
	v_mul_f32_e32 v69, 0x3d372713, v71
	v_mul_f32_e32 v69, v71, v69
	v_fma_f32 v69, v71, v69, v71
	v_mul_f32_e32 v69, 0x3f4c422a, v69
	v_add_f32_e32 v69, v69, v69
	v_mul_f32_e32 v69, 0xbfb8aa3b, v69
	v_exp_f32_e32 v69, v69
	s_nop 0
	v_add_f32_e32 v69, 1.0, v69
	v_rcp_f32_e32 v75, v69
	s_nop 0
	v_pk_mul_f32 v[70:71], v[70:71], v[74:75]
	s_nop 0
	v_cvt_pk_bf16_f32 v69, v70, v71
	v_mul_f32_e32 v70, 0x3d372713, v64
	v_mul_f32_e32 v71, 0x3d372713, v65
	v_mul_f32_e32 v70, v64, v70
	v_mul_f32_e32 v71, v65, v71
	v_mov_b32_e32 v74, v65
	v_fma_f32 v70, v64, v70, v64
	v_fmac_f32_e32 v74, v74, v71
	v_mul_f32_e32 v70, 0x3f4c422a, v70
	v_mul_f32_e32 v71, 0x3f4c422a, v74
	v_add_f32_e32 v70, v70, v70
	v_add_f32_e32 v71, v71, v71
	v_mul_f32_e32 v70, 0xbfb8aa3b, v70
	v_mul_f32_e32 v71, 0xbfb8aa3b, v71
	v_exp_f32_e32 v70, v70
	v_exp_f32_e32 v71, v71
	v_add_f32_e32 v70, 1.0, v70
	v_add_f32_e32 v71, 1.0, v71
	v_rcp_f32_e32 v70, v70
	v_rcp_f32_e32 v71, v71
	s_nop 0
	v_pk_mul_f32 v[64:65], v[64:65], v[70:71]
	s_nop 0
	v_cvt_pk_bf16_f32 v70, v64, v65
	v_mul_f32_e32 v64, 0x3d372713, v66
	v_mul_f32_e32 v65, 0x3d372713, v67
	v_mul_f32_e32 v64, v66, v64
	v_mul_f32_e32 v65, v67, v65
	v_fma_f32 v64, v66, v64, v66
	v_fma_f32 v65, v67, v65, v67
	v_mul_f32_e32 v64, 0x3f4c422a, v64
	v_mul_f32_e32 v65, 0x3f4c422a, v65
	v_add_f32_e32 v64, v64, v64
	v_add_f32_e32 v65, v65, v65
	v_mul_f32_e32 v64, 0xbfb8aa3b, v64
	v_mul_f32_e32 v65, 0xbfb8aa3b, v65
	v_exp_f32_e32 v64, v64
	v_exp_f32_e32 v65, v65
	v_add_f32_e32 v64, 1.0, v64
	v_add_f32_e32 v65, 1.0, v65
	v_rcp_f32_e32 v64, v64
	v_rcp_f32_e32 v65, v65
	s_nop 0
	v_pk_mul_f32 v[64:65], v[66:67], v[64:65]
	s_nop 0
	v_cvt_pk_bf16_f32 v71, v64, v65
	v_lshl_add_u64 v[64:65], v[72:73], 0, v[168:169]
	global_store_dwordx4 v[64:65], v[68:71], off offset:256 nt
.LBB0_614:
	v_add_u32_e32 v66, 0xa0, v198
	v_ashrrev_i32_e32 v67, 31, v66
	v_lshlrev_b64 v[64:65], 10, v[66:67]
	v_pk_fma_f32 v[68:69], v[54:55], v[200:201], v[46:47] op_sel_hi:[1,0,1]
	v_pk_fma_f32 v[70:71], v[52:53], v[200:201], v[44:45] op_sel_hi:[1,0,1]
	v_pk_fma_f32 v[52:53], v[50:51], v[200:201], v[42:43] op_sel_hi:[1,0,1]
	v_pk_fma_f32 v[54:55], v[48:49], v[200:201], v[40:41] op_sel_hi:[1,0,1]
	s_and_b64 vcc, exec, s[10:11]
	s_mov_b64 s[0:1], -1
	s_cbranch_vccnz .LBB0_634
	s_and_b64 vcc, exec, s[8:9]
	s_cbranch_vccnz .LBB0_631
	v_cndmask_b32_e64 v48, 0, 1, s[48:49]
	v_cmp_ne_u32_e64 s[0:1], 1, v48
	s_andn2_b64 vcc, exec, s[48:49]
	s_cbranch_vccnz .LBB0_620
	s_mov_b64 s[12:13], -1
	s_and_b64 vcc, exec, s[46:47]
	s_cbranch_vccz .LBB0_619
	v_or_b32_e32 v72, s75, v184
	v_lshrrev_b32_e32 v72, 4, v72
	s_mov_b32 s12, 0x8400
	v_mad_u64_u32 v[72:73], s[12:13], v72, s12, v[66:67]
	v_lshlrev_b64 v[72:73], 5, v[72:73]
	v_cvt_pk_bf16_f32 v48, v70, v71
	v_cvt_pk_bf16_f32 v49, v68, v69
	v_cvt_pk_bf16_f32 v50, v54, v55
	v_cvt_pk_bf16_f32 v51, v52, v53
	v_lshl_add_u64 v[72:73], v[186:187], 0, v[72:73]
	s_mov_b64 s[12:13], 0
	global_store_dwordx4 v[72:73], v[48:51], off nt

; __device__ __forceinline__ unsigned pk2(float lo, float hi) { const f32x2 v = {lo, hi}; return __builtin_bit_cast(unsigned, __builtin_convertvector(v, bf16x2_t)); }
;     __device__ __forceinline__ void operator()(const f32x4 (&acc)[2][2][4][2], const Unit& un, int wr, int wc, int fr, int fq) const {
;     ...
;                 const bool isq = pn < 10; const int cs = isq ? (pn - 8) * 256 + ct : ct;
;                 float x[8] = {v0.x, v0.y, v0.z, v0.w, v1.x, v1.y, v1.z, v1.w};
;                 if (lat) { const f32x4 ra = rp[m][0], rb = rp[m][1]; const float cc[4] = {ra.x, ra.z, rb.x, rb.z}, sn[4] = {ra.y, ra.w, rb.y, rb.w};
; #pragma unroll
;                     for (int jj = 0; jj < 4; ++jj) { const float x1 = x[2 * jj], x2 = x[2 * jj + 1]; x[2 * jj] = x1 * cc[jj] - x2 * sn[jj]; x[2 * jj + 1] = x1 * sn[jj] + x2 * cc[jj]; } }
;                 const float sc = isq ? QSCALE : 1.f;
;                 u32x4 w; w.x = pk2(x[0] * sc, x[1] * sc); w.y = pk2(x[2] * sc, x[3] * sc); w.z = pk2(x[4] * sc, x[5] * sc); w.w = pk2(x[6] * sc, x[7] * sc);
;                 if (isq) *(u32x4*)(q + (size_t)row * 512 + cs) = w; else *(u32x4*)(k + (size_t)row * 128 + cs) = w;
.LBB0_626:
	v_pk_mul_f32 v[48:49], v[196:197], v[48:49] op_sel_hi:[0,1]
	v_pk_mul_f32 v[50:51], v[196:197], v[50:51] op_sel_hi:[0,1]
	v_cvt_pk_bf16_f32 v48, v48, v49
	v_cvt_pk_bf16_f32 v49, v50, v51
	v_pk_mul_f32 v[50:51], v[196:197], v[72:73] op_sel_hi:[0,1]
	v_pk_mul_f32 v[72:73], v[196:197], v[74:75] op_sel_hi:[0,1]
	v_cvt_pk_bf16_f32 v50, v50, v51
	v_cvt_pk_bf16_f32 v51, v72, v73
	s_and_b64 vcc, exec, s[0:1]
	s_mov_b64 s[0:1], -1
	s_cbranch_vccnz .LBB0_628
	v_lshlrev_b64 v[72:73], 8, v[66:67]
	v_lshl_add_u64 v[72:73], s[22:23], 0, v[72:73]
	v_lshl_add_u64 v[72:73], v[208:209], 1, v[72:73]
	s_mov_b64 s[0:1], 0
	global_store_dwordx4 v[72:73], v[48:51], off nt
.LBB0_628:
	s_andn2_b64 vcc, exec, s[0:1]
	s_cbranch_vccnz .LBB0_630
	v_lshl_add_u64 v[72:73], s[20:21], 0, v[64:65]
	v_lshl_add_u64 v[72:73], v[208:209], 1, v[72:73]
	global_store_dwordx4 v[72:73], v[48:51], off nt

; __device__ __forceinline__ unsigned f2bf(float f) { return pk2(f, f) & 0xffffu; }
;     __device__ __forceinline__ void operator()(const f32x4 (&acc)[2][2][4][2], const Unit& un, int wr, int wc, int fr, int fq) const {
;     ...
;             const int row = rbase + ai * 128 + m * 16; const int ct = bj * 128 + cw;
;             const f32x4 v0 = acc[ai][bj][m][0] * rr[ai][m] + s0[bj], v1 = acc[ai][bj][m][1] * rr[ai][m] + s1[bj];
;             if (pn < 4) {
;                 u32x4 w; w.x = pk2(gelu_tanh(v0.x), gelu_tanh(v0.y)); w.y = pk2(gelu_tanh(v0.z), gelu_tanh(v0.w)); w.z = pk2(gelu_tanh(v1.x), gelu_tanh(v1.y)); w.w = pk2(gelu_tanh(v1.z), gelu_tanh(v1.w));
;                 *(u32x4*)(ga + (size_t)row * 1024 + pn * 256 + ct) = w;
;             } else if (pn < 8) {
;                 u32x2 w; w.x = pk2(v0.x * sigmoidf_(v0.y), v0.z * sigmoidf_(v0.w)); w.y = pk2(v1.x * sigmoidf_(v1.y), v1.z * sigmoidf_(v1.w));
;                 *(u32x2*)(yb + (size_t)row * 512 + (((pn - 4) * 256 + ct) >> 1)) = w;
;             } else if (pn < 10 || (pn == 10 && bj == 0)) {
;                 const bool isq = pn < 10; const int cs = isq ? (pn - 8) * 256 + ct : ct;
;                 float x[8] = {v0.x, v0.y, v0.z, v0.w, v1.x, v1.y, v1.z, v1.w};
;                 if (lat) { const f32x4 ra = rp[m][0], rb = rp[m][1]; const float cc[4] = {ra.x, ra.z, rb.x, rb.z}, sn[4] = {ra.y, ra.w, rb.y, rb.w};
; #pragma unroll
;                     for (int jj = 0; jj < 4; ++jj) { const float x1 = x[2 * jj], x2 = x[2 * jj + 1]; x[2 * jj] = x1 * cc[jj] - x2 * sn[jj]; x[2 * jj + 1] = x1 * sn[jj] + x2 * cc[jj]; } }
;                 const float sc = isq ? QSCALE : 1.f;
;                 u32x4 w; w.x = pk2(x[0] * sc, x[1] * sc); w.y = pk2(x[2] * sc, x[3] * sc); w.z = pk2(x[4] * sc, x[5] * sc); w.w = pk2(x[6] * sc, x[7] * sc);
;                 if (isq) *(u32x4*)(q + (size_t)row * 512 + cs) = w; else *(u32x4*)(k + (size_t)row * 128 + cs) = w;
;             } else if (pn == 10) {
;                 const int dc = ct - 128; const float x[8] = {v0.x, v0.y, v0.z, v0.w, v1.x, v1.y, v1.z, v1.w};
;                 if (lat) { const int b = row >> 13, t = row & (SEQ - 1);
; #pragma unroll
;                     for (int e = 0; e < 8; ++e) vT[((size_t)(b * 128 + dc + e)) * SEQ + t] = (bf16)f2bf(x[e]); }
;                 else { const int rc = row - NLAT, b = rc >> 8, t = rc & 255;
; #pragma unroll
.LBB0_634:
	v_lshlrev_b64 v[48:49], 11, v[66:67]
	v_lshl_add_u64 v[48:49], s[16:17], 0, v[48:49]
	s_andn2_b64 vcc, exec, s[0:1]
	v_lshl_add_u64 v[48:49], s[50:51], 1, v[48:49]
	s_cbranch_vccnz .LBB0_636
	v_mul_f32_e32 v50, 0x3d372713, v70
	v_mul_f32_e32 v51, 0x3d372713, v71
	v_mul_f32_e32 v50, v70, v50
	v_mul_f32_e32 v51, v71, v51
	v_mov_b32_e32 v72, v71
	v_fma_f32 v50, v70, v50, v70
	v_fmac_f32_e32 v72, v72, v51
	v_mul_f32_e32 v50, 0x3f4c422a, v50
	v_mul_f32_e32 v51, 0x3f4c422a, v72
	v_add_f32_e32 v50, v50, v50
	v_add_f32_e32 v51, v51, v51
	v_mul_f32_e32 v50, 0xbfb8aa3b, v50
	v_mul_f32_e32 v51, 0xbfb8aa3b, v51
	v_exp_f32_e32 v50, v50
	v_exp_f32_e32 v51, v51
	v_mov_b32_e32 v169, v209
	v_add_f32_e32 v50, 1.0, v50
	v_add_f32_e32 v51, 1.0, v51
	v_rcp_f32_e32 v50, v50
	v_rcp_f32_e32 v51, v51
	s_nop 0
	v_pk_mul_f32 v[50:51], v[70:71], v[50:51]
	s_nop 0
	v_cvt_pk_bf16_f32 v70, v50, v51
	v_mul_f32_e32 v50, 0x3d372713, v68
	v_mul_f32_e32 v51, 0x3d372713, v69
	v_mul_f32_e32 v50, v68, v50
	v_mul_f32_e32 v51, v69, v51
	v_fma_f32 v50, v68, v50, v68
	v_fma_f32 v51, v69, v51, v69
	v_mul_f32_e32 v50, 0x3f4c422a, v50
	v_mul_f32_e32 v51, 0x3f4c422a, v51
	v_add_f32_e32 v50, v50, v50
	v_add_f32_e32 v51, v51, v51
	v_mul_f32_e32 v50, 0xbfb8aa3b, v50
	v_mul_f32_e32 v51, 0xbfb8aa3b, v51
	v_exp_f32_e32 v50, v50
	v_exp_f32_e32 v51, v51
	v_add_f32_e32 v50, 1.0, v50
	v_add_f32_e32 v51, 1.0, v51
	v_rcp_f32_e32 v50, v50
	v_rcp_f32_e32 v51, v51
	s_nop 0
	v_pk_mul_f32 v[50:51], v[68:69], v[50:51]
	s_nop 0
	v_cvt_pk_bf16_f32 v71, v50, v51
	v_mul_f32_e32 v50, 0x3d372713, v54
	v_mul_f32_e32 v51, 0x3d372713, v55
	v_mul_f32_e32 v50, v54, v50
	v_mul_f32_e32 v51, v55, v51
	v_mov_b32_e32 v68, v55
	v_fma_f32 v50, v54, v50, v54
	v_fmac_f32_e32 v68, v68, v51
	v_mul_f32_e32 v50, 0x3f4c422a, v50
	v_mul_f32_e32 v51, 0x3f4c422a, v68
	v_add_f32_e32 v50, v50, v50
	v_add_f32_e32 v51, v51, v51
	v_mul_f32_e32 v50, 0xbfb8aa3b, v50
	v_mul_f32_e32 v51, 0xbfb8aa3b, v51
	v_exp_f32_e32 v50, v50
	v_exp_f32_e32 v51, v51
	v_add_f32_e32 v50, 1.0, v50
	v_add_f32_e32 v51, 1.0, v51
	v_rcp_f32_e32 v50, v50
	v_rcp_f32_e32 v51, v51
	s_nop 0
	v_pk_mul_f32 v[50:51], v[54:55], v[50:51]
	s_nop 0
	v_cvt_pk_bf16_f32 v72, v50, v51
	v_mul_f32_e32 v50, 0x3d372713, v52
	v_mul_f32_e32 v51, 0x3d372713, v53
	v_mul_f32_e32 v50, v52, v50
	v_mul_f32_e32 v51, v53, v51
	v_fma_f32 v50, v52, v50, v52
	v_fma_f32 v51, v53, v51, v53
	v_mul_f32_e32 v50, 0x3f4c422a, v50
	v_mul_f32_e32 v51, 0x3f4c422a, v51
	v_add_f32_e32 v50, v50, v50
	v_add_f32_e32 v51, v51, v51
	v_mul_f32_e32 v50, 0xbfb8aa3b, v50
	v_mul_f32_e32 v51, 0xbfb8aa3b, v51
	v_exp_f32_e32 v50, v50
	v_exp_f32_e32 v51, v51
	v_add_f32_e32 v50, 1.0, v50
	v_add_f32_e32 v51, 1.0, v51
	v_rcp_f32_e32 v50, v50
	v_rcp_f32_e32 v51, v51
	s_nop 0
	v_pk_mul_f32 v[50:51], v[52:53], v[50:51]
	s_nop 0
	v_cvt_pk_bf16_f32 v73, v50, v51
	v_lshl_add_u64 v[50:51], v[48:49], 0, v[168:169]
	global_store_dwordx4 v[50:51], v[70:73], off nt
.LBB0_636:
	v_mov_b32_e32 v201, v200
	v_mov_b32_e32 v50, v200
	v_mov_b32_e32 v51, v200
	v_pk_fma_f32 v[38:39], v[38:39], v[50:51], v[30:31]
	v_pk_fma_f32 v[36:37], v[36:37], v[200:201], v[28:29]
	v_pk_fma_f32 v[34:35], v[34:35], v[50:51], v[26:27]
	v_pk_fma_f32 v[32:33], v[32:33], v[200:201], v[24:25]
	s_and_b64 vcc, exec, s[10:11]
	s_mov_b64 s[0:1], -1
	s_cbranch_vccnz .LBB0_656
	s_and_b64 vcc, exec, s[8:9]
	s_cbranch_vccnz .LBB0_653
	s_andn2_b64 vcc, exec, s[48:49]
	s_cbranch_vccnz .LBB0_647
	s_andn2_b64 vcc, exec, s[46:47]
	s_cbranch_vccnz .LBB0_641
	v_or_b32_e32 v54, s75, v239
	v_lshrrev_b32_e32 v54, 4, v54
	s_mov_b32 s0, 0x8400
	v_mad_u64_u32 v[54:55], s[0:1], v54, s0, v[66:67]
	v_lshlrev_b64 v[54:55], 5, v[54:55]
	v_cvt_pk_bf16_f32 v50, v36, v37
	v_cvt_pk_bf16_f32 v51, v38, v39
	v_cvt_pk_bf16_f32 v52, v32, v33
	v_cvt_pk_bf16_f32 v53, v34, v35
	v_lshl_add_u64 v[54:55], v[186:187], 0, v[54:55]
	s_mov_b64 s[0:1], 0
	global_store_dwordx4 v[54:55], v[50:53], off nt

; __device__ __forceinline__ unsigned pk2(float lo, float hi) { const f32x2 v = {lo, hi}; return __builtin_bit_cast(unsigned, __builtin_convertvector(v, bf16x2_t)); }
;     __device__ __forceinline__ void operator()(const f32x4 (&acc)[2][2][4][2], const Unit& un, int wr, int wc, int fr, int fq) const {
;     ...
;                 const bool isq = pn < 10; const int cs = isq ? (pn - 8) * 256 + ct : ct;
;                 float x[8] = {v0.x, v0.y, v0.z, v0.w, v1.x, v1.y, v1.z, v1.w};
;                 if (lat) { const f32x4 ra = rp[m][0], rb = rp[m][1]; const float cc[4] = {ra.x, ra.z, rb.x, rb.z}, sn[4] = {ra.y, ra.w, rb.y, rb.w};
; #pragma unroll
;                     for (int jj = 0; jj < 4; ++jj) { const float x1 = x[2 * jj], x2 = x[2 * jj + 1]; x[2 * jj] = x1 * cc[jj] - x2 * sn[jj]; x[2 * jj + 1] = x1 * sn[jj] + x2 * cc[jj]; } }
;                 const float sc = isq ? QSCALE : 1.f;
;                 u32x4 w; w.x = pk2(x[0] * sc, x[1] * sc); w.y = pk2(x[2] * sc, x[3] * sc); w.z = pk2(x[4] * sc, x[5] * sc); w.w = pk2(x[6] * sc, x[7] * sc);
;                 if (isq) *(u32x4*)(q + (size_t)row * 512 + cs) = w; else *(u32x4*)(k + (size_t)row * 128 + cs) = w;
.LBB0_651:
	s_mov_b32 s0, 0x3e38aa3b
	v_pk_mul_f32 v[50:51], v[50:51], s[0:1] op_sel_hi:[1,0]
	v_pk_mul_f32 v[52:53], v[52:53], s[0:1] op_sel_hi:[1,0]
	v_cvt_pk_bf16_f32 v50, v50, v51
	v_cvt_pk_bf16_f32 v51, v52, v53
	v_pk_mul_f32 v[52:53], v[54:55], s[0:1] op_sel_hi:[1,0]
	v_pk_mul_f32 v[54:55], v[56:57], s[0:1] op_sel_hi:[1,0]
	v_cvt_pk_bf16_f32 v52, v52, v53
	v_cvt_pk_bf16_f32 v53, v54, v55
	v_lshl_add_u64 v[54:55], s[20:21], 0, v[64:65]
	v_add_u32_e32 v208, s37, v184
	v_lshl_add_u64 v[54:55], v[208:209], 1, v[54:55]
	global_store_dwordx4 v[54:55], v[50:53], off offset:256 nt

; __device__ __forceinline__ unsigned f2bf(float f) { return pk2(f, f) & 0xffffu; }
;     __device__ __forceinline__ void operator()(const f32x4 (&acc)[2][2][4][2], const Unit& un, int wr, int wc, int fr, int fq) const {
;     ...
;             const int row = rbase + ai * 128 + m * 16; const int ct = bj * 128 + cw;
;             const f32x4 v0 = acc[ai][bj][m][0] * rr[ai][m] + s0[bj], v1 = acc[ai][bj][m][1] * rr[ai][m] + s1[bj];
;             if (pn < 4) {
;                 u32x4 w; w.x = pk2(gelu_tanh(v0.x), gelu_tanh(v0.y)); w.y = pk2(gelu_tanh(v0.z), gelu_tanh(v0.w)); w.z = pk2(gelu_tanh(v1.x), gelu_tanh(v1.y)); w.w = pk2(gelu_tanh(v1.z), gelu_tanh(v1.w));
;                 *(u32x4*)(ga + (size_t)row * 1024 + pn * 256 + ct) = w;
;             } else if (pn < 8) {
;                 u32x2 w; w.x = pk2(v0.x * sigmoidf_(v0.y), v0.z * sigmoidf_(v0.w)); w.y = pk2(v1.x * sigmoidf_(v1.y), v1.z * sigmoidf_(v1.w));
;                 *(u32x2*)(yb + (size_t)row * 512 + (((pn - 4) * 256 + ct) >> 1)) = w;
;             } else if (pn < 10 || (pn == 10 && bj == 0)) {
;                 const bool isq = pn < 10; const int cs = isq ? (pn - 8) * 256 + ct : ct;
;                 float x[8] = {v0.x, v0.y, v0.z, v0.w, v1.x, v1.y, v1.z, v1.w};
;                 if (lat) { const f32x4 ra = rp[m][0], rb = rp[m][1]; const float cc[4] = {ra.x, ra.z, rb.x, rb.z}, sn[4] = {ra.y, ra.w, rb.y, rb.w};
; #pragma unroll
;                     for (int jj = 0; jj < 4; ++jj) { const float x1 = x[2 * jj], x2 = x[2 * jj + 1]; x[2 * jj] = x1 * cc[jj] - x2 * sn[jj]; x[2 * jj + 1] = x1 * sn[jj] + x2 * cc[jj]; } }
;                 const float sc = isq ? QSCALE : 1.f;
;                 u32x4 w; w.x = pk2(x[0] * sc, x[1] * sc); w.y = pk2(x[2] * sc, x[3] * sc); w.z = pk2(x[4] * sc, x[5] * sc); w.w = pk2(x[6] * sc, x[7] * sc);
;                 if (isq) *(u32x4*)(q + (size_t)row * 512 + cs) = w; else *(u32x4*)(k + (size_t)row * 128 + cs) = w;
;             } else if (pn == 10) {
;                 const int dc = ct - 128; const float x[8] = {v0.x, v0.y, v0.z, v0.w, v1.x, v1.y, v1.z, v1.w};
;                 if (lat) { const int b = row >> 13, t = row & (SEQ - 1);
; #pragma unroll
;                     for (int e = 0; e < 8; ++e) vT[((size_t)(b * 128 + dc + e)) * SEQ + t] = (bf16)f2bf(x[e]); }
;                 else { const int rc = row - NLAT, b = rc >> 8, t = rc & 255;
; #pragma unroll
.LBB0_656:
	s_andn2_b64 vcc, exec, s[0:1]
	s_cbranch_vccnz .LBB0_658
	v_mul_f32_e32 v50, 0x3d372713, v36
	v_mul_f32_e32 v51, 0x3d372713, v37
	v_mul_f32_e32 v50, v36, v50
	v_mul_f32_e32 v51, v37, v51
	v_mov_b32_e32 v52, v37
	v_fma_f32 v50, v36, v50, v36
	v_fmac_f32_e32 v52, v52, v51
	v_mul_f32_e32 v50, 0x3f4c422a, v50
	v_mul_f32_e32 v51, 0x3f4c422a, v52
	v_add_f32_e32 v50, v50, v50
	v_add_f32_e32 v51, v51, v51
	v_mul_f32_e32 v50, 0xbfb8aa3b, v50
	v_mul_f32_e32 v51, 0xbfb8aa3b, v51
	v_exp_f32_e32 v50, v50
	v_exp_f32_e32 v51, v51
	v_mov_b32_e32 v169, v209
	v_add_f32_e32 v50, 1.0, v50
	v_add_f32_e32 v51, 1.0, v51
	v_rcp_f32_e32 v50, v50
	v_rcp_f32_e32 v51, v51
	s_nop 0
	v_pk_mul_f32 v[36:37], v[36:37], v[50:51]
	s_nop 0
	v_cvt_pk_bf16_f32 v36, v36, v37
	v_mul_f32_e32 v37, 0x3d372713, v38
	v_mul_f32_e32 v37, v38, v37
	v_fma_f32 v37, v38, v37, v38
	v_mul_f32_e32 v37, 0x3f4c422a, v37
	v_add_f32_e32 v37, v37, v37
	v_mul_f32_e32 v37, 0xbfb8aa3b, v37
	v_exp_f32_e32 v37, v37
	s_nop 0
	v_add_f32_e32 v37, 1.0, v37
	v_rcp_f32_e32 v50, v37
	v_mul_f32_e32 v37, 0x3d372713, v39
	v_mul_f32_e32 v37, v39, v37
	v_fma_f32 v37, v39, v37, v39
	v_mul_f32_e32 v37, 0x3f4c422a, v37
	v_add_f32_e32 v37, v37, v37
	v_mul_f32_e32 v37, 0xbfb8aa3b, v37
	v_exp_f32_e32 v37, v37
	s_nop 0
	v_add_f32_e32 v37, 1.0, v37
	v_rcp_f32_e32 v51, v37
	s_nop 0
	v_pk_mul_f32 v[38:39], v[38:39], v[50:51]
	s_nop 0
	v_cvt_pk_bf16_f32 v37, v38, v39
	v_mul_f32_e32 v38, 0x3d372713, v32
	v_mul_f32_e32 v39, 0x3d372713, v33
	v_mul_f32_e32 v38, v32, v38
	v_mul_f32_e32 v39, v33, v39
	v_mov_b32_e32 v50, v33
	v_fma_f32 v38, v32, v38, v32
	v_fmac_f32_e32 v50, v50, v39
	v_mul_f32_e32 v38, 0x3f4c422a, v38
	v_mul_f32_e32 v39, 0x3f4c422a, v50
	v_add_f32_e32 v38, v38, v38
	v_add_f32_e32 v39, v39, v39
	v_mul_f32_e32 v38, 0xbfb8aa3b, v38
	v_mul_f32_e32 v39, 0xbfb8aa3b, v39
	v_exp_f32_e32 v38, v38
	v_exp_f32_e32 v39, v39
	v_add_f32_e32 v38, 1.0, v38
	v_add_f32_e32 v39, 1.0, v39
	v_rcp_f32_e32 v38, v38
	v_rcp_f32_e32 v39, v39
	s_nop 0
	v_pk_mul_f32 v[32:33], v[32:33], v[38:39]
	s_nop 0
	v_cvt_pk_bf16_f32 v38, v32, v33
	v_mul_f32_e32 v32, 0x3d372713, v34
	v_mul_f32_e32 v33, 0x3d372713, v35
	v_mul_f32_e32 v32, v34, v32
	v_mul_f32_e32 v33, v35, v33
	v_fma_f32 v32, v34, v32, v34
	v_fma_f32 v33, v35, v33, v35
	v_mul_f32_e32 v32, 0x3f4c422a, v32
	v_mul_f32_e32 v33, 0x3f4c422a, v33
	v_add_f32_e32 v32, v32, v32
	v_add_f32_e32 v33, v33, v33
	v_mul_f32_e32 v32, 0xbfb8aa3b, v32
	v_mul_f32_e32 v33, 0xbfb8aa3b, v33
	v_exp_f32_e32 v32, v32
	v_exp_f32_e32 v33, v33
	v_add_f32_e32 v32, 1.0, v32
	v_add_f32_e32 v33, 1.0, v33
	v_rcp_f32_e32 v32, v32
	v_rcp_f32_e32 v33, v33
	s_nop 0
	v_pk_mul_f32 v[32:33], v[34:35], v[32:33]
	s_nop 0
	v_cvt_pk_bf16_f32 v39, v32, v33
	v_lshl_add_u64 v[32:33], v[48:49], 0, v[168:169]
	global_store_dwordx4 v[32:33], v[36:39], off offset:256 nt
.LBB0_658:
	v_add_u32_e32 v34, 0xb0, v198
	v_ashrrev_i32_e32 v35, 31, v34
	v_lshlrev_b64 v[32:33], 10, v[34:35]
	v_pk_fma_f32 v[36:37], v[14:15], v[194:195], v[46:47] op_sel_hi:[1,0,1]
	v_pk_fma_f32 v[38:39], v[12:13], v[194:195], v[44:45] op_sel_hi:[1,0,1]
	v_pk_fma_f32 v[12:13], v[10:11], v[194:195], v[42:43] op_sel_hi:[1,0,1]
	v_pk_fma_f32 v[14:15], v[8:9], v[194:195], v[40:41] op_sel_hi:[1,0,1]
	s_and_b64 vcc, exec, s[10:11]
	s_mov_b64 s[0:1], -1
	s_cbranch_vccnz .LBB0_678
	s_and_b64 vcc, exec, s[8:9]
	s_cbranch_vccnz .LBB0_675
	v_cndmask_b32_e64 v8, 0, 1, s[48:49]
	v_cmp_ne_u32_e64 s[0:1], 1, v8
	s_andn2_b64 vcc, exec, s[48:49]
	s_cbranch_vccnz .LBB0_664
	s_mov_b64 s[12:13], -1
	s_and_b64 vcc, exec, s[46:47]
	s_cbranch_vccz .LBB0_663
	v_or_b32_e32 v40, s75, v184
	v_lshrrev_b32_e32 v40, 4, v40
	s_mov_b32 s12, 0x8400
	v_mad_u64_u32 v[40:41], s[12:13], v40, s12, v[34:35]
	v_lshlrev_b64 v[40:41], 5, v[40:41]
	v_cvt_pk_bf16_f32 v8, v38, v39
	v_cvt_pk_bf16_f32 v9, v36, v37
	v_cvt_pk_bf16_f32 v10, v14, v15
	v_cvt_pk_bf16_f32 v11, v12, v13
	v_lshl_add_u64 v[40:41], v[186:187], 0, v[40:41]
	s_mov_b64 s[12:13], 0
	global_store_dwordx4 v[40:41], v[8:11], off nt

; __device__ __forceinline__ unsigned pk2(float lo, float hi) { const f32x2 v = {lo, hi}; return __builtin_bit_cast(unsigned, __builtin_convertvector(v, bf16x2_t)); }
;     __device__ __forceinline__ void operator()(const f32x4 (&acc)[2][2][4][2], const Unit& un, int wr, int wc, int fr, int fq) const {
;     ...
;                 const bool isq = pn < 10; const int cs = isq ? (pn - 8) * 256 + ct : ct;
;                 float x[8] = {v0.x, v0.y, v0.z, v0.w, v1.x, v1.y, v1.z, v1.w};
;                 if (lat) { const f32x4 ra = rp[m][0], rb = rp[m][1]; const float cc[4] = {ra.x, ra.z, rb.x, rb.z}, sn[4] = {ra.y, ra.w, rb.y, rb.w};
; #pragma unroll
;                     for (int jj = 0; jj < 4; ++jj) { const float x1 = x[2 * jj], x2 = x[2 * jj + 1]; x[2 * jj] = x1 * cc[jj] - x2 * sn[jj]; x[2 * jj + 1] = x1 * sn[jj] + x2 * cc[jj]; } }
;                 const float sc = isq ? QSCALE : 1.f;
;                 u32x4 w; w.x = pk2(x[0] * sc, x[1] * sc); w.y = pk2(x[2] * sc, x[3] * sc); w.z = pk2(x[4] * sc, x[5] * sc); w.w = pk2(x[6] * sc, x[7] * sc);
;                 if (isq) *(u32x4*)(q + (size_t)row * 512 + cs) = w; else *(u32x4*)(k + (size_t)row * 128 + cs) = w;
.LBB0_670:
	v_pk_mul_f32 v[8:9], v[196:197], v[8:9] op_sel_hi:[0,1]
	v_pk_mul_f32 v[10:11], v[196:197], v[10:11] op_sel_hi:[0,1]
	v_cvt_pk_bf16_f32 v8, v8, v9
	v_cvt_pk_bf16_f32 v9, v10, v11
	v_pk_mul_f32 v[10:11], v[196:197], v[40:41] op_sel_hi:[0,1]
	v_pk_mul_f32 v[40:41], v[196:197], v[42:43] op_sel_hi:[0,1]
	v_cvt_pk_bf16_f32 v10, v10, v11
	v_cvt_pk_bf16_f32 v11, v40, v41
	s_and_b64 vcc, exec, s[0:1]
	s_mov_b64 s[0:1], -1
	s_cbranch_vccnz .LBB0_672
	v_lshlrev_b64 v[40:41], 8, v[34:35]
	v_lshl_add_u64 v[40:41], s[22:23], 0, v[40:41]
	v_lshl_add_u64 v[40:41], v[208:209], 1, v[40:41]
	s_mov_b64 s[0:1], 0
	global_store_dwordx4 v[40:41], v[8:11], off nt
.LBB0_672:
	s_andn2_b64 vcc, exec, s[0:1]
	s_cbranch_vccnz .LBB0_674
	v_lshl_add_u64 v[40:41], s[20:21], 0, v[32:33]
	v_lshl_add_u64 v[40:41], v[208:209], 1, v[40:41]
	global_store_dwordx4 v[40:41], v[8:11], off nt

; __device__ __forceinline__ unsigned f2bf(float f) { return pk2(f, f) & 0xffffu; }
;     __device__ __forceinline__ void operator()(const f32x4 (&acc)[2][2][4][2], const Unit& un, int wr, int wc, int fr, int fq) const {
;     ...
;             const int row = rbase + ai * 128 + m * 16; const int ct = bj * 128 + cw;
;             const f32x4 v0 = acc[ai][bj][m][0] * rr[ai][m] + s0[bj], v1 = acc[ai][bj][m][1] * rr[ai][m] + s1[bj];
;             if (pn < 4) {
;                 u32x4 w; w.x = pk2(gelu_tanh(v0.x), gelu_tanh(v0.y)); w.y = pk2(gelu_tanh(v0.z), gelu_tanh(v0.w)); w.z = pk2(gelu_tanh(v1.x), gelu_tanh(v1.y)); w.w = pk2(gelu_tanh(v1.z), gelu_tanh(v1.w));
;                 *(u32x4*)(ga + (size_t)row * 1024 + pn * 256 + ct) = w;
;             } else if (pn < 8) {
;                 u32x2 w; w.x = pk2(v0.x * sigmoidf_(v0.y), v0.z * sigmoidf_(v0.w)); w.y = pk2(v1.x * sigmoidf_(v1.y), v1.z * sigmoidf_(v1.w));
;                 *(u32x2*)(yb + (size_t)row * 512 + (((pn - 4) * 256 + ct) >> 1)) = w;
;             } else if (pn < 10 || (pn == 10 && bj == 0)) {
;                 const bool isq = pn < 10; const int cs = isq ? (pn - 8) * 256 + ct : ct;
;                 float x[8] = {v0.x, v0.y, v0.z, v0.w, v1.x, v1.y, v1.z, v1.w};
;                 if (lat) { const f32x4 ra = rp[m][0], rb = rp[m][1]; const float cc[4] = {ra.x, ra.z, rb.x, rb.z}, sn[4] = {ra.y, ra.w, rb.y, rb.w};
; #pragma unroll
;                     for (int jj = 0; jj < 4; ++jj) { const float x1 = x[2 * jj], x2 = x[2 * jj + 1]; x[2 * jj] = x1 * cc[jj] - x2 * sn[jj]; x[2 * jj + 1] = x1 * sn[jj] + x2 * cc[jj]; } }
;                 const float sc = isq ? QSCALE : 1.f;
;                 u32x4 w; w.x = pk2(x[0] * sc, x[1] * sc); w.y = pk2(x[2] * sc, x[3] * sc); w.z = pk2(x[4] * sc, x[5] * sc); w.w = pk2(x[6] * sc, x[7] * sc);
;                 if (isq) *(u32x4*)(q + (size_t)row * 512 + cs) = w; else *(u32x4*)(k + (size_t)row * 128 + cs) = w;
;             } else if (pn == 10) {
;                 const int dc = ct - 128; const float x[8] = {v0.x, v0.y, v0.z, v0.w, v1.x, v1.y, v1.z, v1.w};
;                 if (lat) { const int b = row >> 13, t = row & (SEQ - 1);
; #pragma unroll
;                     for (int e = 0; e < 8; ++e) vT[((size_t)(b * 128 + dc + e)) * SEQ + t] = (bf16)f2bf(x[e]); }
;                 else { const int rc = row - NLAT, b = rc >> 8, t = rc & 255;
; #pragma unroll
.LBB0_678:
	v_lshlrev_b64 v[8:9], 11, v[34:35]
	v_lshl_add_u64 v[8:9], s[16:17], 0, v[8:9]
	s_andn2_b64 vcc, exec, s[0:1]
	v_lshl_add_u64 v[8:9], s[50:51], 1, v[8:9]
	s_cbranch_vccnz .LBB0_680
	v_mul_f32_e32 v10, 0x3d372713, v38
	v_mul_f32_e32 v11, 0x3d372713, v39
	v_mul_f32_e32 v10, v38, v10
	v_mul_f32_e32 v11, v39, v11
	v_mov_b32_e32 v40, v39
	v_fma_f32 v10, v38, v10, v38
	v_fmac_f32_e32 v40, v40, v11
	v_mul_f32_e32 v10, 0x3f4c422a, v10
	v_mul_f32_e32 v11, 0x3f4c422a, v40
	v_add_f32_e32 v10, v10, v10
	v_add_f32_e32 v11, v11, v11
	v_mul_f32_e32 v10, 0xbfb8aa3b, v10
	v_mul_f32_e32 v11, 0xbfb8aa3b, v11
	v_exp_f32_e32 v10, v10
	v_exp_f32_e32 v11, v11
	v_mov_b32_e32 v169, v209
	v_add_f32_e32 v10, 1.0, v10
	v_add_f32_e32 v11, 1.0, v11
	v_rcp_f32_e32 v10, v10
	v_rcp_f32_e32 v11, v11
	s_nop 0
	v_pk_mul_f32 v[10:11], v[38:39], v[10:11]
	s_nop 0
	v_cvt_pk_bf16_f32 v38, v10, v11
	v_mul_f32_e32 v10, 0x3d372713, v36
	v_mul_f32_e32 v11, 0x3d372713, v37
	v_mul_f32_e32 v10, v36, v10
	v_mul_f32_e32 v11, v37, v11
	v_fma_f32 v10, v36, v10, v36
	v_fma_f32 v11, v37, v11, v37
	v_mul_f32_e32 v10, 0x3f4c422a, v10
	v_mul_f32_e32 v11, 0x3f4c422a, v11
	v_add_f32_e32 v10, v10, v10
	v_add_f32_e32 v11, v11, v11
	v_mul_f32_e32 v10, 0xbfb8aa3b, v10
	v_mul_f32_e32 v11, 0xbfb8aa3b, v11
	v_exp_f32_e32 v10, v10
	v_exp_f32_e32 v11, v11
	v_add_f32_e32 v10, 1.0, v10
	v_add_f32_e32 v11, 1.0, v11
	v_rcp_f32_e32 v10, v10
	v_rcp_f32_e32 v11, v11
	s_nop 0
	v_pk_mul_f32 v[10:11], v[36:37], v[10:11]
	s_nop 0
	v_cvt_pk_bf16_f32 v39, v10, v11
	v_mul_f32_e32 v10, 0x3d372713, v14
	v_mul_f32_e32 v11, 0x3d372713, v15
	v_mul_f32_e32 v10, v14, v10
	v_mul_f32_e32 v11, v15, v11
	v_mov_b32_e32 v36, v15
	v_fma_f32 v10, v14, v10, v14
	v_fmac_f32_e32 v36, v36, v11
	v_mul_f32_e32 v10, 0x3f4c422a, v10
	v_mul_f32_e32 v11, 0x3f4c422a, v36
	v_add_f32_e32 v10, v10, v10
	v_add_f32_e32 v11, v11, v11
	v_mul_f32_e32 v10, 0xbfb8aa3b, v10
	v_mul_f32_e32 v11, 0xbfb8aa3b, v11
	v_exp_f32_e32 v10, v10
	v_exp_f32_e32 v11, v11
	v_add_f32_e32 v10, 1.0, v10
	v_add_f32_e32 v11, 1.0, v11
	v_rcp_f32_e32 v10, v10
	v_rcp_f32_e32 v11, v11
	s_nop 0
	v_pk_mul_f32 v[10:11], v[14:15], v[10:11]
	s_nop 0
	v_cvt_pk_bf16_f32 v40, v10, v11
	v_mul_f32_e32 v10, 0x3d372713, v12
	v_mul_f32_e32 v11, 0x3d372713, v13
	v_mul_f32_e32 v10, v12, v10
	v_mul_f32_e32 v11, v13, v11
	v_fma_f32 v10, v12, v10, v12
	v_fma_f32 v11, v13, v11, v13
	v_mul_f32_e32 v10, 0x3f4c422a, v10
	v_mul_f32_e32 v11, 0x3f4c422a, v11
	v_add_f32_e32 v10, v10, v10
	v_add_f32_e32 v11, v11, v11
	v_mul_f32_e32 v10, 0xbfb8aa3b, v10
	v_mul_f32_e32 v11, 0xbfb8aa3b, v11
	v_exp_f32_e32 v10, v10
	v_exp_f32_e32 v11, v11
	v_add_f32_e32 v10, 1.0, v10
	v_add_f32_e32 v11, 1.0, v11
	v_rcp_f32_e32 v10, v10
	v_rcp_f32_e32 v11, v11
	s_nop 0
	v_pk_mul_f32 v[10:11], v[12:13], v[10:11]
	s_nop 0
	v_cvt_pk_bf16_f32 v41, v10, v11
	v_lshl_add_u64 v[10:11], v[8:9], 0, v[168:169]
	global_store_dwordx4 v[10:11], v[38:41], off nt
.LBB0_680:
	v_mov_b32_e32 v195, v194
	v_mov_b32_e32 v10, v194
	v_mov_b32_e32 v11, v194
	v_pk_fma_f32 v[6:7], v[6:7], v[10:11], v[30:31]
	v_pk_fma_f32 v[4:5], v[4:5], v[194:195], v[28:29]
	v_pk_fma_f32 v[2:3], v[2:3], v[10:11], v[26:27]
	v_pk_fma_f32 v[0:1], v[0:1], v[194:195], v[24:25]
	s_and_b64 vcc, exec, s[10:11]
	s_mov_b64 s[0:1], -1
	s_cbranch_vccnz .LBB0_694
	s_and_b64 vcc, exec, s[8:9]
	s_cbranch_vccnz .LBB0_699
	s_andn2_b64 vcc, exec, s[48:49]
	s_cbranch_vccnz .LBB0_691
	s_andn2_b64 vcc, exec, s[46:47]
	s_cbranch_vccnz .LBB0_685
	v_or_b32_e32 v14, s75, v239
	v_lshrrev_b32_e32 v14, 4, v14
	s_mov_b32 s0, 0x8400
	v_mad_u64_u32 v[14:15], s[0:1], v14, s0, v[34:35]
	v_lshlrev_b64 v[14:15], 5, v[14:15]
	v_cvt_pk_bf16_f32 v10, v4, v5
	v_cvt_pk_bf16_f32 v11, v6, v7
	v_cvt_pk_bf16_f32 v12, v0, v1
	v_cvt_pk_bf16_f32 v13, v2, v3
	v_lshl_add_u64 v[14:15], v[186:187], 0, v[14:15]
	s_mov_b64 s[0:1], 0
	global_store_dwordx4 v[14:15], v[10:13], off nt

;     __host__ __device__ bool next(int i, Unit& u) const { const int L = base + i * Gp + cp; if (L >= end) return false; return T.next(L, u); }
;     __host__ __device__ bool next(int i, Unit& u) const { const int L = i * Gp + cp; if (cp < 0 || L >= n) return false; u.kb = L & 3; u.pn = (L >> 2) % nN; u.pm = pm0 + (L >> 2) / nN; return true; }
;     __host__ __device__ bool next(int i, Unit& u) const { const bool ok = T.next(i >> 2, u); u.kb = i & 3; return ok; }
; __device__ __forceinline__ unsigned pk2(float lo, float hi) { const f32x2 v = {lo, hi}; return __builtin_bit_cast(unsigned, __builtin_convertvector(v, bf16x2_t)); }
; __device__ __forceinline__ float gelu_tanh(float x) { const float y = 0.7978845608028654f * (x + 0.044715f * x * x * x); return x * sigmoidf_(2.f * y); }
; template <class Epi, class Sched, bool ALIGN_EPI = false, bool SP2 = false>
; __device__ __forceinline__ void gemm_phase(PG8_LAS unsigned char* lds, const Gemm g, const Sched& S, const Epi& E, const int tid) {
;     ...
;     for (;;) {
;         const bool has_next = S.next(ui + 1, nxt);
;         const char* nA = has_next ? (const char*)g.A + (size_t)nxt.pm * tstep + (size_t)nxt.kb * g.sA : cA; const char* nB = has_next ? (const char*)g.Bt + (size_t)nxt.pn * tstep + (size_t)nxt.kb * g.sB : cB;
;     __device__ __forceinline__ void operator()(const f32x4 (&acc)[2][2][4][2], const Unit& un, int wr, int wc, int fr, int fq) const {
;     ...
;             const int row = rbase + ai * 128 + m * 16; const int ct = bj * 128 + cw;
;             const f32x4 v0 = acc[ai][bj][m][0] * rr[ai][m] + s0[bj], v1 = acc[ai][bj][m][1] * rr[ai][m] + s1[bj];
;             if (pn < 4) {
;                 u32x4 w; w.x = pk2(gelu_tanh(v0.x), gelu_tanh(v0.y)); w.y = pk2(gelu_tanh(v0.z), gelu_tanh(v0.w)); w.z = pk2(gelu_tanh(v1.x), gelu_tanh(v1.y)); w.w = pk2(gelu_tanh(v1.z), gelu_tanh(v1.w));
;                 *(u32x4*)(ga + (size_t)row * 1024 + pn * 256 + ct) = w;
.LBB0_695:
	v_mul_f32_e32 v10, 0x3d372713, v4
	v_mul_f32_e32 v11, 0x3d372713, v5
	v_mul_f32_e32 v10, v4, v10
	v_mul_f32_e32 v11, v5, v11
	v_mov_b32_e32 v12, v5
	v_fma_f32 v10, v4, v10, v4
	v_fmac_f32_e32 v12, v12, v11
	v_mul_f32_e32 v10, 0x3f4c422a, v10
	v_mul_f32_e32 v11, 0x3f4c422a, v12
	v_add_f32_e32 v10, v10, v10
	v_add_f32_e32 v11, v11, v11
	v_mul_f32_e32 v10, 0xbfb8aa3b, v10
	v_mul_f32_e32 v11, 0xbfb8aa3b, v11
	v_exp_f32_e32 v10, v10
	v_exp_f32_e32 v11, v11
	v_mov_b32_e32 v169, v209
	v_add_f32_e32 v10, 1.0, v10
	v_add_f32_e32 v11, 1.0, v11
	v_rcp_f32_e32 v10, v10
	v_rcp_f32_e32 v11, v11
	s_nop 0
	v_pk_mul_f32 v[4:5], v[4:5], v[10:11]
	s_nop 0
	v_cvt_pk_bf16_f32 v4, v4, v5
	v_mul_f32_e32 v5, 0x3d372713, v6
	v_mul_f32_e32 v5, v6, v5
	v_fma_f32 v5, v6, v5, v6
	v_mul_f32_e32 v5, 0x3f4c422a, v5
	v_add_f32_e32 v5, v5, v5
	v_mul_f32_e32 v5, 0xbfb8aa3b, v5
	v_exp_f32_e32 v5, v5
	s_nop 0
	v_add_f32_e32 v5, 1.0, v5
	v_rcp_f32_e32 v10, v5
	v_mul_f32_e32 v5, 0x3d372713, v7
	v_mul_f32_e32 v5, v7, v5
	v_fma_f32 v5, v7, v5, v7
	v_mul_f32_e32 v5, 0x3f4c422a, v5
	v_add_f32_e32 v5, v5, v5
	v_mul_f32_e32 v5, 0xbfb8aa3b, v5
	v_exp_f32_e32 v5, v5
	s_nop 0
	v_add_f32_e32 v5, 1.0, v5
	v_rcp_f32_e32 v11, v5
	s_nop 0
	v_pk_mul_f32 v[6:7], v[6:7], v[10:11]
	s_nop 0
	v_cvt_pk_bf16_f32 v5, v6, v7
	v_mul_f32_e32 v6, 0x3d372713, v0
	v_mul_f32_e32 v7, 0x3d372713, v1
	v_mul_f32_e32 v6, v0, v6
	v_mul_f32_e32 v7, v1, v7
	v_mov_b32_e32 v10, v1
	v_fma_f32 v6, v0, v6, v0
	v_fmac_f32_e32 v10, v10, v7
	v_mul_f32_e32 v6, 0x3f4c422a, v6
	v_mul_f32_e32 v7, 0x3f4c422a, v10
	v_add_f32_e32 v6, v6, v6
	v_add_f32_e32 v7, v7, v7
	v_mul_f32_e32 v6, 0xbfb8aa3b, v6
	v_mul_f32_e32 v7, 0xbfb8aa3b, v7
	v_exp_f32_e32 v6, v6
	v_exp_f32_e32 v7, v7
	v_add_f32_e32 v6, 1.0, v6
	v_add_f32_e32 v7, 1.0, v7
	v_rcp_f32_e32 v6, v6
	v_rcp_f32_e32 v7, v7
	s_nop 0
	v_pk_mul_f32 v[0:1], v[0:1], v[6:7]
	s_nop 0
	v_cvt_pk_bf16_f32 v6, v0, v1
	v_mul_f32_e32 v0, 0x3d372713, v2
	v_mul_f32_e32 v1, 0x3d372713, v3
	v_mul_f32_e32 v0, v2, v0
	v_mul_f32_e32 v1, v3, v1
	v_fma_f32 v0, v2, v0, v2
	v_fma_f32 v1, v3, v1, v3
	v_mul_f32_e32 v0, 0x3f4c422a, v0
	v_mul_f32_e32 v1, 0x3f4c422a, v1
	v_add_f32_e32 v0, v0, v0
	v_add_f32_e32 v1, v1, v1
	v_mul_f32_e32 v0, 0xbfb8aa3b, v0
	v_mul_f32_e32 v1, 0xbfb8aa3b, v1
	v_exp_f32_e32 v0, v0
	v_exp_f32_e32 v1, v1
	v_add_f32_e32 v0, 1.0, v0
	v_add_f32_e32 v1, 1.0, v1
	v_rcp_f32_e32 v0, v0
	v_rcp_f32_e32 v1, v1
	s_nop 0
	v_pk_mul_f32 v[0:1], v[2:3], v[0:1]
	s_nop 0
	v_cvt_pk_bf16_f32 v7, v0, v1
	v_lshl_add_u64 v[0:1], v[8:9], 0, v[168:169]
	global_store_dwordx4 v[0:1], v[4:7], off offset:256 nt
	s_andn2_b64 vcc, exec, s[6:7]
	s_mov_b64 s[0:1], -1
	s_mov_b64 s[42:43], 0x14a00400
	s_cbranch_vccnz .LBB0_333
	s_branch .LBB0_703

; __device__ __forceinline__ unsigned pk2(float lo, float hi) { const f32x2 v = {lo, hi}; return __builtin_bit_cast(unsigned, __builtin_convertvector(v, bf16x2_t)); }
;     __device__ __forceinline__ void operator()(const f32x4 (&acc)[2][2][4][2], const Unit& un, int wr, int wc, int fr, int fq) const {
;     ...
;                 const bool isq = pn < 10; const int cs = isq ? (pn - 8) * 256 + ct : ct;
;                 float x[8] = {v0.x, v0.y, v0.z, v0.w, v1.x, v1.y, v1.z, v1.w};
;                 if (lat) { const f32x4 ra = rp[m][0], rb = rp[m][1]; const float cc[4] = {ra.x, ra.z, rb.x, rb.z}, sn[4] = {ra.y, ra.w, rb.y, rb.w};
; #pragma unroll
;                     for (int jj = 0; jj < 4; ++jj) { const float x1 = x[2 * jj], x2 = x[2 * jj + 1]; x[2 * jj] = x1 * cc[jj] - x2 * sn[jj]; x[2 * jj + 1] = x1 * sn[jj] + x2 * cc[jj]; } }
;                 const float sc = isq ? QSCALE : 1.f;
;                 u32x4 w; w.x = pk2(x[0] * sc, x[1] * sc); w.y = pk2(x[2] * sc, x[3] * sc); w.z = pk2(x[4] * sc, x[5] * sc); w.w = pk2(x[6] * sc, x[7] * sc);
;                 if (isq) *(u32x4*)(q + (size_t)row * 512 + cs) = w; else *(u32x4*)(k + (size_t)row * 128 + cs) = w;
.LBB0_697:
	s_mov_b32 s0, 0x3e38aa3b
	v_pk_mul_f32 v[10:11], v[10:11], s[0:1] op_sel_hi:[1,0]
	v_pk_mul_f32 v[12:13], v[12:13], s[0:1] op_sel_hi:[1,0]
	v_cvt_pk_bf16_f32 v10, v10, v11
	v_cvt_pk_bf16_f32 v11, v12, v13
	v_pk_mul_f32 v[12:13], v[14:15], s[0:1] op_sel_hi:[1,0]
	v_pk_mul_f32 v[14:15], v[16:17], s[0:1] op_sel_hi:[1,0]
	v_cvt_pk_bf16_f32 v12, v12, v13
	v_cvt_pk_bf16_f32 v13, v14, v15
	v_lshl_add_u64 v[14:15], s[20:21], 0, v[32:33]
	v_add_u32_e32 v208, s37, v184
	v_lshl_add_u64 v[14:15], v[208:209], 1, v[14:15]
	global_store_dwordx4 v[14:15], v[10:13], off offset:256 nt

; __device__ __forceinline__ unsigned pk2(float lo, float hi) { const f32x2 v = {lo, hi}; return __builtin_bit_cast(unsigned, __builtin_convertvector(v, bf16x2_t)); }
; __device__ __forceinline__ float sigmoidf_(float x) { return __builtin_amdgcn_rcpf(1.f + __builtin_amdgcn_exp2f(-x * LOG2E)); }
; #define EPI_LOOP _Pragma("unroll") for (int ai = 0; ai < 2; ++ai) _Pragma("unroll") for (int m = 0; m < 4; ++m) _Pragma("unroll") for (int bj = 0; bj < 2; ++bj)
;     __device__ __forceinline__ void operator()(const f32x4 (&acc)[2][2][4][2], const Unit& un, int wr, int wc, int fr, int fq) const {
;     ...
;         EPI_LOOP { const int row = rbase + ai * 128 + m * 16, col = cw + bj * 128; const float r = rr[ai][m];
;             f32x4 v0 = acc[ai][bj][m][0] * r + s0[bj], v1 = acc[ai][bj][m][1] * r + s1[bj];
;             v0 = (f32x4){sigmoidf_(v0.x), sigmoidf_(v0.y), sigmoidf_(v0.z), sigmoidf_(v0.w)}; v1 = (f32x4){sigmoidf_(v1.x), sigmoidf_(v1.y), sigmoidf_(v1.z), sigmoidf_(v1.w)};
;             u32x4 w; w.x = pk2(v0.x, v0.y); w.y = pk2(v0.z, v0.w); w.z = pk2(v1.x, v1.y); w.w = pk2(v1.z, v1.w);
;             *(u32x4*)(o + (size_t)row * DFF + col) = w; }
.LBB0_771:
	s_mov_b64 s[20:21], 0x240000
	s_waitcnt vmcnt(0)
	v_pk_fma_f32 v[142:143], v[142:143], v[174:175], v[70:71] op_sel_hi:[1,0,1]
	v_pk_fma_f32 v[140:141], v[140:141], v[174:175], v[68:69] op_sel_hi:[1,0,1]
	v_pk_fma_f32 v[138:139], v[138:139], v[174:175], v[66:67] op_sel_hi:[1,0,1]
	v_pk_fma_f32 v[136:137], v[136:137], v[174:175], v[64:65] op_sel_hi:[1,0,1]
	v_mul_f32_e32 v140, 0xbfb8aa3b, v140
	v_mul_f32_e32 v141, 0xbfb8aa3b, v141
	v_mul_f32_e32 v142, 0xbfb8aa3b, v142
	v_mul_f32_e32 v143, 0xbfb8aa3b, v143
	v_mul_f32_e32 v136, 0xbfb8aa3b, v136
	v_mul_f32_e32 v137, 0xbfb8aa3b, v137
	v_mul_f32_e32 v138, 0xbfb8aa3b, v138
	v_mul_f32_e32 v139, 0xbfb8aa3b, v139
	v_exp_f32_e32 v140, v140
	v_exp_f32_e32 v141, v141
	v_exp_f32_e32 v142, v142
	v_exp_f32_e32 v143, v143
	v_exp_f32_e32 v136, v136
	v_exp_f32_e32 v137, v137
	v_exp_f32_e32 v138, v138
	v_exp_f32_e32 v139, v139
	v_add_f32_e32 v140, 1.0, v140
	v_add_f32_e32 v141, 1.0, v141
	v_add_f32_e32 v142, 1.0, v142
	v_add_f32_e32 v143, 1.0, v143
	v_add_f32_e32 v136, 1.0, v136
	v_add_f32_e32 v137, 1.0, v137
	v_add_f32_e32 v138, 1.0, v138
	v_add_f32_e32 v139, 1.0, v139
	v_pk_fma_f32 v[128:129], v[128:129], v[174:175], v[48:49] op_sel_hi:[1,0,1]
	v_rcp_f32_e32 v140, v140
	v_rcp_f32_e32 v141, v141
	v_rcp_f32_e32 v142, v142
	v_rcp_f32_e32 v143, v143
	v_rcp_f32_e32 v136, v136
	v_rcp_f32_e32 v137, v137
	v_rcp_f32_e32 v138, v138
	v_rcp_f32_e32 v139, v139
	v_mul_f32_e32 v128, 0xbfb8aa3b, v128
	v_exp_f32_e32 v128, v128
	v_cvt_pk_bf16_f32 v140, v140, v141
	v_cvt_pk_bf16_f32 v141, v142, v143
	v_cvt_pk_bf16_f32 v142, v136, v137
	v_cvt_pk_bf16_f32 v143, v138, v139
	v_lshl_add_u64 v[136:137], s[4:5], 0, v[178:179]
	v_lshlrev_b64 v[138:139], 1, v[176:177]
	v_lshl_add_u64 v[136:137], v[136:137], 0, v[138:139]
	v_add_f32_e32 v128, 1.0, v128
	global_store_dwordx4 v[136:137], v[140:143], off nt
	v_pk_fma_f32 v[130:131], v[130:131], v[174:175], v[50:51] op_sel_hi:[1,0,1]
	v_pk_fma_f32 v[134:135], v[134:135], v[174:175], v[54:55] op_sel_hi:[1,0,1]
	v_rcp_f32_e32 v140, v128
	v_mul_f32_e32 v128, 0xbfb8aa3b, v129
	v_exp_f32_e32 v128, v128
	v_pk_fma_f32 v[132:133], v[132:133], v[174:175], v[52:53] op_sel_hi:[1,0,1]
	v_mul_f32_e32 v134, 0xbfb8aa3b, v134
	v_mul_f32_e32 v132, 0xbfb8aa3b, v132
	v_add_f32_e32 v128, 1.0, v128
	v_rcp_f32_e32 v141, v128
	v_mul_f32_e32 v128, 0xbfb8aa3b, v130
	v_exp_f32_e32 v128, v128
	v_mul_f32_e32 v133, 0xbfb8aa3b, v133
	v_mul_f32_e32 v135, 0xbfb8aa3b, v135
	v_exp_f32_e32 v132, v132
	v_add_f32_e32 v128, 1.0, v128
	v_rcp_f32_e32 v142, v128
	v_mul_f32_e32 v128, 0xbfb8aa3b, v131
	v_exp_f32_e32 v133, v133
	v_exp_f32_e32 v134, v134
	v_exp_f32_e32 v135, v135
	v_exp_f32_e32 v128, v128
	v_pk_fma_f32 v[120:121], v[120:121], v[170:171], v[64:65] op_sel_hi:[1,0,1]
	v_add_f32_e32 v132, 1.0, v132
	v_add_f32_e32 v133, 1.0, v133
	v_add_f32_e32 v134, 1.0, v134
	v_add_f32_e32 v135, 1.0, v135
	v_add_f32_e32 v128, 1.0, v128
	v_mul_f32_e32 v120, 0xbfb8aa3b, v120
	v_rcp_f32_e32 v132, v132
	v_rcp_f32_e32 v133, v133
	v_rcp_f32_e32 v134, v134
	v_rcp_f32_e32 v135, v135
	v_rcp_f32_e32 v131, v128
	v_exp_f32_e32 v120, v120
	v_cvt_pk_bf16_f32 v128, v132, v133
	v_cvt_pk_bf16_f32 v129, v134, v135
	v_cvt_pk_bf16_f32 v130, v140, v141
	v_cvt_pk_bf16_f32 v131, v142, v131
	v_add_f32_e32 v120, 1.0, v120
	global_store_dwordx4 v[136:137], v[128:131], off offset:256 nt
	v_pk_fma_f32 v[122:123], v[122:123], v[170:171], v[66:67] op_sel_hi:[1,0,1]
	v_pk_fma_f32 v[124:125], v[124:125], v[170:171], v[68:69] op_sel_hi:[1,0,1]
	v_rcp_f32_e32 v130, v120
	v_mul_f32_e32 v120, 0xbfb8aa3b, v121
	v_exp_f32_e32 v120, v120
	v_pk_fma_f32 v[126:127], v[126:127], v[170:171], v[70:71] op_sel_hi:[1,0,1]
	v_mul_f32_e32 v124, 0xbfb8aa3b, v124
	v_mul_f32_e32 v125, 0xbfb8aa3b, v125
	v_add_f32_e32 v120, 1.0, v120
	v_rcp_f32_e32 v131, v120
	v_mul_f32_e32 v120, 0xbfb8aa3b, v122
	v_exp_f32_e32 v120, v120
	v_exp_f32_e32 v124, v124
	v_exp_f32_e32 v125, v125
	v_mul_f32_e32 v126, 0xbfb8aa3b, v126
	v_add_f32_e32 v120, 1.0, v120
	v_mul_f32_e32 v127, 0xbfb8aa3b, v127
	v_rcp_f32_e32 v132, v120
	v_mul_f32_e32 v120, 0xbfb8aa3b, v123
	v_exp_f32_e32 v126, v126
	v_exp_f32_e32 v127, v127
	v_exp_f32_e32 v120, v120
	v_add_f32_e32 v124, 1.0, v124
	v_add_f32_e32 v125, 1.0, v125
	v_pk_fma_f32 v[112:113], v[112:113], v[170:171], v[48:49] op_sel_hi:[1,0,1]
	v_rcp_f32_e32 v124, v124
	v_rcp_f32_e32 v125, v125
	v_add_f32_e32 v126, 1.0, v126
	v_add_f32_e32 v127, 1.0, v127
	v_add_f32_e32 v120, 1.0, v120
	v_mul_f32_e32 v112, 0xbfb8aa3b, v112
	v_rcp_f32_e32 v126, v126
	v_rcp_f32_e32 v127, v127
	v_rcp_f32_e32 v123, v120
	v_exp_f32_e32 v112, v112
	v_lshlrev_b64 v[128:129], 14, v[172:173]
	v_cvt_pk_bf16_f32 v120, v124, v125
	v_lshl_add_u64 v[124:125], s[4:5], 0, v[128:129]
	v_cvt_pk_bf16_f32 v121, v126, v127
	v_cvt_pk_bf16_f32 v122, v130, v131
	v_cvt_pk_bf16_f32 v123, v132, v123
	v_lshl_add_u64 v[124:125], v[124:125], 0, v[138:139]
	v_add_f32_e32 v112, 1.0, v112
	global_store_dwordx4 v[124:125], v[120:123], off nt
	v_pk_fma_f32 v[114:115], v[114:115], v[170:171], v[50:51] op_sel_hi:[1,0,1]
	v_pk_fma_f32 v[118:119], v[118:119], v[170:171], v[54:55] op_sel_hi:[1,0,1]
	v_rcp_f32_e32 v120, v112
	v_mul_f32_e32 v112, 0xbfb8aa3b, v113
	v_exp_f32_e32 v112, v112
	v_pk_fma_f32 v[116:117], v[116:117], v[170:171], v[52:53] op_sel_hi:[1,0,1]
	v_mul_f32_e32 v118, 0xbfb8aa3b, v118
	v_mul_f32_e32 v116, 0xbfb8aa3b, v116
	v_add_f32_e32 v112, 1.0, v112
	v_rcp_f32_e32 v121, v112
	v_mul_f32_e32 v112, 0xbfb8aa3b, v114
	v_exp_f32_e32 v112, v112
	v_mul_f32_e32 v117, 0xbfb8aa3b, v117
	v_mul_f32_e32 v119, 0xbfb8aa3b, v119
	v_exp_f32_e32 v116, v116
	v_add_f32_e32 v112, 1.0, v112
	v_rcp_f32_e32 v122, v112
; __device__ __forceinline__ unsigned pk2(float lo, float hi) { const f32x2 v = {lo, hi}; return __builtin_bit_cast(unsigned, __builtin_convertvector(v, bf16x2_t)); }
; __device__ __forceinline__ float sigmoidf_(float x) { return __builtin_amdgcn_rcpf(1.f + __builtin_amdgcn_exp2f(-x * LOG2E)); }
; #define EPI_LOOP _Pragma("unroll") for (int ai = 0; ai < 2; ++ai) _Pragma("unroll") for (int m = 0; m < 4; ++m) _Pragma("unroll") for (int bj = 0; bj < 2; ++bj)
;     __device__ __forceinline__ void operator()(const f32x4 (&acc)[2][2][4][2], const Unit& un, int wr, int wc, int fr, int fq) const {
;     ...
;         EPI_LOOP { const int row = rbase + ai * 128 + m * 16, col = cw + bj * 128; const float r = rr[ai][m];
;             f32x4 v0 = acc[ai][bj][m][0] * r + s0[bj], v1 = acc[ai][bj][m][1] * r + s1[bj];
;             v0 = (f32x4){sigmoidf_(v0.x), sigmoidf_(v0.y), sigmoidf_(v0.z), sigmoidf_(v0.w)}; v1 = (f32x4){sigmoidf_(v1.x), sigmoidf_(v1.y), sigmoidf_(v1.z), sigmoidf_(v1.w)};
;             u32x4 w; w.x = pk2(v0.x, v0.y); w.y = pk2(v0.z, v0.w); w.z = pk2(v1.x, v1.y); w.w = pk2(v1.z, v1.w);
;             *(u32x4*)(o + (size_t)row * DFF + col) = w; }
	v_mul_f32_e32 v112, 0xbfb8aa3b, v115
	v_exp_f32_e32 v117, v117
	v_exp_f32_e32 v118, v118
	v_exp_f32_e32 v119, v119
	v_exp_f32_e32 v112, v112
	v_pk_fma_f32 v[104:105], v[104:105], v[166:167], v[64:65] op_sel_hi:[1,0,1]
	v_add_f32_e32 v116, 1.0, v116
	v_add_f32_e32 v117, 1.0, v117
	v_add_f32_e32 v118, 1.0, v118
	v_add_f32_e32 v119, 1.0, v119
	v_add_f32_e32 v112, 1.0, v112
	v_mul_f32_e32 v104, 0xbfb8aa3b, v104
	v_rcp_f32_e32 v116, v116
	v_rcp_f32_e32 v117, v117
	v_rcp_f32_e32 v118, v118
	v_rcp_f32_e32 v119, v119
	v_rcp_f32_e32 v115, v112
	v_exp_f32_e32 v104, v104
	v_cvt_pk_bf16_f32 v112, v116, v117
	v_cvt_pk_bf16_f32 v113, v118, v119
	v_cvt_pk_bf16_f32 v114, v120, v121
	v_cvt_pk_bf16_f32 v115, v122, v115
	v_add_f32_e32 v104, 1.0, v104
	global_store_dwordx4 v[124:125], v[112:115], off offset:256 nt
	v_pk_fma_f32 v[106:107], v[106:107], v[166:167], v[66:67] op_sel_hi:[1,0,1]
	v_pk_fma_f32 v[108:109], v[108:109], v[166:167], v[68:69] op_sel_hi:[1,0,1]
	v_rcp_f32_e32 v114, v104
	v_mul_f32_e32 v104, 0xbfb8aa3b, v105
	v_exp_f32_e32 v104, v104
	v_pk_fma_f32 v[110:111], v[110:111], v[166:167], v[70:71] op_sel_hi:[1,0,1]
	v_mul_f32_e32 v108, 0xbfb8aa3b, v108
	v_mul_f32_e32 v109, 0xbfb8aa3b, v109
	v_add_f32_e32 v104, 1.0, v104
	v_rcp_f32_e32 v115, v104
	v_mul_f32_e32 v104, 0xbfb8aa3b, v106
	v_exp_f32_e32 v104, v104
	v_exp_f32_e32 v108, v108
	v_exp_f32_e32 v109, v109
	v_mul_f32_e32 v110, 0xbfb8aa3b, v110
	v_add_f32_e32 v104, 1.0, v104
	v_mul_f32_e32 v111, 0xbfb8aa3b, v111
	v_rcp_f32_e32 v116, v104
	v_mul_f32_e32 v104, 0xbfb8aa3b, v107
	v_exp_f32_e32 v110, v110
	v_exp_f32_e32 v111, v111
	v_exp_f32_e32 v104, v104
	v_add_f32_e32 v108, 1.0, v108
	v_add_f32_e32 v109, 1.0, v109
	v_pk_fma_f32 v[96:97], v[96:97], v[166:167], v[48:49] op_sel_hi:[1,0,1]
	v_rcp_f32_e32 v108, v108
	v_rcp_f32_e32 v109, v109
	v_add_f32_e32 v110, 1.0, v110
	v_add_f32_e32 v111, 1.0, v111
	v_add_f32_e32 v104, 1.0, v104
	v_mul_f32_e32 v96, 0xbfb8aa3b, v96
	v_rcp_f32_e32 v110, v110
	v_rcp_f32_e32 v111, v111
	v_rcp_f32_e32 v107, v104
	v_exp_f32_e32 v96, v96
	v_lshlrev_b64 v[112:113], 14, v[168:169]
	v_cvt_pk_bf16_f32 v104, v108, v109
	v_lshl_add_u64 v[108:109], s[4:5], 0, v[112:113]
	v_cvt_pk_bf16_f32 v105, v110, v111
	v_cvt_pk_bf16_f32 v106, v114, v115
	v_cvt_pk_bf16_f32 v107, v116, v107
	v_lshl_add_u64 v[108:109], v[108:109], 0, v[138:139]
	v_add_f32_e32 v96, 1.0, v96
	global_store_dwordx4 v[108:109], v[104:107], off nt
	v_pk_fma_f32 v[98:99], v[98:99], v[166:167], v[50:51] op_sel_hi:[1,0,1]
	v_pk_fma_f32 v[102:103], v[102:103], v[166:167], v[54:55] op_sel_hi:[1,0,1]
	v_rcp_f32_e32 v104, v96
	v_mul_f32_e32 v96, 0xbfb8aa3b, v97
	v_exp_f32_e32 v96, v96
	v_pk_fma_f32 v[100:101], v[100:101], v[166:167], v[52:53] op_sel_hi:[1,0,1]
	v_mul_f32_e32 v102, 0xbfb8aa3b, v102
	v_mul_f32_e32 v100, 0xbfb8aa3b, v100
	v_add_f32_e32 v96, 1.0, v96
	v_rcp_f32_e32 v105, v96
	v_mul_f32_e32 v96, 0xbfb8aa3b, v98
	v_exp_f32_e32 v96, v96
	v_mul_f32_e32 v101, 0xbfb8aa3b, v101
	v_mul_f32_e32 v103, 0xbfb8aa3b, v103
	v_exp_f32_e32 v100, v100
	v_add_f32_e32 v96, 1.0, v96
	v_rcp_f32_e32 v106, v96
	v_mul_f32_e32 v96, 0xbfb8aa3b, v99
	v_exp_f32_e32 v101, v101
	v_exp_f32_e32 v102, v102
	v_exp_f32_e32 v103, v103
	v_exp_f32_e32 v96, v96
	v_pk_fma_f32 v[88:89], v[88:89], v[162:163], v[64:65] op_sel_hi:[1,0,1]
	v_add_f32_e32 v100, 1.0, v100
	v_add_f32_e32 v101, 1.0, v101
	v_add_f32_e32 v102, 1.0, v102
	v_add_f32_e32 v103, 1.0, v103
	v_add_f32_e32 v96, 1.0, v96
	v_mul_f32_e32 v88, 0xbfb8aa3b, v88
	v_rcp_f32_e32 v100, v100
	v_rcp_f32_e32 v101, v101
	v_rcp_f32_e32 v102, v102
	v_rcp_f32_e32 v103, v103
	v_rcp_f32_e32 v99, v96
	v_exp_f32_e32 v88, v88
	v_cvt_pk_bf16_f32 v96, v100, v101
	v_cvt_pk_bf16_f32 v97, v102, v103
	v_cvt_pk_bf16_f32 v98, v104, v105
	v_cvt_pk_bf16_f32 v99, v106, v99
	v_add_f32_e32 v88, 1.0, v88
	global_store_dwordx4 v[108:109], v[96:99], off offset:256 nt
	v_pk_fma_f32 v[90:91], v[90:91], v[162:163], v[66:67] op_sel_hi:[1,0,1]
	v_pk_fma_f32 v[92:93], v[92:93], v[162:163], v[68:69] op_sel_hi:[1,0,1]
	v_rcp_f32_e32 v98, v88
	v_mul_f32_e32 v88, 0xbfb8aa3b, v89
	v_exp_f32_e32 v88, v88
	v_pk_fma_f32 v[94:95], v[94:95], v[162:163], v[70:71] op_sel_hi:[1,0,1]
	v_mul_f32_e32 v92, 0xbfb8aa3b, v92
	v_mul_f32_e32 v93, 0xbfb8aa3b, v93
	v_add_f32_e32 v88, 1.0, v88
	v_rcp_f32_e32 v99, v88
	v_mul_f32_e32 v88, 0xbfb8aa3b, v90
	v_exp_f32_e32 v88, v88
	v_exp_f32_e32 v92, v92
	v_exp_f32_e32 v93, v93
	v_mul_f32_e32 v94, 0xbfb8aa3b, v94
	v_add_f32_e32 v88, 1.0, v88
	v_mul_f32_e32 v95, 0xbfb8aa3b, v95
	v_rcp_f32_e32 v100, v88
	v_mul_f32_e32 v88, 0xbfb8aa3b, v91
	v_exp_f32_e32 v94, v94
	v_exp_f32_e32 v95, v95
	v_exp_f32_e32 v88, v88
	v_add_f32_e32 v92, 1.0, v92
	v_add_f32_e32 v93, 1.0, v93
	v_pk_fma_f32 v[80:81], v[80:81], v[162:163], v[48:49] op_sel_hi:[1,0,1]
	v_rcp_f32_e32 v92, v92
	v_rcp_f32_e32 v93, v93
	v_add_f32_e32 v94, 1.0, v94
	v_add_f32_e32 v95, 1.0, v95
	v_add_f32_e32 v88, 1.0, v88
	v_mul_f32_e32 v80, 0xbfb8aa3b, v80
	v_rcp_f32_e32 v94, v94
	v_rcp_f32_e32 v95, v95
	v_rcp_f32_e32 v91, v88
	v_exp_f32_e32 v80, v80
	v_lshlrev_b64 v[96:97], 14, v[164:165]
	v_cvt_pk_bf16_f32 v88, v92, v93
	v_lshl_add_u64 v[92:93], s[4:5], 0, v[96:97]
	v_cvt_pk_bf16_f32 v89, v94, v95
	v_cvt_pk_bf16_f32 v90, v98, v99
	v_cvt_pk_bf16_f32 v91, v100, v91
	v_lshl_add_u64 v[92:93], v[92:93], 0, v[138:139]
	v_add_f32_e32 v80, 1.0, v80
	global_store_dwordx4 v[92:93], v[88:91], off nt
	v_pk_fma_f32 v[82:83], v[82:83], v[162:163], v[50:51] op_sel_hi:[1,0,1]
	v_pk_fma_f32 v[86:87], v[86:87], v[162:163], v[54:55] op_sel_hi:[1,0,1]
	v_rcp_f32_e32 v88, v80
	v_mul_f32_e32 v80, 0xbfb8aa3b, v81
	v_exp_f32_e32 v80, v80
	v_pk_fma_f32 v[84:85], v[84:85], v[162:163], v[52:53] op_sel_hi:[1,0,1]
; __device__ __forceinline__ unsigned pk2(float lo, float hi) { const f32x2 v = {lo, hi}; return __builtin_bit_cast(unsigned, __builtin_convertvector(v, bf16x2_t)); }
; __device__ __forceinline__ float sigmoidf_(float x) { return __builtin_amdgcn_rcpf(1.f + __builtin_amdgcn_exp2f(-x * LOG2E)); }
; #define EPI_LOOP _Pragma("unroll") for (int ai = 0; ai < 2; ++ai) _Pragma("unroll") for (int m = 0; m < 4; ++m) _Pragma("unroll") for (int bj = 0; bj < 2; ++bj)
;     __device__ __forceinline__ void operator()(const f32x4 (&acc)[2][2][4][2], const Unit& un, int wr, int wc, int fr, int fq) const {
;     ...
;         EPI_LOOP { const int row = rbase + ai * 128 + m * 16, col = cw + bj * 128; const float r = rr[ai][m];
;             f32x4 v0 = acc[ai][bj][m][0] * r + s0[bj], v1 = acc[ai][bj][m][1] * r + s1[bj];
;             v0 = (f32x4){sigmoidf_(v0.x), sigmoidf_(v0.y), sigmoidf_(v0.z), sigmoidf_(v0.w)}; v1 = (f32x4){sigmoidf_(v1.x), sigmoidf_(v1.y), sigmoidf_(v1.z), sigmoidf_(v1.w)};
;             u32x4 w; w.x = pk2(v0.x, v0.y); w.y = pk2(v0.z, v0.w); w.z = pk2(v1.x, v1.y); w.w = pk2(v1.z, v1.w);
;             *(u32x4*)(o + (size_t)row * DFF + col) = w; }
	v_mul_f32_e32 v86, 0xbfb8aa3b, v86
	v_mul_f32_e32 v84, 0xbfb8aa3b, v84
	v_add_f32_e32 v80, 1.0, v80
	v_rcp_f32_e32 v89, v80
	v_mul_f32_e32 v80, 0xbfb8aa3b, v82
	v_exp_f32_e32 v80, v80
	v_mul_f32_e32 v85, 0xbfb8aa3b, v85
	v_mul_f32_e32 v87, 0xbfb8aa3b, v87
	v_exp_f32_e32 v84, v84
	v_add_f32_e32 v80, 1.0, v80
	v_rcp_f32_e32 v90, v80
	v_mul_f32_e32 v80, 0xbfb8aa3b, v83
	v_exp_f32_e32 v85, v85
	v_exp_f32_e32 v86, v86
	v_exp_f32_e32 v87, v87
	v_exp_f32_e32 v80, v80
	v_pk_fma_f32 v[72:73], v[72:73], v[160:161], v[64:65] op_sel_hi:[1,0,1]
	v_add_f32_e32 v84, 1.0, v84
	v_add_f32_e32 v85, 1.0, v85
	v_add_f32_e32 v86, 1.0, v86
	v_add_f32_e32 v87, 1.0, v87
	v_add_f32_e32 v80, 1.0, v80
	v_mul_f32_e32 v72, 0xbfb8aa3b, v72
	v_rcp_f32_e32 v84, v84
	v_rcp_f32_e32 v85, v85
	v_rcp_f32_e32 v86, v86
	v_rcp_f32_e32 v87, v87
	v_rcp_f32_e32 v83, v80
	v_exp_f32_e32 v72, v72
	v_cvt_pk_bf16_f32 v80, v84, v85
	v_cvt_pk_bf16_f32 v81, v86, v87
	v_cvt_pk_bf16_f32 v82, v88, v89
	v_cvt_pk_bf16_f32 v83, v90, v83
	v_add_f32_e32 v72, 1.0, v72
	global_store_dwordx4 v[92:93], v[80:83], off offset:256 nt
	v_pk_fma_f32 v[74:75], v[74:75], v[160:161], v[66:67] op_sel_hi:[1,0,1]
	v_pk_fma_f32 v[78:79], v[78:79], v[160:161], v[70:71] op_sel_hi:[1,0,1]
	v_rcp_f32_e32 v80, v72
	v_mul_f32_e32 v72, 0xbfb8aa3b, v73
	v_exp_f32_e32 v72, v72
	v_pk_fma_f32 v[76:77], v[76:77], v[160:161], v[68:69] op_sel_hi:[1,0,1]
	v_mul_f32_e32 v78, 0xbfb8aa3b, v78
	v_mul_f32_e32 v79, 0xbfb8aa3b, v79
	v_add_f32_e32 v72, 1.0, v72
	v_rcp_f32_e32 v81, v72
	v_mul_f32_e32 v72, 0xbfb8aa3b, v74
	v_exp_f32_e32 v72, v72
	v_mul_f32_e32 v76, 0xbfb8aa3b, v76
	v_mul_f32_e32 v77, 0xbfb8aa3b, v77
	v_exp_f32_e32 v78, v78
	v_add_f32_e32 v72, 1.0, v72
	v_exp_f32_e32 v79, v79
	v_rcp_f32_e32 v82, v72
	v_mul_f32_e32 v72, 0xbfb8aa3b, v75
	v_exp_f32_e32 v76, v76
	v_exp_f32_e32 v77, v77
	v_exp_f32_e32 v72, v72
	v_add_f32_e32 v78, 1.0, v78
	v_add_f32_e32 v79, 1.0, v79
	v_pk_fma_f32 v[56:57], v[56:57], v[160:161], v[48:49] op_sel_hi:[1,0,1]
	v_add_f32_e32 v76, 1.0, v76
	v_add_f32_e32 v77, 1.0, v77
	v_rcp_f32_e32 v78, v78
	v_rcp_f32_e32 v79, v79
	v_add_f32_e32 v72, 1.0, v72
	v_mul_f32_e32 v56, 0xbfb8aa3b, v56
	v_rcp_f32_e32 v76, v76
	v_rcp_f32_e32 v77, v77
	v_rcp_f32_e32 v75, v72
	v_exp_f32_e32 v56, v56
	v_cvt_pk_bf16_f32 v73, v78, v79
	v_add_co_u32_e32 v78, vcc, s78, v136
	v_cvt_pk_bf16_f32 v72, v76, v77
	v_cvt_pk_bf16_f32 v74, v80, v81
	v_cvt_pk_bf16_f32 v75, v82, v75
	v_addc_co_u32_e32 v79, vcc, 0, v137, vcc
	v_add_f32_e32 v56, 1.0, v56
	global_store_dwordx4 v[78:79], v[72:75], off nt
	v_pk_fma_f32 v[58:59], v[58:59], v[160:161], v[50:51] op_sel_hi:[1,0,1]
	v_pk_fma_f32 v[62:63], v[62:63], v[160:161], v[54:55] op_sel_hi:[1,0,1]
	v_rcp_f32_e32 v72, v56
	v_mul_f32_e32 v56, 0xbfb8aa3b, v57
	v_exp_f32_e32 v56, v56
	v_pk_fma_f32 v[60:61], v[60:61], v[160:161], v[52:53] op_sel_hi:[1,0,1]
	v_mul_f32_e32 v62, 0xbfb8aa3b, v62
	v_mul_f32_e32 v60, 0xbfb8aa3b, v60
	v_add_f32_e32 v56, 1.0, v56
	v_rcp_f32_e32 v73, v56
	v_mul_f32_e32 v56, 0xbfb8aa3b, v58
	v_exp_f32_e32 v56, v56
	v_mul_f32_e32 v61, 0xbfb8aa3b, v61
	v_mul_f32_e32 v63, 0xbfb8aa3b, v63
	v_exp_f32_e32 v60, v60
	v_add_f32_e32 v56, 1.0, v56
	v_rcp_f32_e32 v74, v56
	v_mul_f32_e32 v56, 0xbfb8aa3b, v59
	v_exp_f32_e32 v61, v61
	v_exp_f32_e32 v62, v62
	v_exp_f32_e32 v63, v63
	v_exp_f32_e32 v56, v56
	v_pk_fma_f32 v[40:41], v[40:41], v[158:159], v[64:65] op_sel_hi:[1,0,1]
	v_add_f32_e32 v60, 1.0, v60
	v_add_f32_e32 v61, 1.0, v61
	v_add_f32_e32 v62, 1.0, v62
	v_add_f32_e32 v63, 1.0, v63
	v_add_f32_e32 v56, 1.0, v56
	v_mul_f32_e32 v40, 0xbfb8aa3b, v40
	v_rcp_f32_e32 v60, v60
	v_rcp_f32_e32 v61, v61
	v_rcp_f32_e32 v62, v62
	v_rcp_f32_e32 v63, v63
	v_rcp_f32_e32 v59, v56
	v_exp_f32_e32 v40, v40
	v_lshl_add_u64 v[76:77], v[136:137], 0, s[56:57]
	v_cvt_pk_bf16_f32 v56, v60, v61
	v_cvt_pk_bf16_f32 v57, v62, v63
	v_cvt_pk_bf16_f32 v58, v72, v73
	v_cvt_pk_bf16_f32 v59, v74, v59
	v_add_f32_e32 v40, 1.0, v40
	global_store_dwordx4 v[76:77], v[56:59], off offset:256 nt
	v_pk_fma_f32 v[42:43], v[42:43], v[158:159], v[66:67] op_sel_hi:[1,0,1]
	v_pk_fma_f32 v[46:47], v[46:47], v[158:159], v[70:71] op_sel_hi:[1,0,1]
	v_rcp_f32_e32 v56, v40
	v_mul_f32_e32 v40, 0xbfb8aa3b, v41
	v_exp_f32_e32 v40, v40
	v_pk_fma_f32 v[44:45], v[44:45], v[158:159], v[68:69] op_sel_hi:[1,0,1]
	v_mul_f32_e32 v46, 0xbfb8aa3b, v46
	v_mul_f32_e32 v47, 0xbfb8aa3b, v47
	v_add_f32_e32 v40, 1.0, v40
	v_rcp_f32_e32 v57, v40
	v_mul_f32_e32 v40, 0xbfb8aa3b, v42
	v_exp_f32_e32 v40, v40
	v_mul_f32_e32 v44, 0xbfb8aa3b, v44
	v_mul_f32_e32 v45, 0xbfb8aa3b, v45
	v_exp_f32_e32 v46, v46
	v_add_f32_e32 v40, 1.0, v40
	v_exp_f32_e32 v47, v47
	v_rcp_f32_e32 v58, v40
	v_mul_f32_e32 v40, 0xbfb8aa3b, v43
	v_exp_f32_e32 v44, v44
	v_exp_f32_e32 v45, v45
	v_exp_f32_e32 v40, v40
	v_add_f32_e32 v46, 1.0, v46
	v_add_f32_e32 v47, 1.0, v47
	v_pk_fma_f32 v[32:33], v[32:33], v[158:159], v[48:49] op_sel_hi:[1,0,1]
	v_add_f32_e32 v44, 1.0, v44
	v_add_f32_e32 v45, 1.0, v45
	v_rcp_f32_e32 v46, v46
	v_rcp_f32_e32 v47, v47
	v_add_f32_e32 v40, 1.0, v40
	v_mul_f32_e32 v32, 0xbfb8aa3b, v32
	v_rcp_f32_e32 v44, v44
	v_rcp_f32_e32 v45, v45
	v_rcp_f32_e32 v43, v40
	v_exp_f32_e32 v32, v32
	v_cvt_pk_bf16_f32 v41, v46, v47
	v_add_co_u32_e32 v46, vcc, s74, v136
	v_cvt_pk_bf16_f32 v40, v44, v45
	v_cvt_pk_bf16_f32 v42, v56, v57
	v_cvt_pk_bf16_f32 v43, v58, v43
	v_addc_co_u32_e32 v47, vcc, 0, v137, vcc
	v_add_f32_e32 v32, 1.0, v32
	global_store_dwordx4 v[46:47], v[40:43], off nt
	v_pk_fma_f32 v[34:35], v[34:35], v[158:159], v[50:51] op_sel_hi:[1,0,1]
	v_pk_fma_f32 v[38:39], v[38:39], v[158:159], v[54:55] op_sel_hi:[1,0,1]
	v_rcp_f32_e32 v40, v32
	v_mul_f32_e32 v32, 0xbfb8aa3b, v33
;     __host__ __device__ bool next(int i, Unit& u) const { const int L = base + i * Gp + cp; if (L >= end) return false; return T.next(L, u); }
;     __host__ __device__ bool next(int i, Unit& u) const { const int L = i * Gp + cp; if (cp < 0 || L >= n) return false; u.kb = L & 3; u.pn = (L >> 2) % nN; u.pm = pm0 + (L >> 2) / nN; return true; }
;     __host__ __device__ bool next(int i, Unit& u) const { const bool ok = T.next(i >> 2, u); u.kb = i & 3; return ok; }
; __device__ __forceinline__ unsigned pk2(float lo, float hi) { const f32x2 v = {lo, hi}; return __builtin_bit_cast(unsigned, __builtin_convertvector(v, bf16x2_t)); }
; __device__ __forceinline__ float sigmoidf_(float x) { return __builtin_amdgcn_rcpf(1.f + __builtin_amdgcn_exp2f(-x * LOG2E)); }
; #define EPI_LOOP _Pragma("unroll") for (int ai = 0; ai < 2; ++ai) _Pragma("unroll") for (int m = 0; m < 4; ++m) _Pragma("unroll") for (int bj = 0; bj < 2; ++bj)
; template <class Epi, class Sched, bool ALIGN_EPI = false, bool SP2 = false>
; __device__ __forceinline__ void gemm_phase(PG8_LAS unsigned char* lds, const Gemm g, const Sched& S, const Epi& E, const int tid) {
;     ...
;     for (;;) {
;         const bool has_next = S.next(ui + 1, nxt);
;         const char* nA = has_next ? (const char*)g.A + (size_t)nxt.pm * tstep + (size_t)nxt.kb * g.sA : cA; const char* nB = has_next ? (const char*)g.Bt + (size_t)nxt.pn * tstep + (size_t)nxt.kb * g.sB : cB;
;         for (int t = 0; t < nt; t += 2) {
;     __device__ __forceinline__ void operator()(const f32x4 (&acc)[2][2][4][2], const Unit& un, int wr, int wc, int fr, int fq) const {
;     ...
;         EPI_LOOP { const int row = rbase + ai * 128 + m * 16, col = cw + bj * 128; const float r = rr[ai][m];
;             f32x4 v0 = acc[ai][bj][m][0] * r + s0[bj], v1 = acc[ai][bj][m][1] * r + s1[bj];
;             v0 = (f32x4){sigmoidf_(v0.x), sigmoidf_(v0.y), sigmoidf_(v0.z), sigmoidf_(v0.w)}; v1 = (f32x4){sigmoidf_(v1.x), sigmoidf_(v1.y), sigmoidf_(v1.z), sigmoidf_(v1.w)};
;             u32x4 w; w.x = pk2(v0.x, v0.y); w.y = pk2(v0.z, v0.w); w.z = pk2(v1.x, v1.y); w.w = pk2(v1.z, v1.w);
;             *(u32x4*)(o + (size_t)row * DFF + col) = w; }
	v_exp_f32_e32 v32, v32
	v_pk_fma_f32 v[36:37], v[36:37], v[158:159], v[52:53] op_sel_hi:[1,0,1]
	v_mul_f32_e32 v38, 0xbfb8aa3b, v38
	v_mul_f32_e32 v36, 0xbfb8aa3b, v36
	v_add_f32_e32 v32, 1.0, v32
	v_rcp_f32_e32 v41, v32
	v_mul_f32_e32 v32, 0xbfb8aa3b, v34
	v_exp_f32_e32 v32, v32
	v_mul_f32_e32 v37, 0xbfb8aa3b, v37
	v_mul_f32_e32 v39, 0xbfb8aa3b, v39
	v_exp_f32_e32 v36, v36
	v_add_f32_e32 v32, 1.0, v32
	v_rcp_f32_e32 v42, v32
	v_mul_f32_e32 v32, 0xbfb8aa3b, v35
	v_exp_f32_e32 v37, v37
	v_exp_f32_e32 v38, v38
	v_exp_f32_e32 v39, v39
	v_exp_f32_e32 v32, v32
	v_pk_fma_f32 v[24:25], v[24:25], v[156:157], v[64:65] op_sel_hi:[1,0,1]
	v_add_f32_e32 v36, 1.0, v36
	v_add_f32_e32 v37, 1.0, v37
	v_add_f32_e32 v38, 1.0, v38
	v_add_f32_e32 v39, 1.0, v39
	v_add_f32_e32 v32, 1.0, v32
	v_mul_f32_e32 v24, 0xbfb8aa3b, v24
	v_rcp_f32_e32 v36, v36
	v_rcp_f32_e32 v37, v37
	v_rcp_f32_e32 v38, v38
	v_rcp_f32_e32 v39, v39
	v_rcp_f32_e32 v35, v32
	v_exp_f32_e32 v24, v24
	v_lshl_add_u64 v[44:45], v[136:137], 0, s[20:21]
	v_cvt_pk_bf16_f32 v32, v36, v37
	v_cvt_pk_bf16_f32 v33, v38, v39
	v_cvt_pk_bf16_f32 v34, v40, v41
	v_cvt_pk_bf16_f32 v35, v42, v35
	v_add_f32_e32 v24, 1.0, v24
	global_store_dwordx4 v[44:45], v[32:35], off offset:256 nt
	v_pk_fma_f32 v[26:27], v[26:27], v[156:157], v[66:67] op_sel_hi:[1,0,1]
	v_pk_fma_f32 v[30:31], v[30:31], v[156:157], v[70:71] op_sel_hi:[1,0,1]
	v_rcp_f32_e32 v32, v24
	v_mul_f32_e32 v24, 0xbfb8aa3b, v25
	v_exp_f32_e32 v24, v24
	v_pk_fma_f32 v[28:29], v[28:29], v[156:157], v[68:69] op_sel_hi:[1,0,1]
	v_mul_f32_e32 v30, 0xbfb8aa3b, v30
	v_mul_f32_e32 v31, 0xbfb8aa3b, v31
	v_add_f32_e32 v24, 1.0, v24
	v_rcp_f32_e32 v33, v24
	v_mul_f32_e32 v24, 0xbfb8aa3b, v26
	v_exp_f32_e32 v24, v24
	v_mul_f32_e32 v28, 0xbfb8aa3b, v28
	v_mul_f32_e32 v29, 0xbfb8aa3b, v29
	v_exp_f32_e32 v30, v30
	v_add_f32_e32 v24, 1.0, v24
	v_exp_f32_e32 v31, v31
	v_rcp_f32_e32 v34, v24
	v_mul_f32_e32 v24, 0xbfb8aa3b, v27
	v_exp_f32_e32 v28, v28
	v_exp_f32_e32 v29, v29
	v_exp_f32_e32 v24, v24
	v_add_f32_e32 v30, 1.0, v30
	v_add_f32_e32 v31, 1.0, v31
	v_pk_fma_f32 v[16:17], v[16:17], v[156:157], v[48:49] op_sel_hi:[1,0,1]
	v_add_f32_e32 v28, 1.0, v28
	v_add_f32_e32 v29, 1.0, v29
	v_rcp_f32_e32 v30, v30
	v_rcp_f32_e32 v31, v31
	v_add_f32_e32 v24, 1.0, v24
	v_mul_f32_e32 v16, 0xbfb8aa3b, v16
	v_rcp_f32_e32 v28, v28
	v_rcp_f32_e32 v29, v29
	v_rcp_f32_e32 v27, v24
	v_exp_f32_e32 v16, v16
	v_cvt_pk_bf16_f32 v25, v30, v31
	v_add_co_u32_e32 v30, vcc, s71, v136
	v_cvt_pk_bf16_f32 v24, v28, v29
	v_cvt_pk_bf16_f32 v26, v32, v33
	v_cvt_pk_bf16_f32 v27, v34, v27
	v_addc_co_u32_e32 v31, vcc, 0, v137, vcc
	v_add_f32_e32 v16, 1.0, v16
	global_store_dwordx4 v[30:31], v[24:27], off nt
	v_pk_fma_f32 v[18:19], v[18:19], v[156:157], v[50:51] op_sel_hi:[1,0,1]
	v_pk_fma_f32 v[22:23], v[22:23], v[156:157], v[54:55] op_sel_hi:[1,0,1]
	v_rcp_f32_e32 v24, v16
	v_mul_f32_e32 v16, 0xbfb8aa3b, v17
	v_exp_f32_e32 v16, v16
	v_pk_fma_f32 v[20:21], v[20:21], v[156:157], v[52:53] op_sel_hi:[1,0,1]
	v_mul_f32_e32 v22, 0xbfb8aa3b, v22
	v_mul_f32_e32 v20, 0xbfb8aa3b, v20
	v_add_f32_e32 v16, 1.0, v16
	v_rcp_f32_e32 v25, v16
	v_mul_f32_e32 v16, 0xbfb8aa3b, v18
	v_exp_f32_e32 v16, v16
	v_mul_f32_e32 v21, 0xbfb8aa3b, v21
	v_mul_f32_e32 v23, 0xbfb8aa3b, v23
	v_exp_f32_e32 v20, v20
	v_add_f32_e32 v16, 1.0, v16
	v_rcp_f32_e32 v26, v16
	v_mul_f32_e32 v16, 0xbfb8aa3b, v19
	v_exp_f32_e32 v21, v21
	v_exp_f32_e32 v22, v22
	v_exp_f32_e32 v23, v23
	v_exp_f32_e32 v16, v16
	v_pk_fma_f32 v[8:9], v[8:9], v[154:155], v[64:65] op_sel_hi:[1,0,1]
	v_add_f32_e32 v20, 1.0, v20
	v_add_f32_e32 v21, 1.0, v21
	v_add_f32_e32 v22, 1.0, v22
	v_add_f32_e32 v23, 1.0, v23
	v_add_f32_e32 v16, 1.0, v16
	v_mul_f32_e32 v8, 0xbfb8aa3b, v8
	v_rcp_f32_e32 v20, v20
	v_rcp_f32_e32 v21, v21
	v_rcp_f32_e32 v22, v22
	v_rcp_f32_e32 v23, v23
	v_rcp_f32_e32 v19, v16
	v_exp_f32_e32 v8, v8
	s_mov_b64 s[20:21], 0x280000
	v_lshl_add_u64 v[28:29], v[136:137], 0, s[20:21]
	v_cvt_pk_bf16_f32 v16, v20, v21
	v_cvt_pk_bf16_f32 v17, v22, v23
	v_cvt_pk_bf16_f32 v18, v24, v25
	v_cvt_pk_bf16_f32 v19, v26, v19
	v_add_f32_e32 v8, 1.0, v8
	global_store_dwordx4 v[28:29], v[16:19], off offset:256 nt
	v_pk_fma_f32 v[10:11], v[10:11], v[154:155], v[66:67] op_sel_hi:[1,0,1]
	v_pk_fma_f32 v[14:15], v[14:15], v[154:155], v[70:71] op_sel_hi:[1,0,1]
	v_rcp_f32_e32 v16, v8
	v_mul_f32_e32 v8, 0xbfb8aa3b, v9
	v_exp_f32_e32 v8, v8
	v_pk_fma_f32 v[12:13], v[12:13], v[154:155], v[68:69] op_sel_hi:[1,0,1]
	v_mul_f32_e32 v14, 0xbfb8aa3b, v14
	v_mul_f32_e32 v15, 0xbfb8aa3b, v15
	v_add_f32_e32 v8, 1.0, v8
	v_rcp_f32_e32 v17, v8
	v_mul_f32_e32 v8, 0xbfb8aa3b, v10
	v_exp_f32_e32 v8, v8
	v_mul_f32_e32 v12, 0xbfb8aa3b, v12
	v_mul_f32_e32 v13, 0xbfb8aa3b, v13
	v_exp_f32_e32 v14, v14
	v_add_f32_e32 v8, 1.0, v8
	v_exp_f32_e32 v15, v15
	v_rcp_f32_e32 v18, v8
	v_mul_f32_e32 v8, 0xbfb8aa3b, v11
	v_exp_f32_e32 v12, v12
	v_exp_f32_e32 v13, v13
	v_exp_f32_e32 v8, v8
	v_add_f32_e32 v14, 1.0, v14
	v_add_f32_e32 v15, 1.0, v15
	v_pk_fma_f32 v[0:1], v[0:1], v[154:155], v[48:49] op_sel_hi:[1,0,1]
	v_add_f32_e32 v12, 1.0, v12
	v_add_f32_e32 v13, 1.0, v13
	v_rcp_f32_e32 v14, v14
	v_rcp_f32_e32 v15, v15
	v_add_f32_e32 v8, 1.0, v8
	v_mul_f32_e32 v0, 0xbfb8aa3b, v0
	v_rcp_f32_e32 v12, v12
	v_rcp_f32_e32 v13, v13
	v_rcp_f32_e32 v11, v8
	v_exp_f32_e32 v0, v0
	v_cvt_pk_bf16_f32 v9, v14, v15
	v_add_co_u32_e32 v14, vcc, s72, v136
	v_cvt_pk_bf16_f32 v8, v12, v13
	v_cvt_pk_bf16_f32 v10, v16, v17
	v_cvt_pk_bf16_f32 v11, v18, v11
	v_addc_co_u32_e32 v15, vcc, 0, v137, vcc
	v_add_f32_e32 v0, 1.0, v0
	global_store_dwordx4 v[14:15], v[8:11], off nt
	v_pk_fma_f32 v[2:3], v[2:3], v[154:155], v[50:51] op_sel_hi:[1,0,1]
	v_pk_fma_f32 v[6:7], v[6:7], v[154:155], v[54:55] op_sel_hi:[1,0,1]
	v_rcp_f32_e32 v8, v0
	v_mul_f32_e32 v0, 0xbfb8aa3b, v1
	v_exp_f32_e32 v0, v0
	v_pk_fma_f32 v[4:5], v[4:5], v[154:155], v[52:53] op_sel_hi:[1,0,1]
	v_mul_f32_e32 v6, 0xbfb8aa3b, v6
	v_mul_f32_e32 v4, 0xbfb8aa3b, v4
	v_add_f32_e32 v0, 1.0, v0
	v_rcp_f32_e32 v9, v0
	v_mul_f32_e32 v0, 0xbfb8aa3b, v2
	v_exp_f32_e32 v0, v0
	v_mul_f32_e32 v5, 0xbfb8aa3b, v5
	v_mul_f32_e32 v7, 0xbfb8aa3b, v7
	v_exp_f32_e32 v4, v4
	v_add_f32_e32 v0, 1.0, v0
	v_rcp_f32_e32 v10, v0
	v_mul_f32_e32 v0, 0xbfb8aa3b, v3
	v_exp_f32_e32 v5, v5
	v_exp_f32_e32 v6, v6
	v_exp_f32_e32 v7, v7
	v_exp_f32_e32 v0, v0
	v_add_f32_e32 v4, 1.0, v4
	v_add_f32_e32 v5, 1.0, v5
	v_add_f32_e32 v6, 1.0, v6
	v_add_f32_e32 v7, 1.0, v7
	v_add_f32_e32 v0, 1.0, v0
	v_rcp_f32_e32 v4, v4
	v_rcp_f32_e32 v5, v5
	v_rcp_f32_e32 v6, v6
	v_rcp_f32_e32 v7, v7
	v_rcp_f32_e32 v3, v0
	s_mov_b64 s[20:21], 0x2c0000
	v_lshl_add_u64 v[12:13], v[136:137], 0, s[20:21]
	v_cvt_pk_bf16_f32 v0, v4, v5
	v_cvt_pk_bf16_f32 v1, v6, v7
	v_cvt_pk_bf16_f32 v2, v8, v9
	v_cvt_pk_bf16_f32 v3, v10, v3
	s_mov_b64 s[20:21], -1
	s_andn2_b64 vcc, exec, s[12:13]
	global_store_dwordx4 v[12:13], v[0:3], off offset:256 nt
	s_cbranch_vccnz .LBB0_764
	s_andn2_b64 vcc, exec, s[0:1]
	s_cbranch_vccnz .LBB0_763
	s_mov_b32 s100, 1
	s_branch .LBB0_763

;     __device__ __forceinline__ void operator()(const f32x4 (&acc)[2][2][4][2], const Unit& un, int wr, int wc, int fr, int fq) const {
;     ...
;             u32x4 ga_[4][2];
; #pragma unroll
;             for (int m = 0; m < 4; ++m)
; #pragma unroll
;                 for (int bj = 0; bj < 2; ++bj) ga_[m][bj] = *(const u32x4*)(gate + (size_t)(rbase + ai * 128 + m * 16) * DFF + kb * D + cw + bj * 128);
; #pragma unroll
;             for (int m = 0; m < 4; ++m)
; #pragma unroll
;                 for (int bj = 0; bj < 2; ++bj) { const int row = rbase + ai * 128 + m * 16 - NLAT, col = cw + bj * 128; const f32x4 v0 = acc[ai][bj][m][0], v1 = acc[ai][bj][m][1]; const u32x4 gw = ga_[m][bj];
;                     float* dp = pb + (size_t)row * D + col;
;                     *(f32x4*)dp = (f32x4){bflo(gw.x) * v0.x, bfhi(gw.x) * v0.y, bflo(gw.y) * v0.z, bfhi(gw.y) * v0.w};
;                     *(f32x4*)(dp + 4) = (f32x4){bflo(gw.z) * v1.x, bfhi(gw.z) * v1.y, bflo(gw.w) * v1.z, bfhi(gw.w) * v1.w}; } }
.LBB0_1177:
	s_lshl_b32 s0, s16, 23
	s_add_u32 s0, s12, s0
	v_lshl_or_b32 v128, s17, 8, v139
	s_addc_u32 s1, s13, 0
	s_lshl_b32 s4, s16, 12
	v_or_b32_e32 v164, s23, v128
	s_add_u32 s4, s12, s4
	v_lshl_add_u32 v152, s18, 8, v138
	s_addc_u32 s5, s13, 0
	v_lshlrev_b32_e32 v208, 1, v164
	v_lshl_add_u64 v[128:129], s[4:5], 0, v[208:209]
	s_mov_b64 s[4:5], 0x30a00000
	v_ashrrev_i32_e32 v153, 31, v152
	v_lshl_add_u64 v[128:129], v[128:129], 0, s[4:5]
	v_lshlrev_b64 v[130:131], 14, v[152:153]
	v_lshl_add_u64 v[154:155], v[128:129], 0, v[130:131]
	global_load_dwordx4 v[156:159], v[154:155], off
	global_load_dwordx4 v[160:163], v[154:155], off offset:256
	v_or_b32_e32 v130, 16, v152
	v_ashrrev_i32_e32 v131, 31, v130
	v_lshlrev_b64 v[130:131], 14, v[130:131]
	v_lshl_add_u64 v[130:131], v[128:129], 0, v[130:131]
	global_load_dwordx4 v[148:151], v[130:131], off
	global_load_dwordx4 v[144:147], v[130:131], off offset:256
	v_or_b32_e32 v130, 32, v152
	v_ashrrev_i32_e32 v131, 31, v130
	v_lshlrev_b64 v[130:131], 14, v[130:131]
	v_lshl_add_u64 v[130:131], v[128:129], 0, v[130:131]
	global_load_dwordx4 v[140:143], v[130:131], off
	global_load_dwordx4 v[136:139], v[130:131], off offset:256
	v_or_b32_e32 v130, 48, v152
	v_ashrrev_i32_e32 v131, 31, v130
	v_lshlrev_b64 v[130:131], 14, v[130:131]
	v_lshl_add_u64 v[128:129], v[128:129], 0, v[130:131]
	global_load_dwordx4 v[132:135], v[128:129], off
	s_nop 0
	global_load_dwordx4 v[128:131], v[128:129], off offset:256
	v_lshlrev_b64 v[152:153], 13, v[152:153]
	v_lshlrev_b32_e32 v208, 2, v164
	v_lshl_add_u64 v[152:153], s[0:1], 0, v[152:153]
	v_lshl_add_u64 v[152:153], v[152:153], 0, v[208:209]
	s_mov_b64 s[0:1], 0x46800000
	v_lshl_add_u64 v[164:165], v[152:153], 0, s[0:1]
	s_mov_b32 s0, 0x46800000
	s_waitcnt vmcnt(0)
	v_lshlrev_b32_e32 v166, 16, v156
	v_and_b32_e32 v167, 0xffff0000, v156
	v_lshlrev_b32_e32 v156, 16, v157
	v_and_b32_e32 v157, 0xffff0000, v157
	v_pk_mul_f32 v[126:127], v[126:127], v[156:157]
	v_add_co_u32_e32 v156, vcc, s0, v152
	v_pk_mul_f32 v[124:125], v[124:125], v[166:167]
	s_nop 0
	v_addc_co_u32_e32 v157, vcc, 0, v153, vcc
	global_store_dwordx4 v[156:157], v[124:127], off nt
	s_mov_b64 s[0:1], 0x46820000
	s_nop 0
	v_lshlrev_b32_e32 v124, 16, v158
	v_and_b32_e32 v125, 0xffff0000, v158
	v_pk_mul_f32 v[120:121], v[120:121], v[124:125]
	v_lshlrev_b32_e32 v124, 16, v159
	v_and_b32_e32 v125, 0xffff0000, v159
	v_pk_mul_f32 v[122:123], v[122:123], v[124:125]
	global_store_dwordx4 v[164:165], v[120:123], off offset:16 nt
	s_nop 1
	v_lshlrev_b32_e32 v120, 16, v160
	v_and_b32_e32 v121, 0xffff0000, v160
	v_pk_mul_f32 v[116:117], v[116:117], v[120:121]
	v_lshlrev_b32_e32 v120, 16, v161
	v_and_b32_e32 v121, 0xffff0000, v161
	v_pk_mul_f32 v[118:119], v[118:119], v[120:121]
	global_store_dwordx4 v[164:165], v[116:119], off offset:512 nt
	s_nop 1
	v_lshlrev_b32_e32 v116, 16, v162
	v_and_b32_e32 v117, 0xffff0000, v162
	v_pk_mul_f32 v[112:113], v[112:113], v[116:117]
	v_lshlrev_b32_e32 v116, 16, v163
	v_and_b32_e32 v117, 0xffff0000, v163
	v_pk_mul_f32 v[114:115], v[114:115], v[116:117]
	global_store_dwordx4 v[164:165], v[112:115], off offset:528 nt
	s_nop 1
	v_lshlrev_b32_e32 v114, 16, v148
	v_and_b32_e32 v115, 0xffff0000, v148
	v_lshl_add_u64 v[112:113], v[152:153], 0, s[0:1]
	v_pk_mul_f32 v[108:109], v[108:109], v[114:115]
	v_lshlrev_b32_e32 v114, 16, v149
	v_and_b32_e32 v115, 0xffff0000, v149
	s_mov_b32 s0, 0x46820000
	v_pk_mul_f32 v[110:111], v[110:111], v[114:115]
	v_add_co_u32_e32 v114, vcc, s0, v152
	s_mov_b64 s[0:1], 0x46840000
	s_nop 0
	v_addc_co_u32_e32 v115, vcc, 0, v153, vcc
	global_store_dwordx4 v[114:115], v[108:111], off nt
	s_nop 1
	v_lshlrev_b32_e32 v108, 16, v150
	v_and_b32_e32 v109, 0xffff0000, v150
	v_pk_mul_f32 v[104:105], v[104:105], v[108:109]
	v_lshlrev_b32_e32 v108, 16, v151
	v_and_b32_e32 v109, 0xffff0000, v151
	v_pk_mul_f32 v[106:107], v[106:107], v[108:109]
	global_store_dwordx4 v[112:113], v[104:107], off offset:16 nt
	s_nop 1
	v_lshlrev_b32_e32 v104, 16, v144
	v_and_b32_e32 v105, 0xffff0000, v144
	v_pk_mul_f32 v[100:101], v[100:101], v[104:105]
	v_lshlrev_b32_e32 v104, 16, v145
	v_and_b32_e32 v105, 0xffff0000, v145
	v_pk_mul_f32 v[102:103], v[102:103], v[104:105]
	global_store_dwordx4 v[112:113], v[100:103], off offset:512 nt
	s_nop 1
	v_lshlrev_b32_e32 v100, 16, v146
	v_and_b32_e32 v101, 0xffff0000, v146
	v_pk_mul_f32 v[92:93], v[92:93], v[100:101]
	v_lshlrev_b32_e32 v100, 16, v147
	v_and_b32_e32 v101, 0xffff0000, v147
	v_pk_mul_f32 v[94:95], v[94:95], v[100:101]
	global_store_dwordx4 v[112:113], v[92:95], off offset:528 nt
	v_lshl_add_u64 v[100:101], v[152:153], 0, s[0:1]
	s_mov_b32 s0, 0x46840000
	v_lshlrev_b32_e32 v92, 16, v140
	v_and_b32_e32 v93, 0xffff0000, v140
	v_pk_mul_f32 v[92:93], v[96:97], v[92:93]
	v_lshlrev_b32_e32 v94, 16, v141
	v_and_b32_e32 v95, 0xffff0000, v141
	v_add_co_u32_e32 v96, vcc, s0, v152
	v_pk_mul_f32 v[94:95], v[98:99], v[94:95]
	s_nop 0
	v_addc_co_u32_e32 v97, vcc, 0, v153, vcc
	global_store_dwordx4 v[96:97], v[92:95], off nt
	s_mov_b64 s[0:1], 0x46860000
	s_nop 0
	v_lshlrev_b32_e32 v92, 16, v142
	v_and_b32_e32 v93, 0xffff0000, v142
	v_pk_mul_f32 v[88:89], v[88:89], v[92:93]
	v_lshlrev_b32_e32 v92, 16, v143
	v_and_b32_e32 v93, 0xffff0000, v143
	v_pk_mul_f32 v[90:91], v[90:91], v[92:93]
	global_store_dwordx4 v[100:101], v[88:91], off offset:16 nt
	s_nop 1
	v_lshlrev_b32_e32 v88, 16, v136
	v_and_b32_e32 v89, 0xffff0000, v136
	v_pk_mul_f32 v[84:85], v[84:85], v[88:89]
	v_lshlrev_b32_e32 v88, 16, v137
	v_and_b32_e32 v89, 0xffff0000, v137
	v_pk_mul_f32 v[86:87], v[86:87], v[88:89]
	global_store_dwordx4 v[100:101], v[84:87], off offset:512 nt
	s_nop 1
;     __device__ __forceinline__ void operator()(const f32x4 (&acc)[2][2][4][2], const Unit& un, int wr, int wc, int fr, int fq) const {
;     ...
;             u32x4 ga_[4][2];
; #pragma unroll
;             for (int m = 0; m < 4; ++m)
; #pragma unroll
;                 for (int bj = 0; bj < 2; ++bj) ga_[m][bj] = *(const u32x4*)(gate + (size_t)(rbase + ai * 128 + m * 16) * DFF + kb * D + cw + bj * 128);
; #pragma unroll
;             for (int m = 0; m < 4; ++m)
; #pragma unroll
;                 for (int bj = 0; bj < 2; ++bj) { const int row = rbase + ai * 128 + m * 16 - NLAT, col = cw + bj * 128; const f32x4 v0 = acc[ai][bj][m][0], v1 = acc[ai][bj][m][1]; const u32x4 gw = ga_[m][bj];
;                     float* dp = pb + (size_t)row * D + col;
;                     *(f32x4*)dp = (f32x4){bflo(gw.x) * v0.x, bfhi(gw.x) * v0.y, bflo(gw.y) * v0.z, bfhi(gw.y) * v0.w};
;                     *(f32x4*)(dp + 4) = (f32x4){bflo(gw.z) * v1.x, bfhi(gw.z) * v1.y, bflo(gw.w) * v1.z, bfhi(gw.w) * v1.w}; } }
	v_lshlrev_b32_e32 v84, 16, v138
	v_and_b32_e32 v85, 0xffff0000, v138
	v_pk_mul_f32 v[76:77], v[76:77], v[84:85]
	v_lshlrev_b32_e32 v84, 16, v139
	v_and_b32_e32 v85, 0xffff0000, v139
	v_pk_mul_f32 v[78:79], v[78:79], v[84:85]
	global_store_dwordx4 v[100:101], v[76:79], off offset:528 nt
	v_lshl_add_u64 v[84:85], v[152:153], 0, s[0:1]
	s_mov_b32 s0, 0x46860000
	v_lshlrev_b32_e32 v76, 16, v132
	v_and_b32_e32 v77, 0xffff0000, v132
	v_pk_mul_f32 v[76:77], v[80:81], v[76:77]
	v_lshlrev_b32_e32 v78, 16, v133
	v_and_b32_e32 v79, 0xffff0000, v133
	v_add_co_u32_e32 v80, vcc, s0, v152
	v_pk_mul_f32 v[78:79], v[82:83], v[78:79]
	s_nop 0
	v_addc_co_u32_e32 v81, vcc, 0, v153, vcc
	global_store_dwordx4 v[80:81], v[76:79], off nt
	s_mov_b64 s[0:1], 0x240000
	s_nop 0
	v_lshlrev_b32_e32 v76, 16, v134
	v_and_b32_e32 v77, 0xffff0000, v134
	v_pk_mul_f32 v[72:73], v[72:73], v[76:77]
	v_lshlrev_b32_e32 v76, 16, v135
	v_and_b32_e32 v77, 0xffff0000, v135
	v_pk_mul_f32 v[74:75], v[74:75], v[76:77]
	global_store_dwordx4 v[84:85], v[72:75], off offset:16 nt
	s_nop 1
	v_lshlrev_b32_e32 v72, 16, v128
	v_and_b32_e32 v73, 0xffff0000, v128
	v_pk_mul_f32 v[68:69], v[68:69], v[72:73]
	v_lshlrev_b32_e32 v72, 16, v129
	v_and_b32_e32 v73, 0xffff0000, v129
	v_pk_mul_f32 v[70:71], v[70:71], v[72:73]
	global_store_dwordx4 v[84:85], v[68:71], off offset:512 nt
	s_nop 1
	v_lshlrev_b32_e32 v68, 16, v130
	v_and_b32_e32 v69, 0xffff0000, v130
	v_pk_mul_f32 v[64:65], v[64:65], v[68:69]
	v_lshlrev_b32_e32 v68, 16, v131
	v_and_b32_e32 v69, 0xffff0000, v131
	v_pk_mul_f32 v[66:67], v[66:67], v[68:69]
	global_store_dwordx4 v[84:85], v[64:67], off offset:528 nt
	s_nop 1
	v_add_co_u32_e32 v66, vcc, s78, v154
	v_lshl_add_u64 v[64:65], v[154:155], 0, s[56:57]
	s_nop 0
	v_addc_co_u32_e32 v67, vcc, 0, v155, vcc
	global_load_dwordx4 v[72:75], v[66:67], off
	global_load_dwordx4 v[76:79], v[64:65], off offset:256
	v_add_co_u32_e32 v66, vcc, s74, v154
	v_lshl_add_u64 v[64:65], v[154:155], 0, s[0:1]
	s_nop 0
	v_addc_co_u32_e32 v67, vcc, 0, v155, vcc
	global_load_dwordx4 v[80:83], v[66:67], off
	global_load_dwordx4 v[84:87], v[64:65], off offset:256
	v_add_co_u32_e32 v66, vcc, s71, v154
	s_mov_b64 s[0:1], 0x280000
	s_nop 0
	v_addc_co_u32_e32 v67, vcc, 0, v155, vcc
	v_lshl_add_u64 v[64:65], v[154:155], 0, s[0:1]
	global_load_dwordx4 v[88:91], v[66:67], off
	global_load_dwordx4 v[92:95], v[64:65], off offset:256
	s_mov_b64 s[0:1], 0x2c0000
	v_add_co_u32_e32 v66, vcc, s72, v154
	v_lshl_add_u64 v[64:65], v[154:155], 0, s[0:1]
	s_nop 0
	v_addc_co_u32_e32 v67, vcc, 0, v155, vcc
	global_load_dwordx4 v[68:71], v[66:67], off
	s_nop 0
	global_load_dwordx4 v[64:67], v[64:65], off offset:256
	s_mov_b64 s[0:1], 0x46900000
	v_lshl_add_u64 v[96:97], v[152:153], 0, s[0:1]
	s_mov_b32 s0, 0x46900000
	s_waitcnt vmcnt(7)
	v_lshlrev_b32_e32 v98, 16, v72
	v_and_b32_e32 v99, 0xffff0000, v72
	v_lshlrev_b32_e32 v72, 16, v73
	v_and_b32_e32 v73, 0xffff0000, v73
	v_pk_mul_f32 v[62:63], v[62:63], v[72:73]
	v_add_co_u32_e32 v72, vcc, s0, v152
	v_pk_mul_f32 v[60:61], v[60:61], v[98:99]
	s_nop 0
	v_addc_co_u32_e32 v73, vcc, 0, v153, vcc
	global_store_dwordx4 v[72:73], v[60:63], off nt
	s_mov_b64 s[0:1], 0x46920000
	s_nop 0
	v_lshlrev_b32_e32 v60, 16, v74
	v_and_b32_e32 v61, 0xffff0000, v74
	v_pk_mul_f32 v[56:57], v[56:57], v[60:61]
	v_lshlrev_b32_e32 v60, 16, v75
	v_and_b32_e32 v61, 0xffff0000, v75
	v_pk_mul_f32 v[58:59], v[58:59], v[60:61]
	global_store_dwordx4 v[96:97], v[56:59], off offset:16 nt
	s_waitcnt vmcnt(8)
	s_nop 0
	v_lshlrev_b32_e32 v56, 16, v76
	v_and_b32_e32 v57, 0xffff0000, v76
	v_pk_mul_f32 v[52:53], v[52:53], v[56:57]
	v_lshlrev_b32_e32 v56, 16, v77
	v_and_b32_e32 v57, 0xffff0000, v77
	v_pk_mul_f32 v[54:55], v[54:55], v[56:57]
	global_store_dwordx4 v[96:97], v[52:55], off offset:512 nt
	s_nop 1
	v_lshlrev_b32_e32 v52, 16, v78
	v_and_b32_e32 v53, 0xffff0000, v78
	v_pk_mul_f32 v[44:45], v[44:45], v[52:53]
	v_lshlrev_b32_e32 v52, 16, v79
	v_and_b32_e32 v53, 0xffff0000, v79
	v_pk_mul_f32 v[46:47], v[46:47], v[52:53]
	global_store_dwordx4 v[96:97], v[44:47], off offset:528 nt
	v_lshl_add_u64 v[52:53], v[152:153], 0, s[0:1]
	s_mov_b32 s0, 0x46920000
	s_waitcnt vmcnt(9)
; #define PG8_WAIT_V(n) asm volatile("s_waitcnt vmcnt(" #n ")" ::: "memory")
; #define PG8_BAR __builtin_amdgcn_s_barrier()
; template <class Epi, class Sched, bool ALIGN_EPI = false, bool SP2 = false>
; __device__ __forceinline__ void gemm_phase(PG8_LAS unsigned char* lds, const Gemm g, const Sched& S, const Epi& E, const int tid) {
;     ...
;     PG8_WAIT_V(0);
;     if constexpr (!ALIGN_EPI) { if (wr == 0) PG8_BAR; }
;     PG8_BAR;
;     __device__ __forceinline__ void operator()(const f32x4 (&acc)[2][2][4][2], const Unit& un, int wr, int wc, int fr, int fq) const {
;     ...
;             u32x4 ga_[4][2];
; #pragma unroll
;             for (int m = 0; m < 4; ++m)
; #pragma unroll
;                 for (int bj = 0; bj < 2; ++bj) ga_[m][bj] = *(const u32x4*)(gate + (size_t)(rbase + ai * 128 + m * 16) * DFF + kb * D + cw + bj * 128);
; #pragma unroll
;             for (int m = 0; m < 4; ++m)
; #pragma unroll
;                 for (int bj = 0; bj < 2; ++bj) { const int row = rbase + ai * 128 + m * 16 - NLAT, col = cw + bj * 128; const f32x4 v0 = acc[ai][bj][m][0], v1 = acc[ai][bj][m][1]; const u32x4 gw = ga_[m][bj];
;                     float* dp = pb + (size_t)row * D + col;
;                     *(f32x4*)dp = (f32x4){bflo(gw.x) * v0.x, bfhi(gw.x) * v0.y, bflo(gw.y) * v0.z, bfhi(gw.y) * v0.w};
;                     *(f32x4*)(dp + 4) = (f32x4){bflo(gw.z) * v1.x, bfhi(gw.z) * v1.y, bflo(gw.w) * v1.z, bfhi(gw.w) * v1.w}; } }
	v_lshlrev_b32_e32 v44, 16, v80
	v_and_b32_e32 v45, 0xffff0000, v80
	v_pk_mul_f32 v[44:45], v[48:49], v[44:45]
	v_lshlrev_b32_e32 v46, 16, v81
	v_and_b32_e32 v47, 0xffff0000, v81
	v_add_co_u32_e32 v48, vcc, s0, v152
	v_pk_mul_f32 v[46:47], v[50:51], v[46:47]
	s_nop 0
	v_addc_co_u32_e32 v49, vcc, 0, v153, vcc
	global_store_dwordx4 v[48:49], v[44:47], off nt
	s_mov_b64 s[0:1], 0x46940000
	s_nop 0
	v_lshlrev_b32_e32 v44, 16, v82
	v_and_b32_e32 v45, 0xffff0000, v82
	v_pk_mul_f32 v[40:41], v[40:41], v[44:45]
	v_lshlrev_b32_e32 v44, 16, v83
	v_and_b32_e32 v45, 0xffff0000, v83
	v_pk_mul_f32 v[42:43], v[42:43], v[44:45]
	global_store_dwordx4 v[52:53], v[40:43], off offset:16 nt
	s_waitcnt vmcnt(10)
	s_nop 0
	v_lshlrev_b32_e32 v40, 16, v84
	v_and_b32_e32 v41, 0xffff0000, v84
	v_pk_mul_f32 v[36:37], v[36:37], v[40:41]
	v_lshlrev_b32_e32 v40, 16, v85
	v_and_b32_e32 v41, 0xffff0000, v85
	v_pk_mul_f32 v[38:39], v[38:39], v[40:41]
	global_store_dwordx4 v[52:53], v[36:39], off offset:512 nt
	s_nop 1
	v_lshlrev_b32_e32 v36, 16, v86
	v_and_b32_e32 v37, 0xffff0000, v86
	v_pk_mul_f32 v[28:29], v[28:29], v[36:37]
	v_lshlrev_b32_e32 v36, 16, v87
	v_and_b32_e32 v37, 0xffff0000, v87
	v_pk_mul_f32 v[30:31], v[30:31], v[36:37]
	global_store_dwordx4 v[52:53], v[28:31], off offset:528 nt
	v_lshl_add_u64 v[36:37], v[152:153], 0, s[0:1]
	s_mov_b32 s0, 0x46940000
	s_waitcnt vmcnt(11)
	v_lshlrev_b32_e32 v28, 16, v88
	v_and_b32_e32 v29, 0xffff0000, v88
	v_pk_mul_f32 v[28:29], v[32:33], v[28:29]
	v_lshlrev_b32_e32 v30, 16, v89
	v_and_b32_e32 v31, 0xffff0000, v89
	v_add_co_u32_e32 v32, vcc, s0, v152
	v_pk_mul_f32 v[30:31], v[34:35], v[30:31]
	s_nop 0
	v_addc_co_u32_e32 v33, vcc, 0, v153, vcc
	global_store_dwordx4 v[32:33], v[28:31], off nt
	s_mov_b64 s[0:1], 0x46960000
	s_nop 0
	v_lshlrev_b32_e32 v28, 16, v90
	v_and_b32_e32 v29, 0xffff0000, v90
	v_pk_mul_f32 v[24:25], v[24:25], v[28:29]
	v_lshlrev_b32_e32 v28, 16, v91
	v_and_b32_e32 v29, 0xffff0000, v91
	v_pk_mul_f32 v[26:27], v[26:27], v[28:29]
	global_store_dwordx4 v[36:37], v[24:27], off offset:16 nt
	s_waitcnt vmcnt(12)
	s_nop 0
	v_lshlrev_b32_e32 v24, 16, v92
	v_and_b32_e32 v25, 0xffff0000, v92
	v_pk_mul_f32 v[20:21], v[20:21], v[24:25]
	v_lshlrev_b32_e32 v24, 16, v93
	v_and_b32_e32 v25, 0xffff0000, v93
	v_pk_mul_f32 v[22:23], v[22:23], v[24:25]
	global_store_dwordx4 v[36:37], v[20:23], off offset:512 nt
	s_nop 1
	v_lshlrev_b32_e32 v20, 16, v94
	v_and_b32_e32 v21, 0xffff0000, v94
	v_pk_mul_f32 v[12:13], v[12:13], v[20:21]
	v_lshlrev_b32_e32 v20, 16, v95
	v_and_b32_e32 v21, 0xffff0000, v95
	v_pk_mul_f32 v[14:15], v[14:15], v[20:21]
	global_store_dwordx4 v[36:37], v[12:15], off offset:528 nt
	v_lshl_add_u64 v[20:21], v[152:153], 0, s[0:1]
	s_mov_b32 s0, 0x46960000
	s_waitcnt vmcnt(13)
	v_lshlrev_b32_e32 v12, 16, v68
	v_and_b32_e32 v13, 0xffff0000, v68
	v_pk_mul_f32 v[12:13], v[16:17], v[12:13]
	v_lshlrev_b32_e32 v14, 16, v69
	v_and_b32_e32 v15, 0xffff0000, v69
	v_add_co_u32_e32 v16, vcc, s0, v152
	v_pk_mul_f32 v[14:15], v[18:19], v[14:15]
	s_nop 0
	v_addc_co_u32_e32 v17, vcc, 0, v153, vcc
	global_store_dwordx4 v[16:17], v[12:15], off nt
	s_nop 1
	v_lshlrev_b32_e32 v12, 16, v70
	v_and_b32_e32 v13, 0xffff0000, v70
	v_pk_mul_f32 v[8:9], v[8:9], v[12:13]
	v_lshlrev_b32_e32 v12, 16, v71
	v_and_b32_e32 v13, 0xffff0000, v71
	v_pk_mul_f32 v[10:11], v[10:11], v[12:13]
	global_store_dwordx4 v[20:21], v[8:11], off offset:16 nt
	s_waitcnt vmcnt(14)
	s_nop 0
	v_lshlrev_b32_e32 v8, 16, v64
	v_and_b32_e32 v9, 0xffff0000, v64
	v_pk_mul_f32 v[4:5], v[4:5], v[8:9]
	v_lshlrev_b32_e32 v8, 16, v65
	v_and_b32_e32 v9, 0xffff0000, v65
	v_pk_mul_f32 v[6:7], v[6:7], v[8:9]
	global_store_dwordx4 v[20:21], v[4:7], off offset:512 nt
	s_nop 1
	v_lshlrev_b32_e32 v4, 16, v66
	v_and_b32_e32 v5, 0xffff0000, v66
	v_pk_mul_f32 v[0:1], v[0:1], v[4:5]
	v_lshlrev_b32_e32 v4, 16, v67
	v_and_b32_e32 v5, 0xffff0000, v67
	v_pk_mul_f32 v[2:3], v[2:3], v[4:5]
	global_store_dwordx4 v[20:21], v[0:3], off offset:528 nt
	s_waitcnt vmcnt(0)
	s_barrier

.LBB0_1350:
	s_lshl_b32 s10, s0, 8
	s_lshl_b32 s0, s26, 23
	s_add_u32 s0, s22, s0
	s_addc_u32 s1, s23, 0
	s_add_u32 s0, s0, 0x56800000
	s_addc_u32 s1, s1, 0
	s_add_i32 s10, s10, s31
	v_lshl_or_b32 v128, s27, 8, v139
	v_add_u32_e32 v131, s10, v138
	v_or_b32_e32 v130, s34, v128
	v_add_u32_e32 v128, 0xffff8000, v131
	v_ashrrev_i32_e32 v129, 31, v128
	v_lshlrev_b64 v[128:129], 13, v[128:129]
	v_lshl_add_u64 v[128:129], s[0:1], 0, v[128:129]
	v_lshlrev_b32_e32 v208, 2, v130
	v_lshl_add_u64 v[128:129], v[128:129], 0, v[208:209]
	global_store_dwordx4 v[128:129], v[124:127], off nt
	global_store_dwordx4 v[128:129], v[120:123], off offset:16 nt
	global_store_dwordx4 v[128:129], v[108:111], off offset:512 nt
	global_store_dwordx4 v[128:129], v[100:103], off offset:528 nt
	s_movk_i32 s30, 0x41
	s_mov_b32 s63, s41
	v_add_u32_e32 v100, 0xffff8010, v131
	v_ashrrev_i32_e32 v101, 31, v100
	v_lshlrev_b64 v[100:101], 13, v[100:101]
	v_lshl_add_u64 v[100:101], s[0:1], 0, v[100:101]
	v_lshl_add_u64 v[100:101], v[100:101], 0, v[208:209]
	global_store_dwordx4 v[100:101], v[116:119], off nt
	global_store_dwordx4 v[100:101], v[112:115], off offset:16 nt
	global_store_dwordx4 v[100:101], v[92:95], off offset:512 nt
	global_store_dwordx4 v[100:101], v[84:87], off offset:528 nt
	s_nop 1
	v_add_u32_e32 v84, 0xffff8020, v131
	v_ashrrev_i32_e32 v85, 31, v84
	v_lshlrev_b64 v[84:85], 13, v[84:85]
	v_lshl_add_u64 v[84:85], s[0:1], 0, v[84:85]
	v_lshl_add_u64 v[84:85], v[84:85], 0, v[208:209]
	global_store_dwordx4 v[84:85], v[104:107], off nt
	global_store_dwordx4 v[84:85], v[96:99], off offset:16 nt
	global_store_dwordx4 v[84:85], v[76:79], off offset:512 nt
	global_store_dwordx4 v[84:85], v[72:75], off offset:528 nt
	s_nop 1
	v_add_u32_e32 v72, 0xffff8030, v131
	v_ashrrev_i32_e32 v73, 31, v72
	v_lshlrev_b64 v[72:73], 13, v[72:73]
	v_lshl_add_u64 v[72:73], s[0:1], 0, v[72:73]
	v_lshl_add_u64 v[72:73], v[72:73], 0, v[208:209]
	s_mov_b64 s[0:1], 0x100000
	global_store_dwordx4 v[72:73], v[88:91], off nt
	global_store_dwordx4 v[72:73], v[80:83], off offset:16 nt
	global_store_dwordx4 v[72:73], v[68:71], off offset:512 nt
	global_store_dwordx4 v[72:73], v[64:67], off offset:528 nt
	s_nop 1
	v_lshl_add_u64 v[64:65], v[128:129], 0, s[0:1]
	s_mov_b32 s0, 0x100000
	v_add_co_u32_e32 v66, vcc, s0, v128
	s_mov_b64 s[0:1], 0x120000
	s_nop 0
	v_addc_co_u32_e32 v67, vcc, 0, v129, vcc
	global_store_dwordx4 v[66:67], v[60:63], off nt
	global_store_dwordx4 v[64:65], v[56:59], off offset:16 nt
	global_store_dwordx4 v[64:65], v[44:47], off offset:512 nt
	global_store_dwordx4 v[64:65], v[40:43], off offset:528 nt
	s_nop 1
	v_lshl_add_u64 v[40:41], v[128:129], 0, s[0:1]
	s_mov_b32 s0, 0x120000
	v_add_co_u32_e32 v42, vcc, s0, v128
	s_mov_b64 s[0:1], 0x140000
	s_nop 0
	v_addc_co_u32_e32 v43, vcc, 0, v129, vcc
	global_store_dwordx4 v[42:43], v[52:55], off nt
	global_store_dwordx4 v[40:41], v[48:51], off offset:16 nt
	global_store_dwordx4 v[40:41], v[28:31], off offset:512 nt
	global_store_dwordx4 v[40:41], v[24:27], off offset:528 nt
	s_nop 1
	v_lshl_add_u64 v[24:25], v[128:129], 0, s[0:1]
	s_mov_b32 s0, 0x140000
	v_add_co_u32_e32 v26, vcc, s0, v128
	s_mov_b64 s[0:1], 0x160000
	s_nop 0
	v_addc_co_u32_e32 v27, vcc, 0, v129, vcc
	global_store_dwordx4 v[26:27], v[36:39], off nt
	global_store_dwordx4 v[24:25], v[32:35], off offset:16 nt
	global_store_dwordx4 v[24:25], v[12:15], off offset:512 nt
	global_store_dwordx4 v[24:25], v[8:11], off offset:528 nt
	s_nop 1
	v_add_co_u32_e32 v10, vcc, 0x160000, v128
	v_lshl_add_u64 v[8:9], v[128:129], 0, s[0:1]
	s_nop 0
	v_addc_co_u32_e32 v11, vcc, 0, v129, vcc
	global_store_dwordx4 v[10:11], v[20:23], off nt
	global_store_dwordx4 v[8:9], v[16:19], off offset:16 nt
	global_store_dwordx4 v[8:9], v[4:7], off offset:512 nt
	global_store_dwordx4 v[8:9], v[0:3], off offset:528 nt
	s_waitcnt vmcnt(0)
	s_barrier

; __device__ __forceinline__ unsigned pk2(float lo, float hi) { const f32x2 v = {lo, hi}; return __builtin_bit_cast(unsigned, __builtin_convertvector(v, bf16x2_t)); }
; #define EPI_LOOP _Pragma("unroll") for (int ai = 0; ai < 2; ++ai) _Pragma("unroll") for (int m = 0; m < 4; ++m) _Pragma("unroll") for (int bj = 0; bj < 2; ++bj)
;     __device__ __forceinline__ void operator()(const f32x4 (&acc)[2][2][4][2], const Unit& un, int wr, int wc, int fr, int fq) const {
;     ...
;         EPI_LOOP { const int row = rbase + ai * 128 + m * 16, col = cw + bj * 128; const float r = rr[ai][m];
;             f32x4 v0 = acc[ai][bj][m][0] * r + s0[bj], v1 = acc[ai][bj][m][1] * r + s1[bj];
;             v0 = __builtin_elementwise_max(v0, (f32x4){0.f, 0.f, 0.f, 0.f}); v1 = __builtin_elementwise_max(v1, (f32x4){0.f, 0.f, 0.f, 0.f}); v0 = v0 * v0; v1 = v1 * v1;
;             u32x4 w; w.x = pk2(v0.x, v0.y); w.y = pk2(v0.z, v0.w); w.z = pk2(v1.x, v1.y); w.w = pk2(v1.z, v1.w);
;             *(u32x4*)(o + (size_t)row * DFF + col) = w; }
.LBB0_1482:
	v_lshlrev_b64 v[176:177], 14, v[176:177]
	s_mov_b64 s[24:25], 0x200000
	v_readlane_b32 s58, v254, 51
	s_waitcnt vmcnt(0)
	v_pk_fma_f32 v[142:143], v[142:143], v[180:181], v[126:127] op_sel_hi:[1,0,1]
	v_pk_fma_f32 v[140:141], v[140:141], v[180:181], v[124:125] op_sel_hi:[1,0,1]
	v_pk_fma_f32 v[138:139], v[138:139], v[180:181], v[122:123] op_sel_hi:[1,0,1]
	v_pk_fma_f32 v[136:137], v[136:137], v[180:181], v[120:121] op_sel_hi:[1,0,1]
	v_max_f32_e32 v143, 0, v143
	v_max_f32_e32 v142, 0, v142
	v_max_f32_e32 v141, 0, v141
	v_max_f32_e32 v140, 0, v140
	v_max_f32_e32 v139, 0, v139
	v_max_f32_e32 v138, 0, v138
	v_max_f32_e32 v137, 0, v137
	v_max_f32_e32 v136, 0, v136
	v_pk_mul_f32 v[142:143], v[142:143], v[142:143]
	v_pk_mul_f32 v[140:141], v[140:141], v[140:141]
	v_pk_mul_f32 v[138:139], v[138:139], v[138:139]
	v_pk_mul_f32 v[136:137], v[136:137], v[136:137]
	v_cvt_pk_bf16_f32 v140, v140, v141
	v_cvt_pk_bf16_f32 v141, v142, v143
	v_cvt_pk_bf16_f32 v142, v136, v137
	v_cvt_pk_bf16_f32 v143, v138, v139
	v_lshl_add_u64 v[136:137], s[10:11], 0, v[176:177]
	v_lshlrev_b64 v[138:139], 1, v[174:175]
	v_pk_fma_f32 v[134:135], v[134:135], v[180:181], v[118:119] op_sel_hi:[1,0,1]
	v_pk_fma_f32 v[132:133], v[132:133], v[180:181], v[116:117] op_sel_hi:[1,0,1]
	v_pk_fma_f32 v[130:131], v[130:131], v[180:181], v[114:115] op_sel_hi:[1,0,1]
	v_pk_fma_f32 v[128:129], v[128:129], v[180:181], v[112:113] op_sel_hi:[1,0,1]
	v_lshl_add_u64 v[136:137], v[136:137], 0, v[138:139]
	v_max_f32_e32 v135, 0, v135
	v_max_f32_e32 v134, 0, v134
	v_max_f32_e32 v133, 0, v133
	v_max_f32_e32 v132, 0, v132
	v_max_f32_e32 v131, 0, v131
	v_max_f32_e32 v130, 0, v130
	v_max_f32_e32 v129, 0, v129
	v_max_f32_e32 v128, 0, v128
	global_store_dwordx4 v[136:137], v[140:143], off nt
	v_pk_mul_f32 v[134:135], v[134:135], v[134:135]
	v_pk_mul_f32 v[132:133], v[132:133], v[132:133]
	v_pk_mul_f32 v[140:141], v[130:131], v[130:131]
	v_pk_mul_f32 v[130:131], v[128:129], v[128:129]
	v_pk_fma_f32 v[108:109], v[108:109], v[170:171], v[124:125] op_sel_hi:[1,0,1]
	v_cvt_pk_bf16_f32 v128, v132, v133
	v_cvt_pk_bf16_f32 v129, v134, v135
	v_cvt_pk_bf16_f32 v130, v130, v131
	v_cvt_pk_bf16_f32 v131, v140, v141
	v_pk_fma_f32 v[110:111], v[110:111], v[170:171], v[126:127] op_sel_hi:[1,0,1]
	v_pk_fma_f32 v[106:107], v[106:107], v[170:171], v[122:123] op_sel_hi:[1,0,1]
	v_pk_fma_f32 v[104:105], v[104:105], v[170:171], v[120:121] op_sel_hi:[1,0,1]
	v_max_f32_e32 v109, 0, v109
	v_max_f32_e32 v108, 0, v108
	global_store_dwordx4 v[136:137], v[128:131], off offset:256 nt
	v_max_f32_e32 v111, 0, v111
	v_max_f32_e32 v110, 0, v110
	v_lshlrev_b64 v[128:129], 14, v[172:173]
	v_max_f32_e32 v107, 0, v107
	v_max_f32_e32 v106, 0, v106
	v_max_f32_e32 v105, 0, v105
	v_max_f32_e32 v104, 0, v104
	v_pk_mul_f32 v[108:109], v[108:109], v[108:109]
	v_pk_mul_f32 v[110:111], v[110:111], v[110:111]
	v_pk_mul_f32 v[130:131], v[106:107], v[106:107]
	v_pk_mul_f32 v[106:107], v[104:105], v[104:105]
	v_cvt_pk_bf16_f32 v104, v108, v109
	v_lshl_add_u64 v[108:109], s[10:11], 0, v[128:129]
	v_pk_fma_f32 v[102:103], v[102:103], v[170:171], v[118:119] op_sel_hi:[1,0,1]
	v_pk_fma_f32 v[100:101], v[100:101], v[170:171], v[116:117] op_sel_hi:[1,0,1]
	v_pk_fma_f32 v[98:99], v[98:99], v[170:171], v[114:115] op_sel_hi:[1,0,1]
	v_pk_fma_f32 v[96:97], v[96:97], v[170:171], v[112:113] op_sel_hi:[1,0,1]
	v_cvt_pk_bf16_f32 v105, v110, v111
	v_cvt_pk_bf16_f32 v106, v106, v107
	v_cvt_pk_bf16_f32 v107, v130, v131
	v_lshl_add_u64 v[108:109], v[108:109], 0, v[138:139]
	v_max_f32_e32 v103, 0, v103
	v_max_f32_e32 v102, 0, v102
	v_max_f32_e32 v101, 0, v101
	v_max_f32_e32 v100, 0, v100
	v_max_f32_e32 v99, 0, v99
	v_max_f32_e32 v98, 0, v98
	v_max_f32_e32 v97, 0, v97
	v_max_f32_e32 v96, 0, v96
	global_store_dwordx4 v[108:109], v[104:107], off nt
	v_pk_mul_f32 v[102:103], v[102:103], v[102:103]
	v_pk_mul_f32 v[100:101], v[100:101], v[100:101]
	v_pk_mul_f32 v[104:105], v[98:99], v[98:99]
	v_pk_mul_f32 v[98:99], v[96:97], v[96:97]
	v_pk_fma_f32 v[92:93], v[92:93], v[166:167], v[124:125] op_sel_hi:[1,0,1]
	v_cvt_pk_bf16_f32 v96, v100, v101
	v_cvt_pk_bf16_f32 v97, v102, v103
	v_cvt_pk_bf16_f32 v98, v98, v99
	v_cvt_pk_bf16_f32 v99, v104, v105
	v_pk_fma_f32 v[94:95], v[94:95], v[166:167], v[126:127] op_sel_hi:[1,0,1]
	v_pk_fma_f32 v[90:91], v[90:91], v[166:167], v[122:123] op_sel_hi:[1,0,1]
	v_pk_fma_f32 v[88:89], v[88:89], v[166:167], v[120:121] op_sel_hi:[1,0,1]
	v_max_f32_e32 v93, 0, v93
	v_max_f32_e32 v92, 0, v92
	global_store_dwordx4 v[108:109], v[96:99], off offset:256 nt
	v_max_f32_e32 v95, 0, v95
	v_max_f32_e32 v94, 0, v94
	v_lshlrev_b64 v[96:97], 14, v[168:169]
	v_max_f32_e32 v91, 0, v91
	v_max_f32_e32 v90, 0, v90
	v_max_f32_e32 v89, 0, v89
	v_max_f32_e32 v88, 0, v88
	v_pk_mul_f32 v[92:93], v[92:93], v[92:93]
	v_pk_mul_f32 v[94:95], v[94:95], v[94:95]
	v_pk_mul_f32 v[98:99], v[90:91], v[90:91]
	v_pk_mul_f32 v[90:91], v[88:89], v[88:89]
	v_cvt_pk_bf16_f32 v88, v92, v93
	v_lshl_add_u64 v[92:93], s[10:11], 0, v[96:97]
	v_pk_fma_f32 v[86:87], v[86:87], v[166:167], v[118:119] op_sel_hi:[1,0,1]
	v_pk_fma_f32 v[84:85], v[84:85], v[166:167], v[116:117] op_sel_hi:[1,0,1]
	v_pk_fma_f32 v[82:83], v[82:83], v[166:167], v[114:115] op_sel_hi:[1,0,1]
	v_pk_fma_f32 v[80:81], v[80:81], v[166:167], v[112:113] op_sel_hi:[1,0,1]
	v_cvt_pk_bf16_f32 v89, v94, v95
	v_cvt_pk_bf16_f32 v90, v90, v91
	v_cvt_pk_bf16_f32 v91, v98, v99
	v_lshl_add_u64 v[92:93], v[92:93], 0, v[138:139]
	v_max_f32_e32 v87, 0, v87
	v_max_f32_e32 v86, 0, v86
	v_max_f32_e32 v85, 0, v85
	v_max_f32_e32 v84, 0, v84
	v_max_f32_e32 v83, 0, v83
	v_max_f32_e32 v82, 0, v82
	v_max_f32_e32 v81, 0, v81
; __device__ __forceinline__ unsigned pk2(float lo, float hi) { const f32x2 v = {lo, hi}; return __builtin_bit_cast(unsigned, __builtin_convertvector(v, bf16x2_t)); }
; #define EPI_LOOP _Pragma("unroll") for (int ai = 0; ai < 2; ++ai) _Pragma("unroll") for (int m = 0; m < 4; ++m) _Pragma("unroll") for (int bj = 0; bj < 2; ++bj)
;     __device__ __forceinline__ void operator()(const f32x4 (&acc)[2][2][4][2], const Unit& un, int wr, int wc, int fr, int fq) const {
;     ...
;         EPI_LOOP { const int row = rbase + ai * 128 + m * 16, col = cw + bj * 128; const float r = rr[ai][m];
;             f32x4 v0 = acc[ai][bj][m][0] * r + s0[bj], v1 = acc[ai][bj][m][1] * r + s1[bj];
;             v0 = __builtin_elementwise_max(v0, (f32x4){0.f, 0.f, 0.f, 0.f}); v1 = __builtin_elementwise_max(v1, (f32x4){0.f, 0.f, 0.f, 0.f}); v0 = v0 * v0; v1 = v1 * v1;
;             u32x4 w; w.x = pk2(v0.x, v0.y); w.y = pk2(v0.z, v0.w); w.z = pk2(v1.x, v1.y); w.w = pk2(v1.z, v1.w);
;             *(u32x4*)(o + (size_t)row * DFF + col) = w; }
	v_max_f32_e32 v80, 0, v80
	global_store_dwordx4 v[92:93], v[88:91], off nt
	v_pk_mul_f32 v[86:87], v[86:87], v[86:87]
	v_pk_mul_f32 v[84:85], v[84:85], v[84:85]
	v_pk_mul_f32 v[88:89], v[82:83], v[82:83]
	v_pk_mul_f32 v[82:83], v[80:81], v[80:81]
	v_pk_fma_f32 v[76:77], v[76:77], v[162:163], v[124:125] op_sel_hi:[1,0,1]
	v_cvt_pk_bf16_f32 v80, v84, v85
	v_cvt_pk_bf16_f32 v81, v86, v87
	v_cvt_pk_bf16_f32 v82, v82, v83
	v_cvt_pk_bf16_f32 v83, v88, v89
	v_pk_fma_f32 v[78:79], v[78:79], v[162:163], v[126:127] op_sel_hi:[1,0,1]
	v_pk_fma_f32 v[74:75], v[74:75], v[162:163], v[122:123] op_sel_hi:[1,0,1]
	v_pk_fma_f32 v[72:73], v[72:73], v[162:163], v[120:121] op_sel_hi:[1,0,1]
	v_max_f32_e32 v77, 0, v77
	v_max_f32_e32 v76, 0, v76
	global_store_dwordx4 v[92:93], v[80:83], off offset:256 nt
	v_max_f32_e32 v79, 0, v79
	v_max_f32_e32 v78, 0, v78
	v_lshlrev_b64 v[80:81], 14, v[164:165]
	v_max_f32_e32 v75, 0, v75
	v_max_f32_e32 v74, 0, v74
	v_max_f32_e32 v73, 0, v73
	v_max_f32_e32 v72, 0, v72
	v_pk_mul_f32 v[76:77], v[76:77], v[76:77]
	v_pk_mul_f32 v[78:79], v[78:79], v[78:79]
	v_pk_mul_f32 v[82:83], v[74:75], v[74:75]
	v_pk_mul_f32 v[74:75], v[72:73], v[72:73]
	v_cvt_pk_bf16_f32 v72, v76, v77
	v_lshl_add_u64 v[76:77], s[10:11], 0, v[80:81]
	v_pk_fma_f32 v[70:71], v[70:71], v[162:163], v[118:119] op_sel_hi:[1,0,1]
	v_pk_fma_f32 v[68:69], v[68:69], v[162:163], v[116:117] op_sel_hi:[1,0,1]
	v_pk_fma_f32 v[66:67], v[66:67], v[162:163], v[114:115] op_sel_hi:[1,0,1]
	v_pk_fma_f32 v[64:65], v[64:65], v[162:163], v[112:113] op_sel_hi:[1,0,1]
	v_cvt_pk_bf16_f32 v73, v78, v79
	v_cvt_pk_bf16_f32 v74, v74, v75
	v_cvt_pk_bf16_f32 v75, v82, v83
	v_lshl_add_u64 v[76:77], v[76:77], 0, v[138:139]
	v_max_f32_e32 v71, 0, v71
	v_max_f32_e32 v70, 0, v70
	v_max_f32_e32 v69, 0, v69
	v_max_f32_e32 v68, 0, v68
	v_max_f32_e32 v67, 0, v67
	v_max_f32_e32 v66, 0, v66
	v_max_f32_e32 v65, 0, v65
	v_max_f32_e32 v64, 0, v64
	v_pk_fma_f32 v[62:63], v[62:63], v[160:161], v[126:127] op_sel_hi:[1,0,1]
	global_store_dwordx4 v[76:77], v[72:75], off nt
	v_pk_mul_f32 v[70:71], v[70:71], v[70:71]
	v_pk_mul_f32 v[68:69], v[68:69], v[68:69]
	v_pk_mul_f32 v[72:73], v[66:67], v[66:67]
	v_pk_mul_f32 v[66:67], v[64:65], v[64:65]
	v_pk_fma_f32 v[60:61], v[60:61], v[160:161], v[124:125] op_sel_hi:[1,0,1]
	v_pk_fma_f32 v[58:59], v[58:59], v[160:161], v[122:123] op_sel_hi:[1,0,1]
	v_pk_fma_f32 v[56:57], v[56:57], v[160:161], v[120:121] op_sel_hi:[1,0,1]
	v_max_f32_e32 v63, 0, v63
	v_max_f32_e32 v62, 0, v62
	v_cvt_pk_bf16_f32 v64, v68, v69
	v_cvt_pk_bf16_f32 v65, v70, v71
	v_cvt_pk_bf16_f32 v66, v66, v67
	v_cvt_pk_bf16_f32 v67, v72, v73
	v_max_f32_e32 v61, 0, v61
	v_max_f32_e32 v60, 0, v60
	v_max_f32_e32 v59, 0, v59
	v_max_f32_e32 v58, 0, v58
	v_max_f32_e32 v57, 0, v57
	v_max_f32_e32 v56, 0, v56
	v_pk_mul_f32 v[62:63], v[62:63], v[62:63]
	global_store_dwordx4 v[76:77], v[64:67], off offset:256 nt
	v_pk_mul_f32 v[60:61], v[60:61], v[60:61]
	v_pk_fma_f32 v[54:55], v[54:55], v[160:161], v[118:119] op_sel_hi:[1,0,1]
	v_pk_mul_f32 v[64:65], v[58:59], v[58:59]
	v_pk_mul_f32 v[58:59], v[56:57], v[56:57]
	v_cvt_pk_bf16_f32 v57, v62, v63
	v_add_co_u32_e32 v62, vcc, s78, v136
	v_pk_fma_f32 v[52:53], v[52:53], v[160:161], v[116:117] op_sel_hi:[1,0,1]
	v_pk_fma_f32 v[50:51], v[50:51], v[160:161], v[114:115] op_sel_hi:[1,0,1]
	v_pk_fma_f32 v[48:49], v[48:49], v[160:161], v[112:113] op_sel_hi:[1,0,1]
	v_cvt_pk_bf16_f32 v56, v60, v61
	v_cvt_pk_bf16_f32 v58, v58, v59
	v_cvt_pk_bf16_f32 v59, v64, v65
	v_addc_co_u32_e32 v63, vcc, 0, v137, vcc
	v_max_f32_e32 v55, 0, v55
	v_max_f32_e32 v54, 0, v54
	v_max_f32_e32 v53, 0, v53
	v_max_f32_e32 v52, 0, v52
	v_max_f32_e32 v51, 0, v51
	v_max_f32_e32 v50, 0, v50
	v_max_f32_e32 v49, 0, v49
	v_max_f32_e32 v48, 0, v48
	v_pk_fma_f32 v[46:47], v[46:47], v[158:159], v[126:127] op_sel_hi:[1,0,1]
	global_store_dwordx4 v[62:63], v[56:59], off nt
	v_pk_mul_f32 v[54:55], v[54:55], v[54:55]
	v_pk_mul_f32 v[52:53], v[52:53], v[52:53]
	v_pk_mul_f32 v[56:57], v[50:51], v[50:51]
	v_pk_mul_f32 v[50:51], v[48:49], v[48:49]
	v_pk_fma_f32 v[44:45], v[44:45], v[158:159], v[124:125] op_sel_hi:[1,0,1]
	v_pk_fma_f32 v[42:43], v[42:43], v[158:159], v[122:123] op_sel_hi:[1,0,1]
	v_pk_fma_f32 v[40:41], v[40:41], v[158:159], v[120:121] op_sel_hi:[1,0,1]
	v_max_f32_e32 v47, 0, v47
	v_max_f32_e32 v46, 0, v46
	v_lshl_add_u64 v[60:61], v[136:137], 0, s[24:25]
	v_cvt_pk_bf16_f32 v48, v52, v53
	v_cvt_pk_bf16_f32 v49, v54, v55
	v_cvt_pk_bf16_f32 v50, v50, v51
	v_cvt_pk_bf16_f32 v51, v56, v57
	v_max_f32_e32 v45, 0, v45
	v_max_f32_e32 v44, 0, v44
	v_max_f32_e32 v43, 0, v43
	v_max_f32_e32 v42, 0, v42
	v_max_f32_e32 v41, 0, v41
	v_max_f32_e32 v40, 0, v40
	v_pk_mul_f32 v[46:47], v[46:47], v[46:47]
	global_store_dwordx4 v[60:61], v[48:51], off offset:256 nt
	v_pk_mul_f32 v[44:45], v[44:45], v[44:45]
	v_pk_fma_f32 v[38:39], v[38:39], v[158:159], v[118:119] op_sel_hi:[1,0,1]
	v_pk_mul_f32 v[48:49], v[42:43], v[42:43]
	v_pk_mul_f32 v[42:43], v[40:41], v[40:41]
	v_cvt_pk_bf16_f32 v41, v46, v47
;     __host__ __device__ bool next(int i, Unit& u) const { const int L = base + i * Gp + cp; if (L >= end) return false; return T.next(L, u); }
;     __host__ __device__ bool next(int i, Unit& u) const { const int L = i * Gp + cp; if (cp < 0 || L >= n) return false; u.kb = L & 3; u.pn = (L >> 2) % nN; u.pm = pm0 + (L >> 2) / nN; return true; }
;     __host__ __device__ bool next(int i, Unit& u) const { const bool ok = T.next(i >> 2, u); u.kb = i & 3; return ok; }
; __device__ __forceinline__ unsigned pk2(float lo, float hi) { const f32x2 v = {lo, hi}; return __builtin_bit_cast(unsigned, __builtin_convertvector(v, bf16x2_t)); }
; #define EPI_LOOP _Pragma("unroll") for (int ai = 0; ai < 2; ++ai) _Pragma("unroll") for (int m = 0; m < 4; ++m) _Pragma("unroll") for (int bj = 0; bj < 2; ++bj)
; template <class Epi, class Sched, bool ALIGN_EPI = false, bool SP2 = false>
; __device__ __forceinline__ void gemm_phase(PG8_LAS unsigned char* lds, const Gemm g, const Sched& S, const Epi& E, const int tid) {
;     ...
;     for (;;) {
;         const bool has_next = S.next(ui + 1, nxt);
;         const char* nA = has_next ? (const char*)g.A + (size_t)nxt.pm * tstep + (size_t)nxt.kb * g.sA : cA; const char* nB = has_next ? (const char*)g.Bt + (size_t)nxt.pn * tstep + (size_t)nxt.kb * g.sB : cB;
;         for (int t = 0; t < nt; t += 2) {
;     __device__ __forceinline__ void operator()(const f32x4 (&acc)[2][2][4][2], const Unit& un, int wr, int wc, int fr, int fq) const {
;     ...
;         EPI_LOOP { const int row = rbase + ai * 128 + m * 16, col = cw + bj * 128; const float r = rr[ai][m];
;             f32x4 v0 = acc[ai][bj][m][0] * r + s0[bj], v1 = acc[ai][bj][m][1] * r + s1[bj];
;             v0 = __builtin_elementwise_max(v0, (f32x4){0.f, 0.f, 0.f, 0.f}); v1 = __builtin_elementwise_max(v1, (f32x4){0.f, 0.f, 0.f, 0.f}); v0 = v0 * v0; v1 = v1 * v1;
;             u32x4 w; w.x = pk2(v0.x, v0.y); w.y = pk2(v0.z, v0.w); w.z = pk2(v1.x, v1.y); w.w = pk2(v1.z, v1.w);
;             *(u32x4*)(o + (size_t)row * DFF + col) = w; }
	v_add_co_u32_e32 v46, vcc, s74, v136
	v_pk_fma_f32 v[36:37], v[36:37], v[158:159], v[116:117] op_sel_hi:[1,0,1]
	v_pk_fma_f32 v[34:35], v[34:35], v[158:159], v[114:115] op_sel_hi:[1,0,1]
	v_pk_fma_f32 v[32:33], v[32:33], v[158:159], v[112:113] op_sel_hi:[1,0,1]
	v_cvt_pk_bf16_f32 v40, v44, v45
	v_cvt_pk_bf16_f32 v42, v42, v43
	v_cvt_pk_bf16_f32 v43, v48, v49
	v_addc_co_u32_e32 v47, vcc, 0, v137, vcc
	v_max_f32_e32 v39, 0, v39
	v_max_f32_e32 v38, 0, v38
	v_max_f32_e32 v37, 0, v37
	v_max_f32_e32 v36, 0, v36
	v_max_f32_e32 v35, 0, v35
	v_max_f32_e32 v34, 0, v34
	v_max_f32_e32 v33, 0, v33
	v_max_f32_e32 v32, 0, v32
	v_pk_fma_f32 v[30:31], v[30:31], v[156:157], v[126:127] op_sel_hi:[1,0,1]
	s_mov_b64 s[24:25], 0x240000
	global_store_dwordx4 v[46:47], v[40:43], off nt
	v_pk_mul_f32 v[38:39], v[38:39], v[38:39]
	v_pk_mul_f32 v[36:37], v[36:37], v[36:37]
	v_pk_mul_f32 v[40:41], v[34:35], v[34:35]
	v_pk_mul_f32 v[34:35], v[32:33], v[32:33]
	v_pk_fma_f32 v[28:29], v[28:29], v[156:157], v[124:125] op_sel_hi:[1,0,1]
	v_pk_fma_f32 v[26:27], v[26:27], v[156:157], v[122:123] op_sel_hi:[1,0,1]
	v_pk_fma_f32 v[24:25], v[24:25], v[156:157], v[120:121] op_sel_hi:[1,0,1]
	v_max_f32_e32 v31, 0, v31
	v_max_f32_e32 v30, 0, v30
	v_lshl_add_u64 v[44:45], v[136:137], 0, s[24:25]
	v_cvt_pk_bf16_f32 v32, v36, v37
	v_cvt_pk_bf16_f32 v33, v38, v39
	v_cvt_pk_bf16_f32 v34, v34, v35
	v_cvt_pk_bf16_f32 v35, v40, v41
	v_max_f32_e32 v29, 0, v29
	v_max_f32_e32 v28, 0, v28
	v_max_f32_e32 v27, 0, v27
	v_max_f32_e32 v26, 0, v26
	v_max_f32_e32 v25, 0, v25
	v_max_f32_e32 v24, 0, v24
	v_pk_mul_f32 v[30:31], v[30:31], v[30:31]
	global_store_dwordx4 v[44:45], v[32:35], off offset:256 nt
	v_pk_mul_f32 v[28:29], v[28:29], v[28:29]
	v_pk_fma_f32 v[22:23], v[22:23], v[156:157], v[118:119] op_sel_hi:[1,0,1]
	v_pk_mul_f32 v[32:33], v[26:27], v[26:27]
	v_pk_mul_f32 v[26:27], v[24:25], v[24:25]
	v_cvt_pk_bf16_f32 v25, v30, v31
	v_add_co_u32_e32 v30, vcc, s71, v136
	v_pk_fma_f32 v[20:21], v[20:21], v[156:157], v[116:117] op_sel_hi:[1,0,1]
	v_pk_fma_f32 v[18:19], v[18:19], v[156:157], v[114:115] op_sel_hi:[1,0,1]
	v_pk_fma_f32 v[16:17], v[16:17], v[156:157], v[112:113] op_sel_hi:[1,0,1]
	v_cvt_pk_bf16_f32 v24, v28, v29
	v_cvt_pk_bf16_f32 v26, v26, v27
	v_cvt_pk_bf16_f32 v27, v32, v33
	v_addc_co_u32_e32 v31, vcc, 0, v137, vcc
	v_max_f32_e32 v23, 0, v23
	v_max_f32_e32 v22, 0, v22
	v_max_f32_e32 v21, 0, v21
	v_max_f32_e32 v20, 0, v20
	v_max_f32_e32 v19, 0, v19
	v_max_f32_e32 v18, 0, v18
	v_max_f32_e32 v17, 0, v17
	v_max_f32_e32 v16, 0, v16
	v_pk_fma_f32 v[14:15], v[14:15], v[154:155], v[126:127] op_sel_hi:[1,0,1]
	s_mov_b64 s[24:25], 0x280000
	global_store_dwordx4 v[30:31], v[24:27], off nt
	v_pk_mul_f32 v[22:23], v[22:23], v[22:23]
	v_pk_mul_f32 v[20:21], v[20:21], v[20:21]
	v_pk_mul_f32 v[24:25], v[18:19], v[18:19]
	v_pk_mul_f32 v[18:19], v[16:17], v[16:17]
	v_pk_fma_f32 v[12:13], v[12:13], v[154:155], v[124:125] op_sel_hi:[1,0,1]
	v_pk_fma_f32 v[10:11], v[10:11], v[154:155], v[122:123] op_sel_hi:[1,0,1]
	v_pk_fma_f32 v[8:9], v[8:9], v[154:155], v[120:121] op_sel_hi:[1,0,1]
	v_max_f32_e32 v15, 0, v15
	v_max_f32_e32 v14, 0, v14
	v_lshl_add_u64 v[28:29], v[136:137], 0, s[24:25]
	v_cvt_pk_bf16_f32 v16, v20, v21
	v_cvt_pk_bf16_f32 v17, v22, v23
	v_cvt_pk_bf16_f32 v18, v18, v19
	v_cvt_pk_bf16_f32 v19, v24, v25
	v_max_f32_e32 v13, 0, v13
	v_max_f32_e32 v12, 0, v12
	v_max_f32_e32 v11, 0, v11
	v_max_f32_e32 v10, 0, v10
	v_max_f32_e32 v9, 0, v9
	v_max_f32_e32 v8, 0, v8
	v_pk_mul_f32 v[14:15], v[14:15], v[14:15]
	global_store_dwordx4 v[28:29], v[16:19], off offset:256 nt
	v_pk_mul_f32 v[12:13], v[12:13], v[12:13]
	v_pk_fma_f32 v[6:7], v[6:7], v[154:155], v[118:119] op_sel_hi:[1,0,1]
	v_pk_mul_f32 v[16:17], v[10:11], v[10:11]
	v_pk_mul_f32 v[10:11], v[8:9], v[8:9]
	v_cvt_pk_bf16_f32 v9, v14, v15
	v_add_co_u32_e32 v14, vcc, s72, v136
	v_pk_fma_f32 v[4:5], v[4:5], v[154:155], v[116:117] op_sel_hi:[1,0,1]
	v_pk_fma_f32 v[2:3], v[2:3], v[154:155], v[114:115] op_sel_hi:[1,0,1]
	v_pk_fma_f32 v[0:1], v[0:1], v[154:155], v[112:113] op_sel_hi:[1,0,1]
	v_cvt_pk_bf16_f32 v8, v12, v13
	v_cvt_pk_bf16_f32 v10, v10, v11
	v_cvt_pk_bf16_f32 v11, v16, v17
	v_addc_co_u32_e32 v15, vcc, 0, v137, vcc
	v_max_f32_e32 v7, 0, v7
	v_max_f32_e32 v6, 0, v6
	v_max_f32_e32 v5, 0, v5
	v_max_f32_e32 v4, 0, v4
	v_max_f32_e32 v3, 0, v3
	v_max_f32_e32 v2, 0, v2
	v_max_f32_e32 v1, 0, v1
	v_max_f32_e32 v0, 0, v0
	s_mov_b64 s[24:25], 0x2c0000
	global_store_dwordx4 v[14:15], v[8:11], off nt
	v_pk_mul_f32 v[6:7], v[6:7], v[6:7]
	v_pk_mul_f32 v[4:5], v[4:5], v[4:5]
	v_pk_mul_f32 v[8:9], v[2:3], v[2:3]
	v_pk_mul_f32 v[2:3], v[0:1], v[0:1]
	v_lshl_add_u64 v[12:13], v[136:137], 0, s[24:25]
	v_cvt_pk_bf16_f32 v0, v4, v5
	v_cvt_pk_bf16_f32 v1, v6, v7
	v_cvt_pk_bf16_f32 v2, v2, v3
	v_cvt_pk_bf16_f32 v3, v8, v9
	s_mov_b64 s[24:25], -1
	s_andn2_b64 vcc, exec, s[0:1]
	global_store_dwordx4 v[12:13], v[0:3], off offset:256 nt
	s_cbranch_vccnz .LBB0_1475
	s_andn2_b64 vcc, exec, s[6:7]
	s_cbranch_vccnz .LBB0_1474
	s_mov_b32 s100, 1
	s_branch .LBB0_1474

;     __device__ __forceinline__ void operator()(const f32x4 (&acc)[2][2][4][2], const Unit& un, int wr, int wc, int fr, int fq) const {
;     ...
;         for (int bj = 0; bj < 2; ++bj) { g0[bj] = *(const f32x4*)(gp + cw + bj * 128); g1[bj] = *(const f32x4*)(gp + cw + bj * 128 + 4); }
; #pragma unroll
;         for (int ai = 0; ai < 2; ++ai) {
;             f32x4 xa[4][2][2];
; #pragma unroll
;             for (int m = 0; m < 4; ++m)
; #pragma unroll
;                 for (int bj = 0; bj < 2; ++bj) { const float* sp = src + (size_t)(rbase + ai * 128 + m * 16 - radj) * D + cw + bj * 128; xa[m][bj][0] = *(const f32x4*)sp; xa[m][bj][1] = *(const f32x4*)(sp + 4); }
; #pragma unroll
;             for (int m = 0; m < 4; ++m)
; #pragma unroll
;                 for (int bj = 0; bj < 2; ++bj) { float* dp = dst + (size_t)(rbase + ai * 128 + m * 16 - radj) * D + cw + bj * 128;
;                     *(f32x4*)dp = xa[m][bj][0] + g0[bj] * acc[ai][bj][m][0]; *(f32x4*)(dp + 4) = xa[m][bj][1] + g1[bj] * acc[ai][bj][m][1]; } }
.LBB0_1610:
	s_lshl_b32 s23, s28, 8
	s_lshl_b64 s[36:37], s[36:37], 2
	s_add_u32 s36, s49, s36
	v_lshl_or_b32 v128, s55, 8, v162
	s_addc_u32 s37, s50, s37
	s_add_i32 s21, s21, s23
	v_ashrrev_i32_e32 v129, 31, v128
	v_add_u32_e32 v158, s21, v160
	v_lshlrev_b64 v[154:155], 2, v[128:129]
	v_ashrrev_i32_e32 v159, 31, v158
	v_or_b32_e32 v180, 16, v158
	v_or_b32_e32 v196, 32, v158
	v_or_b32_e32 v218, 48, v158
	v_lshl_add_u64 v[156:157], s[34:35], 0, v[154:155]
	v_lshlrev_b64 v[210:211], 13, v[158:159]
	v_ashrrev_i32_e32 v181, 31, v180
	v_ashrrev_i32_e32 v197, 31, v196
	v_ashrrev_i32_e32 v219, 31, v218
	v_lshl_add_u64 v[128:129], s[36:37], 0, v[154:155]
	v_lshl_add_u64 v[176:177], v[156:157], 0, v[210:211]
	v_lshlrev_b64 v[212:213], 13, v[180:181]
	v_lshlrev_b64 v[234:235], 13, v[196:197]
	v_lshlrev_b64 v[236:237], 13, v[218:219]
	global_load_dwordx4 v[164:167], v[176:177], off
	global_load_dwordx4 v[140:143], v[128:129], off
	global_load_dwordx4 v[136:139], v[128:129], off offset:16
	global_load_dwordx4 v[168:171], v[176:177], off offset:16
	global_load_dwordx4 v[172:175], v[176:177], off offset:512
	global_load_dwordx4 v[132:135], v[128:129], off offset:512
	s_nop 0
	global_load_dwordx4 v[128:131], v[128:129], off offset:528
	s_nop 0
	global_load_dwordx4 v[176:179], v[176:177], off offset:528
	v_lshl_add_u64 v[192:193], v[156:157], 0, v[212:213]
	v_lshl_add_u64 v[214:215], v[156:157], 0, v[234:235]
	v_lshl_add_u64 v[230:231], v[156:157], 0, v[236:237]
	global_load_dwordx4 v[180:183], v[192:193], off
	global_load_dwordx4 v[184:187], v[192:193], off offset:16
	global_load_dwordx4 v[188:191], v[192:193], off offset:528
	s_nop 0
	global_load_dwordx4 v[192:195], v[192:193], off offset:512
	s_nop 0
	global_load_dwordx4 v[196:199], v[214:215], off
	global_load_dwordx4 v[200:203], v[214:215], off offset:16
	global_load_dwordx4 v[204:207], v[214:215], off offset:528
	s_nop 0
	global_load_dwordx4 v[214:217], v[214:215], off offset:512
	s_nop 0
	global_load_dwordx4 v[218:221], v[230:231], off
	global_load_dwordx4 v[222:225], v[230:231], off offset:16
	global_load_dwordx4 v[226:229], v[230:231], off offset:512
	s_nop 0
	global_load_dwordx4 v[230:233], v[230:231], off offset:528
	v_lshl_add_u64 v[154:155], s[30:31], 0, v[154:155]
	v_lshl_add_u64 v[210:211], v[154:155], 0, v[210:211]
	v_lshl_add_u64 v[212:213], v[154:155], 0, v[212:213]
	v_lshl_add_u64 v[236:237], v[154:155], 0, v[236:237]
	v_lshl_add_u64 v[234:235], v[154:155], 0, v[234:235]
	s_andn2_b64 vcc, exec, s[0:1]
	s_mov_b64 s[0:1], -1
	s_waitcnt vmcnt(0)
	v_pk_fma_f32 v[126:127], v[126:127], v[142:143], v[166:167]
	v_pk_fma_f32 v[124:125], v[124:125], v[140:141], v[164:165]
	v_pk_fma_f32 v[122:123], v[122:123], v[138:139], v[170:171]
	v_pk_fma_f32 v[120:121], v[120:121], v[136:137], v[168:169]
	v_pk_fma_f32 v[106:107], v[106:107], v[134:135], v[174:175]
	v_pk_fma_f32 v[104:105], v[104:105], v[132:133], v[172:173]
	v_pk_fma_f32 v[98:99], v[98:99], v[130:131], v[178:179]
	v_pk_fma_f32 v[96:97], v[96:97], v[128:129], v[176:177]
	global_store_dwordx4 v[210:211], v[124:127], off nt
	global_store_dwordx4 v[210:211], v[120:123], off offset:16 nt
	global_store_dwordx4 v[210:211], v[104:107], off offset:512 nt
	global_store_dwordx4 v[210:211], v[96:99], off offset:528 nt
	v_pk_fma_f32 v[86:87], v[86:87], v[130:131], v[190:191]
	v_pk_fma_f32 v[106:107], v[114:115], v[138:139], v[186:187]
	v_pk_fma_f32 v[98:99], v[118:119], v[142:143], v[182:183]
	v_pk_fma_f32 v[96:97], v[116:117], v[140:141], v[180:181]
	v_pk_fma_f32 v[80:81], v[80:81], v[132:133], v[214:215]
	v_pk_fma_f32 v[66:67], v[66:67], v[130:131], v[232:233]
	v_pk_fma_f32 v[64:65], v[64:65], v[128:129], v[230:231]
	v_pk_fma_f32 v[104:105], v[112:113], v[136:137], v[184:185]
	v_pk_fma_f32 v[90:91], v[90:91], v[134:135], v[194:195]
	v_pk_fma_f32 v[88:89], v[88:89], v[132:133], v[192:193]
	v_pk_fma_f32 v[84:85], v[84:85], v[128:129], v[188:189]
	v_pk_fma_f32 v[110:111], v[110:111], v[142:143], v[198:199]
	v_pk_fma_f32 v[108:109], v[108:109], v[140:141], v[196:197]
	v_pk_fma_f32 v[102:103], v[102:103], v[138:139], v[202:203]
	v_pk_fma_f32 v[100:101], v[100:101], v[136:137], v[200:201]
	v_pk_fma_f32 v[82:83], v[82:83], v[134:135], v[216:217]
	v_pk_fma_f32 v[78:79], v[78:79], v[130:131], v[206:207]
	v_pk_fma_f32 v[76:77], v[76:77], v[128:129], v[204:205]
	v_pk_fma_f32 v[94:95], v[94:95], v[142:143], v[220:221]
	v_pk_fma_f32 v[92:93], v[92:93], v[140:141], v[218:219]
	global_store_dwordx4 v[212:213], v[96:99], off nt
	global_store_dwordx4 v[212:213], v[104:107], off offset:16 nt
	global_store_dwordx4 v[212:213], v[88:91], off offset:512 nt
	global_store_dwordx4 v[212:213], v[84:87], off offset:528 nt
	global_store_dwordx4 v[234:235], v[108:111], off nt
	global_store_dwordx4 v[234:235], v[100:103], off offset:16 nt
	global_store_dwordx4 v[234:235], v[80:83], off offset:512 nt
	global_store_dwordx4 v[234:235], v[76:79], off offset:528 nt
	global_store_dwordx4 v[236:237], v[92:95], off nt
	global_store_dwordx4 v[236:237], v[64:67], off offset:528 nt
	v_add_u32_e32 v80, 0x90, v158
;     __host__ __device__ bool next(int i, Unit& u) const { const int L = base + i * Gp + cp; if (L >= end) return false; return T.next(L, u); }
;     __host__ __device__ bool next(int i, Unit& u) const { const int L = i * Gp + cp; if (cp < 0 || L >= n) return false; u.kb = L & 3; u.pn = (L >> 2) % nN; u.pm = pm0 + (L >> 2) / nN; return true; }
;     __host__ __device__ bool next(int i, Unit& u) const { const bool ok = T.next(i >> 2, u); u.kb = i & 3; return ok; }
; template <class Epi, class Sched, bool ALIGN_EPI = false, bool SP2 = false>
; __device__ __forceinline__ void gemm_phase(PG8_LAS unsigned char* lds, const Gemm g, const Sched& S, const Epi& E, const int tid) {
;     ...
;     for (;;) {
;         const bool has_next = S.next(ui + 1, nxt);
;         const char* nA = has_next ? (const char*)g.A + (size_t)nxt.pm * tstep + (size_t)nxt.kb * g.sA : cA; const char* nB = has_next ? (const char*)g.Bt + (size_t)nxt.pn * tstep + (size_t)nxt.kb * g.sB : cB;
;         for (int t = 0; t < nt; t += 2) {
;     __device__ __forceinline__ void operator()(const f32x4 (&acc)[2][2][4][2], const Unit& un, int wr, int wc, int fr, int fq) const {
;     ...
;         for (int bj = 0; bj < 2; ++bj) { g0[bj] = *(const f32x4*)(gp + cw + bj * 128); g1[bj] = *(const f32x4*)(gp + cw + bj * 128 + 4); }
; #pragma unroll
;         for (int ai = 0; ai < 2; ++ai) {
;             f32x4 xa[4][2][2];
; #pragma unroll
;             for (int m = 0; m < 4; ++m)
; #pragma unroll
;                 for (int bj = 0; bj < 2; ++bj) { const float* sp = src + (size_t)(rbase + ai * 128 + m * 16 - radj) * D + cw + bj * 128; xa[m][bj][0] = *(const f32x4*)sp; xa[m][bj][1] = *(const f32x4*)(sp + 4); }
; #pragma unroll
;             for (int m = 0; m < 4; ++m)
; #pragma unroll
;                 for (int bj = 0; bj < 2; ++bj) { float* dp = dst + (size_t)(rbase + ai * 128 + m * 16 - radj) * D + cw + bj * 128;
;                     *(f32x4*)dp = xa[m][bj][0] + g0[bj] * acc[ai][bj][m][0]; *(f32x4*)(dp + 4) = xa[m][bj][1] + g1[bj] * acc[ai][bj][m][1]; } }
	v_add_u32_e32 v96, 0xa0, v158
	v_add_u32_e32 v64, 0x80, v158
	v_add_u32_e32 v112, 0xb0, v158
	v_ashrrev_i32_e32 v65, 31, v64
	v_ashrrev_i32_e32 v81, 31, v80
	v_ashrrev_i32_e32 v97, 31, v96
	v_ashrrev_i32_e32 v113, 31, v112
	v_pk_fma_f32 v[74:75], v[74:75], v[138:139], v[224:225]
	v_pk_fma_f32 v[72:73], v[72:73], v[136:137], v[222:223]
	v_pk_fma_f32 v[70:71], v[70:71], v[134:135], v[228:229]
	v_pk_fma_f32 v[68:69], v[68:69], v[132:133], v[226:227]
	v_lshlrev_b64 v[164:165], 13, v[64:65]
	v_lshlrev_b64 v[166:167], 13, v[80:81]
	v_lshlrev_b64 v[168:169], 13, v[96:97]
	v_lshlrev_b64 v[158:159], 13, v[112:113]
	global_store_dwordx4 v[236:237], v[72:75], off offset:16 nt
	global_store_dwordx4 v[236:237], v[68:71], off offset:512 nt
	v_lshl_add_u64 v[76:77], v[156:157], 0, v[164:165]
	v_lshl_add_u64 v[92:93], v[156:157], 0, v[166:167]
	v_lshl_add_u64 v[108:109], v[156:157], 0, v[168:169]
	v_lshl_add_u64 v[124:125], v[156:157], 0, v[158:159]
	global_load_dwordx4 v[64:67], v[76:77], off
	global_load_dwordx4 v[68:71], v[76:77], off offset:16
	global_load_dwordx4 v[72:75], v[76:77], off offset:528
	s_nop 0
	global_load_dwordx4 v[76:79], v[76:77], off offset:512
	s_nop 0
	global_load_dwordx4 v[80:83], v[92:93], off
	global_load_dwordx4 v[84:87], v[92:93], off offset:16
	global_load_dwordx4 v[88:91], v[92:93], off offset:528
	s_nop 0
	global_load_dwordx4 v[92:95], v[92:93], off offset:512
	s_nop 0
	global_load_dwordx4 v[96:99], v[108:109], off
	global_load_dwordx4 v[100:103], v[108:109], off offset:16
	global_load_dwordx4 v[104:107], v[108:109], off offset:528
	s_nop 0
	global_load_dwordx4 v[108:111], v[108:109], off offset:512
	s_nop 0
	global_load_dwordx4 v[112:115], v[124:125], off
	global_load_dwordx4 v[116:119], v[124:125], off offset:16
	global_load_dwordx4 v[120:123], v[124:125], off offset:512
	s_nop 0
	global_load_dwordx4 v[124:127], v[124:125], off offset:528
	v_lshl_add_u64 v[156:157], v[154:155], 0, v[164:165]
	v_lshl_add_u64 v[164:165], v[154:155], 0, v[166:167]
	v_lshl_add_u64 v[166:167], v[154:155], 0, v[168:169]
	v_lshl_add_u64 v[154:155], v[154:155], 0, v[158:159]
	s_waitcnt vmcnt(15)
	v_pk_fma_f32 v[62:63], v[62:63], v[142:143], v[66:67]
	v_pk_fma_f32 v[60:61], v[60:61], v[140:141], v[64:65]
	s_waitcnt vmcnt(14)
	v_pk_fma_f32 v[58:59], v[58:59], v[138:139], v[70:71]
	s_waitcnt vmcnt(3)
	v_pk_fma_f32 v[22:23], v[22:23], v[142:143], v[114:115]
	v_pk_fma_f32 v[20:21], v[20:21], v[140:141], v[112:113]
	s_waitcnt vmcnt(2)
	v_pk_fma_f32 v[10:11], v[10:11], v[138:139], v[118:119]
	v_pk_fma_f32 v[8:9], v[8:9], v[136:137], v[116:117]
	s_waitcnt vmcnt(1)
	v_pk_fma_f32 v[6:7], v[6:7], v[134:135], v[122:123]
	v_pk_fma_f32 v[4:5], v[4:5], v[132:133], v[120:121]
	s_waitcnt vmcnt(0)
	v_pk_fma_f32 v[2:3], v[2:3], v[130:131], v[126:127]
	v_pk_fma_f32 v[0:1], v[0:1], v[128:129], v[124:125]
	v_pk_fma_f32 v[56:57], v[56:57], v[136:137], v[68:69]
	v_pk_fma_f32 v[42:43], v[42:43], v[134:135], v[78:79]
	v_pk_fma_f32 v[40:41], v[40:41], v[132:133], v[76:77]
	v_pk_fma_f32 v[34:35], v[34:35], v[130:131], v[74:75]
	v_pk_fma_f32 v[32:33], v[32:33], v[128:129], v[72:73]
	v_pk_fma_f32 v[54:55], v[54:55], v[142:143], v[82:83]
	v_pk_fma_f32 v[52:53], v[52:53], v[140:141], v[80:81]
	v_pk_fma_f32 v[50:51], v[50:51], v[138:139], v[86:87]
	v_pk_fma_f32 v[48:49], v[48:49], v[136:137], v[84:85]
	v_pk_fma_f32 v[30:31], v[30:31], v[134:135], v[94:95]
	v_pk_fma_f32 v[28:29], v[28:29], v[132:133], v[92:93]
	v_pk_fma_f32 v[26:27], v[26:27], v[130:131], v[90:91]
	v_pk_fma_f32 v[24:25], v[24:25], v[128:129], v[88:89]
	v_pk_fma_f32 v[46:47], v[46:47], v[142:143], v[98:99]
	v_pk_fma_f32 v[44:45], v[44:45], v[140:141], v[96:97]
	v_pk_fma_f32 v[38:39], v[38:39], v[138:139], v[102:103]
	v_pk_fma_f32 v[36:37], v[36:37], v[136:137], v[100:101]
	v_pk_fma_f32 v[18:19], v[18:19], v[134:135], v[110:111]
	v_pk_fma_f32 v[16:17], v[16:17], v[132:133], v[108:109]
	v_pk_fma_f32 v[14:15], v[14:15], v[130:131], v[106:107]
	v_pk_fma_f32 v[12:13], v[12:13], v[128:129], v[104:105]
	global_store_dwordx4 v[156:157], v[60:63], off nt
	global_store_dwordx4 v[156:157], v[56:59], off offset:16 nt
	global_store_dwordx4 v[156:157], v[40:43], off offset:512 nt
	global_store_dwordx4 v[156:157], v[32:35], off offset:528 nt
	global_store_dwordx4 v[164:165], v[52:55], off nt
	global_store_dwordx4 v[164:165], v[48:51], off offset:16 nt
	global_store_dwordx4 v[164:165], v[28:31], off offset:512 nt
	global_store_dwordx4 v[164:165], v[24:27], off offset:528 nt
	global_store_dwordx4 v[166:167], v[44:47], off nt
	global_store_dwordx4 v[166:167], v[36:39], off offset:16 nt
	global_store_dwordx4 v[166:167], v[16:19], off offset:512 nt
	global_store_dwordx4 v[166:167], v[12:15], off offset:528 nt
	global_store_dwordx4 v[154:155], v[20:23], off nt
	global_store_dwordx4 v[154:155], v[8:11], off offset:16 nt
	global_store_dwordx4 v[154:155], v[4:7], off offset:512 nt
	global_store_dwordx4 v[154:155], v[0:3], off offset:528 nt
	s_cbranch_vccnz .LBB0_1596
	s_andn2_b64 vcc, exec, s[16:17]
	s_cbranch_vccnz .LBB0_1595
	s_mov_b32 s100, 1
	s_branch .LBB0_1595

.LBB0_1622:
	s_lshl_b32 s4, s0, 8
	s_lshl_b32 s0, s7, 23
	s_add_u32 s0, s20, s0
	s_addc_u32 s1, s21, 0
	s_add_u32 s0, s0, 0x56800000
	s_addc_u32 s1, s1, 0
	s_add_i32 s4, s4, s28
	v_lshl_or_b32 v128, s24, 8, v139
	v_add_u32_e32 v131, s4, v138
	v_or_b32_e32 v130, s29, v128
	v_add_u32_e32 v128, 0xffff8000, v131
	v_ashrrev_i32_e32 v129, 31, v128
	v_lshlrev_b64 v[128:129], 13, v[128:129]
	v_lshl_add_u64 v[128:129], s[0:1], 0, v[128:129]
	v_lshlrev_b32_e32 v208, 2, v130
	v_lshl_add_u64 v[128:129], v[128:129], 0, v[208:209]
	global_store_dwordx4 v[128:129], v[124:127], off nt
	global_store_dwordx4 v[128:129], v[120:123], off offset:16 nt
	global_store_dwordx4 v[128:129], v[108:111], off offset:512 nt
	global_store_dwordx4 v[128:129], v[100:103], off offset:528 nt
	s_mov_b32 s59, s37
	s_nop 0
	v_add_u32_e32 v100, 0xffff8010, v131
	v_ashrrev_i32_e32 v101, 31, v100
	v_lshlrev_b64 v[100:101], 13, v[100:101]
	v_lshl_add_u64 v[100:101], s[0:1], 0, v[100:101]
	v_lshl_add_u64 v[100:101], v[100:101], 0, v[208:209]
	global_store_dwordx4 v[100:101], v[116:119], off nt
	global_store_dwordx4 v[100:101], v[112:115], off offset:16 nt
	global_store_dwordx4 v[100:101], v[92:95], off offset:512 nt
	global_store_dwordx4 v[100:101], v[84:87], off offset:528 nt
	s_nop 1
	v_add_u32_e32 v84, 0xffff8020, v131
	v_ashrrev_i32_e32 v85, 31, v84
	v_lshlrev_b64 v[84:85], 13, v[84:85]
	v_lshl_add_u64 v[84:85], s[0:1], 0, v[84:85]
	v_lshl_add_u64 v[84:85], v[84:85], 0, v[208:209]
	global_store_dwordx4 v[84:85], v[104:107], off nt
	global_store_dwordx4 v[84:85], v[96:99], off offset:16 nt
	global_store_dwordx4 v[84:85], v[76:79], off offset:512 nt
	global_store_dwordx4 v[84:85], v[72:75], off offset:528 nt
	s_nop 1
	v_add_u32_e32 v72, 0xffff8030, v131
	v_ashrrev_i32_e32 v73, 31, v72
	v_lshlrev_b64 v[72:73], 13, v[72:73]
	v_lshl_add_u64 v[72:73], s[0:1], 0, v[72:73]
	v_lshl_add_u64 v[72:73], v[72:73], 0, v[208:209]
	s_mov_b64 s[0:1], 0x100000
	global_store_dwordx4 v[72:73], v[88:91], off nt
	global_store_dwordx4 v[72:73], v[80:83], off offset:16 nt
	global_store_dwordx4 v[72:73], v[68:71], off offset:512 nt
	global_store_dwordx4 v[72:73], v[64:67], off offset:528 nt
	s_nop 1
	v_lshl_add_u64 v[64:65], v[128:129], 0, s[0:1]
	s_mov_b32 s0, 0x100000
	v_add_co_u32_e32 v66, vcc, s0, v128
	s_mov_b64 s[0:1], 0x120000
	s_nop 0
	v_addc_co_u32_e32 v67, vcc, 0, v129, vcc
	global_store_dwordx4 v[66:67], v[60:63], off nt
	global_store_dwordx4 v[64:65], v[56:59], off offset:16 nt
	global_store_dwordx4 v[64:65], v[44:47], off offset:512 nt
	global_store_dwordx4 v[64:65], v[40:43], off offset:528 nt
	s_nop 1
	v_lshl_add_u64 v[40:41], v[128:129], 0, s[0:1]
	s_mov_b32 s0, 0x120000
	v_add_co_u32_e32 v42, vcc, s0, v128
	s_mov_b64 s[0:1], 0x140000
	s_nop 0
	v_addc_co_u32_e32 v43, vcc, 0, v129, vcc
	global_store_dwordx4 v[42:43], v[52:55], off nt
	global_store_dwordx4 v[40:41], v[48:51], off offset:16 nt
	global_store_dwordx4 v[40:41], v[28:31], off offset:512 nt
	global_store_dwordx4 v[40:41], v[24:27], off offset:528 nt
	s_nop 1
	v_lshl_add_u64 v[24:25], v[128:129], 0, s[0:1]
	s_mov_b32 s0, 0x140000
	v_add_co_u32_e32 v26, vcc, s0, v128
	s_mov_b64 s[0:1], 0x160000
	s_nop 0
	v_addc_co_u32_e32 v27, vcc, 0, v129, vcc
	global_store_dwordx4 v[26:27], v[36:39], off nt
	global_store_dwordx4 v[24:25], v[32:35], off offset:16 nt
	global_store_dwordx4 v[24:25], v[12:15], off offset:512 nt
	global_store_dwordx4 v[24:25], v[8:11], off offset:528 nt
	s_nop 1
	v_add_co_u32_e32 v10, vcc, 0x160000, v128
	v_lshl_add_u64 v[8:9], v[128:129], 0, s[0:1]
	s_nop 0
	v_addc_co_u32_e32 v11, vcc, 0, v129, vcc
	global_store_dwordx4 v[10:11], v[20:23], off nt
	global_store_dwordx4 v[8:9], v[16:19], off offset:16 nt
	global_store_dwordx4 v[8:9], v[4:7], off offset:512 nt
	global_store_dwordx4 v[8:9], v[0:3], off offset:528 nt
	s_waitcnt vmcnt(0)
	s_barrier
